# speedup vs baseline: 1.0075x; 1.0075x over previous
; __device__ __forceinline__ float bflo(unsigned w) { return __uint_as_float(w << 16); }
; __device__ __forceinline__ float bfhi(unsigned w) { return __uint_as_float(w & 0xffff0000u); }
; #define AISSUE(k0, soff) do { const char* kb_ = (const char*)Kn + (size_t)(k0) * 4096; const char* rb_ = (const char*)Kr + (size_t)(k0) * 1024; \
;     char* st_ = lds + (soff) + tid * 16; \
;     GLDS(kb_ + vkn0, st_ + KOFF); GLDS(kb_ + vkn1, st_ + KOFF + 8192); GLDS(rb_ + vkr, st_ + KOFF + KROPE_OFF); \
;     GLDS(kb_ + vv0, st_); GLDS(kb_ + vv1, st_ + 8192); } while (0)
; __device__ __forceinline__ void attn_body(const u16* __restrict__ Qb, const u16* __restrict__ Kn, const u16* __restrict__ Kr,
;                                           u16* __restrict__ Ob, char* lds, int tid, const float* __restrict__ gq_, const float* __restrict__ tab_, int qpos0, float negM) {
;   const int wid = tid >> 6, lane = tid & 63, r32 = lane & 31, hi = lane >> 5;
;   float* wsp = (float*)(lds + 3 * 40960) + wid * 64; float* li_l = wsp;
;   float l_reg = 0; f32x16 o[4] = {}; bf16x8 qr[12];
;   unsigned vkn0, vkn1, vkr, vv0, vv1;
;   { int sl = tid;        int row = sl >> 4, c = (sl & 15) ^ (row & 15);        vkn0 = (unsigned)(row * 4096 + c * 16);
;     sl = tid + 512;      row = sl >> 4;     c = (sl & 15) ^ (row & 15);        vkn1 = (unsigned)(row * 4096 + c * 16);
;     row = tid >> 3;      c = (tid & 7) ^ ((row >> 1) & 7);                     vkr  = (unsigned)(row * 1024 + c * 16);
; #pragma unroll
;     for (int i = 0; i < 2; ++i) { const int o = (tid + i * 512) * 16, sub = o >> 9, within = o & 511;
;       const int kk = (sub >> 2) * 8 + (within >> 6), cc = (sub & 3) * 32 + ((within & 63) >> 1);
;       const int k = (kk & ~0xC) | ((kk & 4) << 1) | ((kk & 8) >> 1);
;       const unsigned v = (unsigned)(k * 4096 + cc * 2 + 256);
;       if (i == 0) vv0 = v; else vv1 = v; } }
;   constexpr int STG = 40960, KOFF = 16384;
;     ...
;   AISSUE(0, 0);
;   {
;     const char* Qw = (const char*)Qb + (unsigned)(((wid * 32 + r32) * 1536 + hi * 8) * 2);
;     u32x4 qw[12];
; #pragma unroll
;     for (int d0 = 0; d0 < 12; ++d0) qw[d0] = *reinterpret_cast<const u32x4*>(Qw + d0 * 32);
;     float ss = 0.f;
; #pragma unroll
;     for (int d0 = 0; d0 < 12; ++d0)
; #pragma unroll
;       for (int e = 0; e < 4; ++e) { const float a = bflo(qw[d0][e]), b = bfhi(qw[d0][e]); ss += a * a + b * b; }
.LBB0_718:
	s_lshl_b32 s87, s3, 4
	s_lshl_b32 s0, s71, 10
	s_and_b32 s80, s0, 0x7e00000
	s_lshl_b32 s0, s71, 12
	v_mbcnt_lo_u32_b32 v96, -1, 0
	v_mbcnt_hi_u32_b32 v96, -1, v96
	s_and_b32 s79, s0, 0x1f800000
	v_or_b32_e32 v210, s3, v96
	s_lshl_b32 s0, s56, 8
	v_ashrrev_i32_e32 v20, 1, v210
	s_and_b32 s54, s0, 0x1f800
	s_mul_i32 s48, s56, 0xc0000
	v_bfi_b32 v66, s76, v20, v96
	s_mul_hi_u32 s49, s0, 0xc00
	s_add_u32 s50, s57, s48
	v_bfe_u32 v207, v96, 5, 1
	v_mul_lo_u32 v21, v66, s72
	s_addc_u32 s51, s58, s49
	v_lshl_or_b32 v67, v207, 4, v21
	s_barrier
	global_load_dwordx4 v[24:27], v67, s[50:51]
	v_lshlrev_b32_e32 v211, 4, v210
	v_bfe_u32 v23, v210, 2, 2
	v_lshrrev_b32_e32 v28, 1, v210
	v_and_or_b32 v23, v28, 8, v23
	v_lshlrev_b32_e32 v28, 1, v210
	v_and_b32_e32 v29, 48, v211
	v_and_or_b32 v38, v28, s73, v29
	v_bfe_i32 v28, v210, 4, 24
	v_and_b32_e32 v29, 0xffff0, v28
	v_lshrrev_b32_e32 v28, 1, v28
	v_and_b32_e32 v28, 4, v28
	v_or3_b32 v28, v29, v28, v23
	v_lshlrev_b32_e32 v36, 12, v28
	global_load_dwordx4 v[28:31], v67, s[50:51] offset:32
	global_load_dwordx4 v[42:45], v67, s[50:51] offset:64
	global_load_dwordx4 v[46:49], v67, s[50:51] offset:96
	v_add_u32_e32 v50, 0x2000, v211
	v_ashrrev_i32_e32 v33, 8, v50
	v_ashrrev_i32_e32 v16, 4, v210
	v_add_u32_e32 v18, 0x200, v210
	v_and_b32_e32 v34, 0xffff0, v33
	v_lshrrev_b32_e32 v33, 1, v33
	v_xor_b32_e32 v17, v16, v96
	v_ashrrev_i32_e32 v18, 4, v18
	v_and_b32_e32 v33, 4, v33
	v_lshlrev_b32_e32 v17, 4, v17
	v_xor_b32_e32 v19, v18, v96
	v_or3_b32 v23, v34, v33, v23
	v_lshlrev_b32_e32 v16, 12, v16
	v_lshlrev_b32_e32 v19, 4, v19
	v_lshlrev_b32_e32 v21, 7, v210
	v_or_b32_e32 v32, 0x100, v38
	v_lshlrev_b32_e32 v23, 12, v23
	v_and_or_b32 v176, v17, s74, v16
	v_lshlrev_b32_e32 v16, 12, v18
	v_bitop3_b32 v22, v211, v96, s3 bitop3:0x1e
	v_or_b32_e32 v80, v36, v32
	v_or_b32_e32 v81, v23, v32
	v_and_or_b32 v32, v19, s74, v16
	v_and_b32_e32 v16, 0xfffffc00, v21
	s_lshl_b32 s48, s54, 12
	v_and_or_b32 v34, v22, s75, v16
	v_add_u32_e32 v16, 0x4000, v211
	s_add_u32 s48, s61, s48
	v_readfirstlane_b32 s82, v16
	v_add_u32_e32 v16, 0x6000, v211
	s_addc_u32 s49, s62, 0
	s_lshl_b32 s54, s54, 10
	s_mov_b32 m0, s82
	v_readfirstlane_b32 s82, v16
	v_add_u32_e32 v16, 0x8000, v211
	s_add_u32 s54, s65, s54
	global_load_lds_dwordx4 v176, s[48:49]
	s_mov_b32 m0, s82
	v_readfirstlane_b32 s82, v16
	s_addc_u32 s55, s66, 0
	global_load_lds_dwordx4 v32, s[48:49]
	v_mov_b32_e32 v35, v177
	s_mov_b32 m0, s82
	v_or_b32_e32 v36, v38, v36
	v_mov_b32_e32 v37, v177
	v_lshl_add_u64 v[40:41], s[54:55], 0, v[34:35]
	global_load_lds_dwordx4 v34, s[54:55]
	v_lshl_add_u64 v[16:17], s[48:49], 0, v[36:37]
	v_readfirstlane_b32 s54, v211
	v_lshl_add_u64 v[16:17], v[16:17], 0, s[4:5]
	s_mov_b32 m0, s54
	v_or_b32_e32 v38, v38, v23
	v_mov_b32_e32 v39, v177
	global_load_lds_dwordx4 v[16:17], off
	v_lshl_add_u64 v[16:17], s[48:49], 0, v[38:39]
	v_readfirstlane_b32 s54, v50
	v_lshl_add_u64 v[16:17], v[16:17], 0, s[4:5]
	s_mov_b32 m0, s54
	v_and_b32_e32 v208, 0xffffffe0, v20
	global_load_lds_dwordx4 v[16:17], off
	global_load_dwordx4 v[50:53], v67, s[50:51] offset:128
	global_load_dwordx4 v[54:57], v67, s[50:51] offset:160
	global_load_dwordx4 v[58:61], v67, s[50:51] offset:192
	global_load_dwordx4 v[62:65], v67, s[50:51] offset:224
	s_nop 0
	global_load_dwordx4 v[16:19], v67, s[50:51] offset:256
	global_load_dwordx4 v[68:71], v67, s[50:51] offset:288
	global_load_dwordx4 v[20:23], v67, s[50:51] offset:320
	global_load_dwordx4 v[72:75], v67, s[50:51] offset:352
	s_waitcnt vmcnt(0)
	v_and_b32_e32 v133, 0xffff0000, v24
	v_and_b32_e32 v155, 0xffff0000, v25
	v_lshlrev_b32_e32 v132, 16, v24
	v_mul_f32_e32 v24, v133, v133
	v_lshlrev_b32_e32 v154, 16, v25
	v_mul_f32_e32 v25, v155, v155
	v_fmac_f32_e32 v24, v132, v132
	v_fmac_f32_e32 v25, v154, v154
	v_and_b32_e32 v163, 0xffff0000, v26
	v_add_f32_e32 v24, v24, v25
	v_lshlrev_b32_e32 v162, 16, v26
	v_mul_f32_e32 v25, v163, v163
	v_fmac_f32_e32 v25, v162, v162
	v_and_b32_e32 v165, 0xffff0000, v27
	v_add_f32_e32 v24, v25, v24
	v_lshlrev_b32_e32 v164, 16, v27
	v_mul_f32_e32 v25, v165, v165
	v_fmac_f32_e32 v25, v164, v164
	v_and_b32_e32 v167, 0xffff0000, v28
	v_add_f32_e32 v24, v25, v24
	v_lshlrev_b32_e32 v166, 16, v28
	v_mul_f32_e32 v25, v167, v167
	v_fmac_f32_e32 v25, v166, v166
	v_and_b32_e32 v169, 0xffff0000, v29
	v_add_f32_e32 v24, v25, v24
	v_lshlrev_b32_e32 v168, 16, v29
	v_mul_f32_e32 v25, v169, v169
	v_fmac_f32_e32 v25, v168, v168
	v_and_b32_e32 v125, 0xffff0000, v30
	v_add_f32_e32 v24, v25, v24
	v_lshlrev_b32_e32 v126, 16, v30
	v_mul_f32_e32 v25, v125, v125
	v_fmac_f32_e32 v25, v126, v126
	v_and_b32_e32 v127, 0xffff0000, v31
	v_add_f32_e32 v24, v25, v24
	v_lshlrev_b32_e32 v170, 16, v31
	v_mul_f32_e32 v25, v127, v127
	v_fmac_f32_e32 v25, v170, v170
	v_and_b32_e32 v172, 0xffff0000, v42
	v_add_f32_e32 v24, v25, v24
	v_lshlrev_b32_e32 v171, 16, v42
	v_mul_f32_e32 v25, v172, v172
	v_fmac_f32_e32 v25, v171, v171
	v_and_b32_e32 v174, 0xffff0000, v43
	v_add_f32_e32 v24, v25, v24
	v_lshlrev_b32_e32 v173, 16, v43
	v_mul_f32_e32 v25, v174, v174
	v_fmac_f32_e32 v25, v173, v173
	v_and_b32_e32 v178, 0xffff0000, v44
	v_add_f32_e32 v24, v25, v24
	v_lshlrev_b32_e32 v175, 16, v44
	v_mul_f32_e32 v25, v178, v178
	v_fmac_f32_e32 v25, v175, v175
	v_and_b32_e32 v117, 0xffff0000, v45
	v_add_f32_e32 v24, v25, v24
	v_lshlrev_b32_e32 v118, 16, v45
	v_mul_f32_e32 v25, v117, v117
	v_fmac_f32_e32 v25, v118, v118
	v_and_b32_e32 v119, 0xffff0000, v46
	v_add_f32_e32 v24, v25, v24
	v_lshlrev_b32_e32 v120, 16, v46
	v_mul_f32_e32 v25, v119, v119
	v_fmac_f32_e32 v25, v120, v120
	v_and_b32_e32 v121, 0xffff0000, v47
	v_add_f32_e32 v24, v25, v24
; __device__ __forceinline__ float bflo(unsigned w) { return __uint_as_float(w << 16); }
; __device__ __forceinline__ float bfhi(unsigned w) { return __uint_as_float(w & 0xffff0000u); }
; __device__ __forceinline__ void attn_body(const u16* __restrict__ Qb, const u16* __restrict__ Kn, const u16* __restrict__ Kr,
;                                           u16* __restrict__ Ob, char* lds, int tid, const float* __restrict__ gq_, const float* __restrict__ tab_, int qpos0, float negM) {
;     ...
;       for (int e = 0; e < 4; ++e) { const float a = bflo(qw[d0][e]), b = bfhi(qw[d0][e]); ss += a * a + b * b; }
;     { auto rr = __builtin_amdgcn_permlane32_swap(__float_as_uint(ss), __float_as_uint(ss), false, false);
;       ss = __uint_as_float(rr[0]) + __uint_as_float(rr[1]); }
;     const float rq = rsqrtf(ss * (1.f / 192.f) + EPS) * QSCALE;
;     const float* gq = gq_ + hi * 8;
; #pragma unroll
;     for (int d0 = 0; d0 < 8; ++d0) {
;       const f32x4 g0 = *reinterpret_cast<const f32x4*>(gq + d0 * 16), g1 = *reinterpret_cast<const f32x4*>(gq + d0 * 16 + 4);
;       const u32x4 w = qw[d0];
;       const u32x4 o = {cvtpk(bflo(w[0]) * rq * g0[0], bfhi(w[0]) * rq * g0[1]), cvtpk(bflo(w[1]) * rq * g0[2], bfhi(w[1]) * rq * g0[3]),
;                        cvtpk(bflo(w[2]) * rq * g1[0], bfhi(w[2]) * rq * g1[1]), cvtpk(bflo(w[3]) * rq * g1[2], bfhi(w[3]) * rq * g1[3])};
;       qr[d0] = *reinterpret_cast<const bf16x8*>(&o); }
;     const float* tcp = tab_ + (size_t)(qpos0 + wid * 32 + r32) * 32 + hi * 8; const float* tsp = tcp + SEQ * 32;
; #pragma unroll
;     for (int dd = 0; dd < 2; ++dd) {
;       float x1[8], x2[8], c_[8], s_[8];
;       { const f32x4 ga = *reinterpret_cast<const f32x4*>(gq + 128 + dd * 16), gb = *reinterpret_cast<const f32x4*>(gq + 128 + dd * 16 + 4);
;         const f32x4 gc = *reinterpret_cast<const f32x4*>(gq + 160 + dd * 16), gd = *reinterpret_cast<const f32x4*>(gq + 160 + dd * 16 + 4);
;         const f32x4 ca = *reinterpret_cast<const f32x4*>(tcp + dd * 16), cb = *reinterpret_cast<const f32x4*>(tcp + dd * 16 + 4);
;         const f32x4 sa = *reinterpret_cast<const f32x4*>(tsp + dd * 16), sb = *reinterpret_cast<const f32x4*>(tsp + dd * 16 + 4);
	v_lshlrev_b32_e32 v122, 16, v47
	v_mul_f32_e32 v25, v121, v121
	v_fmac_f32_e32 v25, v122, v122
	v_and_b32_e32 v123, 0xffff0000, v48
	v_add_f32_e32 v24, v25, v24
	v_lshlrev_b32_e32 v124, 16, v48
	v_mul_f32_e32 v25, v123, v123
	v_fmac_f32_e32 v25, v124, v124
	v_and_b32_e32 v110, 0xffff0000, v49
	v_add_f32_e32 v24, v25, v24
	v_lshlrev_b32_e32 v111, 16, v49
	v_mul_f32_e32 v25, v110, v110
	v_fmac_f32_e32 v25, v111, v111
	v_and_b32_e32 v112, 0xffff0000, v50
	v_add_f32_e32 v24, v25, v24
	v_lshlrev_b32_e32 v113, 16, v50
	v_mul_f32_e32 v25, v112, v112
	v_fmac_f32_e32 v25, v113, v113
	v_and_b32_e32 v114, 0xffff0000, v51
	v_add_f32_e32 v24, v25, v24
	v_lshlrev_b32_e32 v115, 16, v51
	v_mul_f32_e32 v25, v114, v114
	v_fmac_f32_e32 v25, v115, v115
	v_and_b32_e32 v90, 0xffff0000, v52
	v_add_f32_e32 v24, v25, v24
	v_lshlrev_b32_e32 v116, 16, v52
	v_mul_f32_e32 v25, v90, v90
	v_fmac_f32_e32 v25, v116, v116
	v_and_b32_e32 v94, 0xffff0000, v53
	v_add_f32_e32 v24, v25, v24
	v_lshlrev_b32_e32 v98, 16, v53
	v_mul_f32_e32 v25, v94, v94
	v_fmac_f32_e32 v25, v98, v98
	v_and_b32_e32 v99, 0xffff0000, v54
	v_add_f32_e32 v24, v25, v24
	v_lshlrev_b32_e32 v103, 16, v54
	v_mul_f32_e32 v25, v99, v99
	v_fmac_f32_e32 v25, v103, v103
	v_and_b32_e32 v104, 0xffff0000, v55
	v_add_f32_e32 v24, v25, v24
	v_lshlrev_b32_e32 v106, 16, v55
	v_mul_f32_e32 v25, v104, v104
	v_fmac_f32_e32 v25, v106, v106
	v_and_b32_e32 v107, 0xffff0000, v56
	v_add_f32_e32 v24, v25, v24
	v_lshlrev_b32_e32 v108, 16, v56
	v_mul_f32_e32 v25, v107, v107
	v_fmac_f32_e32 v25, v108, v108
	v_and_b32_e32 v82, 0xffff0000, v57
	v_add_f32_e32 v24, v25, v24
	v_lshlrev_b32_e32 v109, 16, v57
	v_mul_f32_e32 v25, v82, v82
	v_fmac_f32_e32 v25, v109, v109
	v_and_b32_e32 v83, 0xffff0000, v58
	v_add_f32_e32 v24, v25, v24
	v_lshlrev_b32_e32 v84, 16, v58
	v_mul_f32_e32 v25, v83, v83
	v_fmac_f32_e32 v25, v84, v84
	v_and_b32_e32 v85, 0xffff0000, v59
	v_add_f32_e32 v24, v25, v24
	v_lshlrev_b32_e32 v86, 16, v59
	v_mul_f32_e32 v25, v85, v85
	v_fmac_f32_e32 v25, v86, v86
	v_and_b32_e32 v87, 0xffff0000, v60
	v_add_f32_e32 v24, v25, v24
	v_lshlrev_b32_e32 v88, 16, v60
	v_mul_f32_e32 v25, v87, v87
	v_fmac_f32_e32 v25, v88, v88
	v_and_b32_e32 v89, 0xffff0000, v61
	v_add_f32_e32 v24, v25, v24
	v_lshlrev_b32_e32 v91, 16, v61
	v_mul_f32_e32 v25, v89, v89
	v_fmac_f32_e32 v25, v91, v91
	v_and_b32_e32 v92, 0xffff0000, v62
	v_add_f32_e32 v24, v25, v24
	v_lshlrev_b32_e32 v95, 16, v62
	v_mul_f32_e32 v25, v92, v92
	v_fmac_f32_e32 v25, v95, v95
	v_and_b32_e32 v93, 0xffff0000, v63
	v_add_f32_e32 v24, v25, v24
	v_lshlrev_b32_e32 v100, 16, v63
	v_mul_f32_e32 v25, v93, v93
	v_fmac_f32_e32 v25, v100, v100
	v_and_b32_e32 v97, 0xffff0000, v64
	v_add_f32_e32 v24, v25, v24
	v_lshlrev_b32_e32 v101, 16, v64
	v_mul_f32_e32 v25, v97, v97
	v_fmac_f32_e32 v25, v101, v101
	v_and_b32_e32 v102, 0xffff0000, v65
	v_add_f32_e32 v24, v25, v24
	v_lshlrev_b32_e32 v105, 16, v65
	v_mul_f32_e32 v25, v102, v102
	v_fmac_f32_e32 v25, v105, v105
	v_and_b32_e32 v58, 32, v96
	v_add_f32_e32 v146, v25, v24
	global_load_dwordx4 v[24:27], v58, s[52:53] offset:16
	global_load_dwordx4 v[28:31], v58, s[52:53]
	global_load_dwordx4 v[134:137], v58, s[52:53] offset:80
	global_load_dwordx4 v[138:141], v58, s[52:53] offset:64
	s_and_b32 s81, s0, 0x700
	v_add_u32_e32 v42, s81, v66
	v_ashrrev_i32_e32 v43, 31, v42
	v_lshlrev_b64 v[42:43], 7, v[42:43]
	v_lshl_add_u64 v[66:67], s[8:9], 0, v[42:43]
	v_and_b32_e32 v42, 0xffff0000, v75
	v_and_b32_e32 v46, 0xffff0000, v74
	v_lshlrev_b32_e32 v44, 16, v75
	v_lshlrev_b32_e32 v48, 16, v74
	v_mov_b32_e32 v52, v42
	v_mov_b32_e32 v53, v46
	v_mov_b32_e32 v50, v44
	v_mov_b32_e32 v51, v48
	v_pk_mul_f32 v[52:53], v[52:53], v[52:53]
	v_and_b32_e32 v54, 0xffff0000, v72
	v_pk_fma_f32 v[78:79], v[50:51], v[50:51], v[52:53]
	v_and_b32_e32 v50, 0xffff0000, v73
	v_lshlrev_b32_e32 v52, 16, v73
	v_lshlrev_b32_e32 v56, 16, v72
	v_mov_b32_e32 v62, v50
	v_mov_b32_e32 v63, v54
	v_mov_b32_e32 v60, v52
	v_mov_b32_e32 v61, v56
	v_pk_mul_f32 v[62:63], v[62:63], v[62:63]
	v_lshlrev_b32_e32 v53, 16, v69
	v_and_b32_e32 v51, 0xffff0000, v69
	v_lshlrev_b32_e32 v57, 16, v68
	v_and_b32_e32 v55, 0xffff0000, v68
	v_pk_fma_f32 v[68:69], v[60:61], v[60:61], v[62:63]
	v_and_b32_e32 v60, 0xffff0000, v23
	v_lshlrev_b32_e32 v64, 16, v22
	v_and_b32_e32 v22, 0xffff0000, v22
	v_lshlrev_b32_e32 v45, 16, v71
	v_and_b32_e32 v43, 0xffff0000, v71
	v_lshlrev_b32_e32 v49, 16, v70
	v_and_b32_e32 v47, 0xffff0000, v70
	v_lshlrev_b32_e32 v62, 16, v23
	v_mov_b32_e32 v70, v60
	v_mov_b32_e32 v71, v22
	v_lshlrev_b32_e32 v63, 16, v19
	v_and_b32_e32 v61, 0xffff0000, v19
	v_lshlrev_b32_e32 v65, 16, v18
	v_and_b32_e32 v23, 0xffff0000, v18
	v_mov_b32_e32 v18, v62
	v_mov_b32_e32 v19, v64
	v_pk_mul_f32 v[70:71], v[70:71], v[70:71]
	v_and_b32_e32 v75, 0xffff0000, v16
	v_and_b32_e32 v74, 0xffff0000, v20
	v_pk_fma_f32 v[128:129], v[18:19], v[18:19], v[70:71]
	v_lshlrev_b32_e32 v72, 16, v21
	v_and_b32_e32 v71, 0xffff0000, v17
	v_and_b32_e32 v70, 0xffff0000, v21
	v_lshlrev_b32_e32 v77, 16, v16
	v_lshlrev_b32_e32 v76, 16, v20
	v_pk_mul_f32 v[20:21], v[74:75], v[74:75]
	v_lshlrev_b32_e32 v73, 16, v17
	v_pk_mul_f32 v[18:19], v[70:71], v[70:71]
	v_pk_fma_f32 v[20:21], v[76:77], v[76:77], v[20:21]
	v_mul_f32_e32 v152, v65, v65
	v_pk_fma_f32 v[130:131], v[72:73], v[72:73], v[18:19]
	v_add_f32_e32 v21, v21, v146
	v_mul_f32_e32 v151, v63, v63
	v_fmac_f32_e32 v152, v23, v23
	v_add_f32_e32 v21, v131, v21
	v_mul_f32_e32 v150, v57, v57
	v_fmac_f32_e32 v151, v61, v61
	v_add_f32_e32 v21, v152, v21
	v_mul_f32_e32 v149, v53, v53
	v_fmac_f32_e32 v150, v55, v55
	v_add_f32_e32 v21, v151, v21
	v_mul_f32_e32 v148, v49, v49
	v_fmac_f32_e32 v149, v51, v51
	v_add_f32_e32 v21, v150, v21
	v_mul_f32_e32 v147, v45, v45
	v_fmac_f32_e32 v148, v47, v47
	v_add_f32_e32 v21, v149, v21
	v_fmac_f32_e32 v147, v43, v43
	v_add_f32_e32 v21, v148, v21
	v_add_f32_e32 v21, v147, v21
	v_add_f32_e32 v20, v20, v21
	v_add_f32_e32 v20, v130, v20
	v_add_f32_e32 v20, v129, v20
	v_add_f32_e32 v20, v128, v20
	v_add_f32_e32 v20, v69, v20
	v_add_f32_e32 v20, v68, v20
	v_add_f32_e32 v20, v79, v20
	v_add_f32_e32 v20, v78, v20
	v_mov_b32_e32 v21, v20
	s_nop 1
	v_permlane32_swap_b32_e32 v20, v21
	global_load_dwordx4 v[16:19], v58, s[52:53] offset:144
	global_load_dwordx4 v[142:145], v58, s[52:53] offset:128
	v_add_f32_e32 v20, v20, v21
	v_mov_b32_e32 v21, 0x358637bd
	v_fmamk_f32 v20, v20, 0x3baaaaab, v21
	v_mul_f32_e32 v21, 0x4b800000, v20
	v_cmp_gt_f32_e32 vcc, s77, v20
	global_load_dwordx4 v[146:149], v58, s[52:53] offset:208
	global_load_dwordx4 v[150:153], v58, s[52:53] offset:192
	v_cndmask_b32_e32 v20, v20, v21, vcc
	v_rsq_f32_e32 v20, v20
	v_mov_b32_e32 v59, v177
	v_lshl_add_u64 v[68:69], v[66:67], 0, v[58:59]
	v_lshl_add_u64 v[78:79], v[68:69], 0, s[10:11]
	v_mul_f32_e32 v21, 0x45800000, v20
	v_cndmask_b32_e32 v20, v20, v21, vcc
	v_mul_f32_e32 v20, 0x3dd53b94, v20
	v_mul_f32_e32 v21, v20, v132
	s_waitcnt vmcnt(0)
; __device__ __forceinline__ float bflo(unsigned w) { return __uint_as_float(w << 16); }
; __device__ __forceinline__ float bfhi(unsigned w) { return __uint_as_float(w & 0xffff0000u); }
; __device__ __forceinline__ void attn_body(const u16* __restrict__ Qb, const u16* __restrict__ Kn, const u16* __restrict__ Kr,
;                                           u16* __restrict__ Ob, char* lds, int tid, const float* __restrict__ gq_, const float* __restrict__ tab_, int qpos0, float negM) {
;     ...
;     const float rq = rsqrtf(ss * (1.f / 192.f) + EPS) * QSCALE;
;     const float* gq = gq_ + hi * 8;
; #pragma unroll
;     for (int d0 = 0; d0 < 8; ++d0) {
;       const f32x4 g0 = *reinterpret_cast<const f32x4*>(gq + d0 * 16), g1 = *reinterpret_cast<const f32x4*>(gq + d0 * 16 + 4);
;       const u32x4 w = qw[d0];
;       const u32x4 o = {cvtpk(bflo(w[0]) * rq * g0[0], bfhi(w[0]) * rq * g0[1]), cvtpk(bflo(w[1]) * rq * g0[2], bfhi(w[1]) * rq * g0[3]),
;                        cvtpk(bflo(w[2]) * rq * g1[0], bfhi(w[2]) * rq * g1[1]), cvtpk(bflo(w[3]) * rq * g1[2], bfhi(w[3]) * rq * g1[3])};
;       qr[d0] = *reinterpret_cast<const bf16x8*>(&o); }
;     const float* tcp = tab_ + (size_t)(qpos0 + wid * 32 + r32) * 32 + hi * 8; const float* tsp = tcp + SEQ * 32;
; #pragma unroll
;     for (int dd = 0; dd < 2; ++dd) {
;       float x1[8], x2[8], c_[8], s_[8];
;       { const f32x4 ga = *reinterpret_cast<const f32x4*>(gq + 128 + dd * 16), gb = *reinterpret_cast<const f32x4*>(gq + 128 + dd * 16 + 4);
;         const f32x4 gc = *reinterpret_cast<const f32x4*>(gq + 160 + dd * 16), gd = *reinterpret_cast<const f32x4*>(gq + 160 + dd * 16 + 4);
;         const f32x4 ca = *reinterpret_cast<const f32x4*>(tcp + dd * 16), cb = *reinterpret_cast<const f32x4*>(tcp + dd * 16 + 4);
;         const f32x4 sa = *reinterpret_cast<const f32x4*>(tsp + dd * 16), sb = *reinterpret_cast<const f32x4*>(tsp + dd * 16 + 4);
	v_mul_f32_e32 v21, v28, v21
	v_mul_f32_e32 v28, v20, v133
	v_mul_f32_e32 v28, v29, v28
	s_nop 0
	v_cvt_pk_bf16_f32 v128, v21, v28
	v_mul_f32_e32 v21, v20, v154
	v_mul_f32_e32 v21, v30, v21
	v_mul_f32_e32 v28, v20, v155
	v_mul_f32_e32 v28, v31, v28
	s_nop 0
	v_cvt_pk_bf16_f32 v129, v21, v28
	v_mul_f32_e32 v21, v20, v162
	global_load_dwordx4 v[154:157], v58, s[52:53] offset:272
	global_load_dwordx4 v[158:161], v58, s[52:53] offset:256
	v_mul_f32_e32 v21, v24, v21
	v_mul_f32_e32 v24, v20, v163
	v_mul_f32_e32 v24, v25, v24
	s_nop 0
	v_cvt_pk_bf16_f32 v130, v21, v24
	v_mul_f32_e32 v24, v20, v165
	v_mul_f32_e32 v21, v20, v164
	v_mul_f32_e32 v24, v27, v24
	v_mul_f32_e32 v21, v26, v21
	s_nop 0
	v_cvt_pk_bf16_f32 v131, v21, v24
	v_mul_f32_e32 v24, v20, v167
	v_mul_f32_e32 v21, v20, v166
	v_mul_f32_e32 v24, v139, v24
	v_mul_f32_e32 v21, v138, v21
	s_nop 0
	v_cvt_pk_bf16_f32 v132, v21, v24
	v_mul_f32_e32 v24, v20, v169
	v_mul_f32_e32 v21, v20, v168
	v_mul_f32_e32 v24, v141, v24
	v_mul_f32_e32 v21, v140, v21
	s_nop 0
	v_cvt_pk_bf16_f32 v133, v21, v24
	global_load_dwordx4 v[24:27], v58, s[52:53] offset:336
	global_load_dwordx4 v[28:31], v58, s[52:53] offset:320
	v_mul_f32_e32 v21, v20, v126
	v_mul_f32_e32 v21, v134, v21
	v_mul_f32_e32 v59, v20, v125
	v_mul_f32_e32 v59, v135, v59
	s_nop 0
	v_cvt_pk_bf16_f32 v134, v21, v59
	v_mul_f32_e32 v21, v20, v170
	v_mul_f32_e32 v21, v136, v21
	v_mul_f32_e32 v59, v20, v127
	v_mul_f32_e32 v59, v137, v59
	s_nop 0
	v_cvt_pk_bf16_f32 v135, v21, v59
	v_mul_f32_e32 v21, v20, v171
	v_mul_f32_e32 v59, v20, v172
	global_load_dwordx4 v[162:165], v58, s[52:53] offset:400
	global_load_dwordx4 v[166:169], v58, s[52:53] offset:384
	v_lshl_add_u64 v[66:67], v[68:69], 0, s[12:13]
	v_and_b32_e32 v209, 63, v96
	v_and_b32_e32 v206, 31, v96
	v_mov_b32_e32 v33, v177
	s_mov_b32 s50, 0
	v_mul_f32_e32 v21, v21, v142
	v_mul_f32_e32 v59, v59, v143
	s_nop 0
	v_cvt_pk_bf16_f32 v136, v21, v59
	v_mul_f32_e32 v21, v20, v173
	v_mul_f32_e32 v21, v21, v144
	v_mul_f32_e32 v59, v20, v174
	v_mul_f32_e32 v59, v59, v145
	s_nop 0
	v_cvt_pk_bf16_f32 v137, v21, v59
	v_mul_f32_e32 v21, v20, v175
	v_mul_f32_e32 v16, v21, v16
	v_mul_f32_e32 v21, v20, v178
	v_mul_f32_e32 v17, v21, v17
	s_nop 0
	v_cvt_pk_bf16_f32 v138, v16, v17
	v_mul_f32_e32 v16, v20, v118
	v_mul_f32_e32 v16, v16, v18
	v_mul_f32_e32 v17, v20, v117
	v_mul_f32_e32 v17, v17, v19
	s_nop 0
	v_cvt_pk_bf16_f32 v139, v16, v17
	v_mul_f32_e32 v16, v20, v120
	v_mul_f32_e32 v16, v16, v150
	v_mul_f32_e32 v17, v20, v119
	v_mul_f32_e32 v17, v17, v151
	s_nop 0
	v_cvt_pk_bf16_f32 v140, v16, v17
	v_mul_f32_e32 v16, v20, v122
	v_mul_f32_e32 v16, v16, v152
	v_mul_f32_e32 v17, v20, v121
	v_mul_f32_e32 v17, v17, v153
	s_nop 0
	v_cvt_pk_bf16_f32 v141, v16, v17
	v_mul_f32_e32 v16, v20, v124
	v_mul_f32_e32 v16, v16, v146
	v_mul_f32_e32 v17, v20, v123
	v_mul_f32_e32 v17, v17, v147
	s_nop 0
	v_cvt_pk_bf16_f32 v142, v16, v17
	v_mul_f32_e32 v16, v20, v111
	v_mul_f32_e32 v16, v16, v148
	v_mul_f32_e32 v17, v20, v110
	v_mul_f32_e32 v17, v17, v149
	s_nop 0
	v_cvt_pk_bf16_f32 v143, v16, v17
	v_mul_f32_e32 v16, v20, v113
	s_waitcnt vmcnt(0)
	v_mul_f32_e32 v16, v16, v158
	v_mul_f32_e32 v17, v20, v112
	v_mul_f32_e32 v17, v17, v159
	s_nop 0
	v_cvt_pk_bf16_f32 v144, v16, v17
	v_mul_f32_e32 v16, v20, v115
	v_mul_f32_e32 v16, v16, v160
	v_mul_f32_e32 v17, v20, v114
	global_load_dwordx4 v[118:121], v58, s[52:53] offset:464
	global_load_dwordx4 v[122:125], v58, s[52:53] offset:448
	v_mul_f32_e32 v17, v17, v161
	s_nop 0
	v_cvt_pk_bf16_f32 v145, v16, v17
	v_mul_f32_e32 v16, v20, v116
	v_mul_f32_e32 v16, v16, v154
	v_mul_f32_e32 v17, v20, v90
	v_mul_f32_e32 v17, v17, v155
	s_nop 0
	v_cvt_pk_bf16_f32 v146, v16, v17
	v_mul_f32_e32 v16, v20, v98
	v_mul_f32_e32 v16, v16, v156
	v_mul_f32_e32 v17, v20, v94
	v_mul_f32_e32 v17, v17, v157
	s_nop 0
	v_cvt_pk_bf16_f32 v147, v16, v17
	v_mul_f32_e32 v16, v20, v103
	v_mul_f32_e32 v16, v16, v28
	v_mul_f32_e32 v17, v20, v99
	v_mul_f32_e32 v17, v17, v29
	s_nop 0
	v_cvt_pk_bf16_f32 v148, v16, v17
	v_mul_f32_e32 v16, v20, v106
	global_load_dwordx4 v[110:113], v58, s[52:53] offset:656
	global_load_dwordx4 v[114:117], v58, s[52:53] offset:640
	global_load_dwordx4 v[170:173], v58, s[52:53] offset:528
	global_load_dwordx4 v[178:181], v58, s[52:53] offset:512
	v_mul_f32_e32 v16, v16, v30
	v_mul_f32_e32 v17, v20, v104
	v_mul_f32_e32 v17, v17, v31
	s_nop 0
	v_cvt_pk_bf16_f32 v149, v16, v17
	v_mul_f32_e32 v16, v20, v108
	v_mul_f32_e32 v16, v16, v24
	v_mul_f32_e32 v17, v20, v107
	v_add_co_u32_e32 v98, vcc, s78, v68
	v_mul_f32_e32 v17, v17, v25
	s_nop 0
	v_cvt_pk_bf16_f32 v150, v16, v17
	v_mul_f32_e32 v16, v20, v109
	v_addc_co_u32_e32 v99, vcc, 0, v69, vcc
	v_mul_f32_e32 v21, v16, v26
	global_load_dwordx4 v[28:31], v[98:99], off
	global_load_dwordx4 v[16:19], v[68:69], off offset:16
	global_load_dwordx4 v[106:109], v[68:69], off
	v_mul_f32_e32 v24, v20, v82
	v_mul_f32_e32 v24, v24, v27
	s_nop 0
	v_cvt_pk_bf16_f32 v151, v21, v24
	v_mul_f32_e32 v21, v20, v84
	v_mul_f32_e32 v21, v21, v166
	v_mul_f32_e32 v24, v20, v83
	v_mul_f32_e32 v24, v24, v167
	s_nop 0
	v_cvt_pk_bf16_f32 v152, v21, v24
	v_mul_f32_e32 v21, v20, v86
	v_mul_f32_e32 v21, v21, v168
	v_mul_f32_e32 v24, v20, v85
	v_mul_f32_e32 v24, v24, v169
	s_nop 0
	v_cvt_pk_bf16_f32 v153, v21, v24
	v_mul_f32_e32 v21, v20, v88
	v_mul_f32_e32 v21, v21, v162
	v_mul_f32_e32 v24, v20, v87
	v_mul_f32_e32 v24, v24, v163
	s_nop 0
	v_cvt_pk_bf16_f32 v154, v21, v24
	v_mul_f32_e32 v21, v20, v91
	v_mul_f32_e32 v21, v21, v164
	v_mul_f32_e32 v24, v20, v89
	v_mul_f32_e32 v24, v24, v165
	s_nop 0
	v_cvt_pk_bf16_f32 v155, v21, v24
	v_mul_f32_e32 v21, v20, v95
	v_mul_f32_e32 v24, v20, v92
	v_mul_f32_e32 v59, v20, v93
	s_waitcnt vmcnt(0)
; __device__ __forceinline__ void attn_body(const u16* __restrict__ Qb, const u16* __restrict__ Kn, const u16* __restrict__ Kr,
;                                           u16* __restrict__ Ob, char* lds, int tid, const float* __restrict__ gq_, const float* __restrict__ tab_, int qpos0, float negM) {
;     ...
;     const float* tcp = tab_ + (size_t)(qpos0 + wid * 32 + r32) * 32 + hi * 8; const float* tsp = tcp + SEQ * 32;
; #pragma unroll
;     for (int dd = 0; dd < 2; ++dd) {
;       float x1[8], x2[8], c_[8], s_[8];
;       { const f32x4 ga = *reinterpret_cast<const f32x4*>(gq + 128 + dd * 16), gb = *reinterpret_cast<const f32x4*>(gq + 128 + dd * 16 + 4);
;         const f32x4 gc = *reinterpret_cast<const f32x4*>(gq + 160 + dd * 16), gd = *reinterpret_cast<const f32x4*>(gq + 160 + dd * 16 + 4);
;         const f32x4 ca = *reinterpret_cast<const f32x4*>(tcp + dd * 16), cb = *reinterpret_cast<const f32x4*>(tcp + dd * 16 + 4);
;         const f32x4 sa = *reinterpret_cast<const f32x4*>(tsp + dd * 16), sb = *reinterpret_cast<const f32x4*>(tsp + dd * 16 + 4);
;         const u32x4 w1 = qw[8 + dd], w2 = qw[10 + dd];
; #pragma unroll
;         for (int e = 0; e < 4; ++e) {
;           const float g1lo = e < 2 ? ga[2 * e] : gb[2 * e - 4], g1hi = e < 2 ? ga[2 * e + 1] : gb[2 * e - 3];
;           const float g2lo = e < 2 ? gc[2 * e] : gd[2 * e - 4], g2hi = e < 2 ? gc[2 * e + 1] : gd[2 * e - 3];
;           x1[2 * e] = bflo(w1[e]) * rq * g1lo; x1[2 * e + 1] = bfhi(w1[e]) * rq * g1hi;
;           x2[2 * e] = bflo(w2[e]) * rq * g2lo; x2[2 * e + 1] = bfhi(w2[e]) * rq * g2hi;
;           c_[2 * e] = e < 2 ? ca[2 * e] : cb[2 * e - 4]; c_[2 * e + 1] = e < 2 ? ca[2 * e + 1] : cb[2 * e - 3];
;           s_[2 * e] = e < 2 ? sa[2 * e] : sb[2 * e - 4]; s_[2 * e + 1] = e < 2 ? sa[2 * e + 1] : sb[2 * e - 3]; } }
;       float y1[8], y2[8];
; #pragma unroll
;       for (int e = 0; e < 8; ++e) { y1[e] = x1[e] * c_[e] - x2[e] * s_[e]; y2[e] = x2[e] * c_[e] + x1[e] * s_[e]; }
;       const u32x4 o1 = {cvtpk(y1[0], y1[1]), cvtpk(y1[2], y1[3]), cvtpk(y1[4], y1[5]), cvtpk(y1[6], y1[7])};
;       const u32x4 o2 = {cvtpk(y2[0], y2[1]), cvtpk(y2[2], y2[3]), cvtpk(y2[4], y2[5]), cvtpk(y2[6], y2[7])};
;       qr[8 + dd] = *reinterpret_cast<const bf16x8*>(&o1); qr[10 + dd] = *reinterpret_cast<const bf16x8*>(&o2); }
	v_mul_f32_e32 v21, v21, v122
	v_mul_f32_e32 v24, v24, v123
	s_nop 0
	v_cvt_pk_bf16_f32 v156, v21, v24
	v_mul_f32_e32 v21, v20, v100
	v_mul_f32_e32 v21, v21, v124
	global_load_dwordx4 v[24:27], v[78:79], off offset:16
	v_mul_f32_e32 v59, v59, v125
	s_nop 0
	v_cvt_pk_bf16_f32 v157, v21, v59
	v_mul_f32_e32 v21, v20, v101
	v_mul_f32_e32 v21, v21, v118
	v_mul_f32_e32 v59, v20, v97
	v_mul_f32_e32 v59, v59, v119
	s_nop 0
	v_cvt_pk_bf16_f32 v158, v21, v59
	v_mul_f32_e32 v21, v20, v105
	v_mul_f32_e32 v21, v21, v120
	v_pk_mul_f32 v[74:75], v[20:21], v[74:75] op_sel_hi:[0,1]
	v_mul_f32_e32 v59, v20, v102
	v_pk_mul_f32 v[70:71], v[20:21], v[70:71] op_sel_hi:[0,1]
	v_mul_f32_e32 v59, v59, v121
	v_mov_b32_e32 v79, v178
	v_mov_b32_e32 v178, v115
	v_pk_mul_f32 v[90:91], v[74:75], v[178:179]
	v_mov_b32_e32 v75, v180
	v_mov_b32_e32 v180, v117
	v_pk_mul_f32 v[76:77], v[20:21], v[76:77] op_sel_hi:[0,1]
	v_mov_b32_e32 v78, v114
	v_pk_mul_f32 v[72:73], v[20:21], v[72:73] op_sel_hi:[0,1]
	v_mov_b32_e32 v74, v116
	v_pk_mul_f32 v[100:101], v[70:71], v[180:181]
	v_pk_mul_f32 v[64:65], v[20:21], v[64:65] op_sel_hi:[0,1]
	v_mov_b32_e32 v70, v110
	v_mov_b32_e32 v71, v170
	s_nop 0
	v_cvt_pk_bf16_f32 v159, v21, v59
	v_pk_mul_f32 v[78:79], v[76:77], v[78:79]
	v_pk_mul_f32 v[94:95], v[72:73], v[74:75]
	v_pk_mul_f32 v[102:103], v[64:65], v[70:71]
	global_load_dwordx4 v[70:73], v58, s[52:53] offset:720
	global_load_dwordx4 v[74:77], v58, s[52:53] offset:704
	global_load_dwordx4 v[82:85], v58, s[52:53] offset:592
	global_load_dwordx4 v[86:89], v58, s[52:53] offset:576
	v_pk_mul_f32 v[58:59], v[20:21], v[62:63] op_sel_hi:[0,1]
	v_mov_b32_e32 v62, v112
	v_mov_b32_e32 v63, v172
	v_pk_mul_f32 v[104:105], v[58:59], v[62:63]
	v_mov_b32_e32 v62, v28
	v_mov_b32_e32 v63, v106
	v_pk_mul_f32 v[62:63], v[78:79], v[62:63]
	v_pk_mul_f32 v[22:23], v[20:21], v[22:23] op_sel_hi:[0,1]
	v_pk_mul_f32 v[58:59], v[20:21], v[60:61] op_sel_hi:[0,1]
	v_sub_f32_e32 v21, v63, v62
	v_mov_b32_e32 v62, v106
	v_mov_b32_e32 v63, v28
	v_pk_mul_f32 v[62:63], v[78:79], v[62:63]
	v_mov_b32_e32 v106, v29
	v_mov_b32_e32 v172, v113
	v_add_f32_e32 v78, v62, v63
	v_pk_mul_f32 v[62:63], v[90:91], v[106:107]
	v_mov_b32_e32 v28, v107
	v_mov_b32_e32 v170, v111
	v_pk_mul_f32 v[110:111], v[58:59], v[172:173]
	global_load_dwordx4 v[58:61], v[98:99], off offset:64
	v_sub_f32_e32 v79, v63, v62
	v_pk_mul_f32 v[28:29], v[90:91], v[28:29]
	global_load_dwordx4 v[62:65], v[68:69], off offset:80
	global_load_dwordx4 v[90:93], v[68:69], off offset:64
	v_add_f32_e32 v97, v28, v29
	v_mov_b32_e32 v28, v30
	v_mov_b32_e32 v29, v108
	v_pk_mul_f32 v[28:29], v[94:95], v[28:29]
	v_pk_mul_f32 v[22:23], v[22:23], v[170:171]
	v_sub_f32_e32 v68, v29, v28
	v_mov_b32_e32 v28, v108
	v_mov_b32_e32 v29, v30
	v_pk_mul_f32 v[28:29], v[94:95], v[28:29]
	v_mov_b32_e32 v108, v31
	v_add_f32_e32 v69, v28, v29
	v_pk_mul_f32 v[28:29], v[100:101], v[108:109]
	v_mov_b32_e32 v30, v109
	v_sub_f32_e32 v94, v29, v28
	v_pk_mul_f32 v[28:29], v[100:101], v[30:31]
	s_nop 0
	v_cvt_pk_bf16_f32 v164, v21, v79
	v_pk_mul_f32 v[46:47], v[20:21], v[46:47] op_sel_hi:[0,1]
	v_add_f32_e32 v95, v28, v29
	global_load_dwordx4 v[28:31], v[66:67], off offset:16
	v_mov_b32_e32 v67, v16
	v_pk_mul_f32 v[44:45], v[20:21], v[44:45] op_sel_hi:[0,1]
	s_waitcnt vmcnt(0)
	s_nop 0
	v_cvt_pk_bf16_f32 v165, v68, v94
	s_nop 0
	v_cvt_pk_bf16_f32 v160, v78, v97
	s_waitcnt vmcnt(0)
	v_mov_b32_e32 v66, v24
	v_pk_mul_f32 v[66:67], v[102:103], v[66:67]
	s_nop 0
	v_cvt_pk_bf16_f32 v161, v69, v95
	s_barrier
	v_sub_f32_e32 v98, v67, v66
	v_mov_b32_e32 v66, v16
	v_mov_b32_e32 v67, v24
	v_pk_mul_f32 v[66:67], v[102:103], v[66:67]
	v_mov_b32_e32 v16, v25
	v_mov_b32_e32 v24, v17
	v_add_f32_e32 v99, v66, v67
	v_pk_mul_f32 v[66:67], v[22:23], v[16:17]
	v_pk_mul_f32 v[16:17], v[22:23], v[24:25]
	v_sub_f32_e32 v66, v67, v66
	v_add_f32_e32 v22, v16, v17
	v_mov_b32_e32 v16, v26
	v_mov_b32_e32 v17, v18
	v_pk_mul_f32 v[16:17], v[104:105], v[16:17]
	s_nop 0
	v_cvt_pk_bf16_f32 v162, v99, v22
	s_nop 0
	v_cvt_pk_bf16_f32 v166, v98, v66
	v_mov_b32_e32 v25, v88
	v_sub_f32_e32 v23, v17, v16
	v_mov_b32_e32 v16, v18
	v_mov_b32_e32 v17, v26
	v_pk_mul_f32 v[16:17], v[104:105], v[16:17]
	v_mov_b32_e32 v18, v27
	v_add_f32_e32 v24, v16, v17
	v_pk_mul_f32 v[16:17], v[110:111], v[18:19]
	v_mov_b32_e32 v26, v19
	v_sub_f32_e32 v18, v17, v16
	v_pk_mul_f32 v[16:17], v[110:111], v[26:27]
	s_nop 0
	v_cvt_pk_bf16_f32 v167, v23, v18
	v_mov_b32_e32 v18, v74
	v_add_f32_e32 v16, v16, v17
	s_nop 0
	v_cvt_pk_bf16_f32 v163, v24, v16
	v_pk_mul_f32 v[16:17], v[20:21], v[56:57] op_sel_hi:[0,1]
	v_mov_b32_e32 v19, v86
	v_pk_mul_f32 v[22:23], v[20:21], v[52:53] op_sel_hi:[0,1]
	v_mov_b32_e32 v24, v76
	v_pk_mul_f32 v[16:17], v[16:17], v[18:19]
	v_pk_mul_f32 v[18:19], v[20:21], v[54:55] op_sel_hi:[0,1]
	v_pk_mul_f32 v[22:23], v[22:23], v[24:25]
	v_pk_mul_f32 v[24:25], v[20:21], v[50:51] op_sel_hi:[0,1]
	v_pk_mul_f32 v[26:27], v[20:21], v[48:49] op_sel_hi:[0,1]
	v_mov_b32_e32 v48, v70
	v_mov_b32_e32 v49, v82
	v_pk_mul_f32 v[20:21], v[20:21], v[42:43] op_sel_hi:[0,1]
	v_mov_b32_e32 v42, v58
	v_mov_b32_e32 v43, v90
	v_pk_mul_f32 v[26:27], v[26:27], v[48:49]
	v_mov_b32_e32 v48, v72
	v_mov_b32_e32 v49, v84
	v_pk_mul_f32 v[42:43], v[16:17], v[42:43]
	v_mov_b32_e32 v86, v75
	v_pk_mul_f32 v[44:45], v[44:45], v[48:49]
	v_sub_f32_e32 v48, v43, v42
	v_mov_b32_e32 v42, v90
	v_mov_b32_e32 v43, v58
	v_pk_mul_f32 v[18:19], v[18:19], v[86:87]
	v_pk_mul_f32 v[16:17], v[16:17], v[42:43]
	v_mov_b32_e32 v90, v59
	v_add_f32_e32 v42, v16, v17
	v_pk_mul_f32 v[16:17], v[18:19], v[90:91]
	v_mov_b32_e32 v58, v91
	v_sub_f32_e32 v43, v17, v16
	v_pk_mul_f32 v[16:17], v[18:19], v[58:59]
; __device__ __forceinline__ int v_rd_base(int lane) { return ((lane & 3) << 3) | (((lane >> 2) & 3) << 6) | (((lane >> 4) & 1) << 5) | (((lane >> 5) & 1) << 8); }
; __device__ __forceinline__ void qkt(f32x16& p0, f32x16& p1, const char* Ks, const bf16x8* qr, int r32, int hi, float negM) {
; #pragma unroll
;   for (int r = 0; r < 16; ++r) { p0[r] = negM; p1[r] = negM; }
;   __builtin_amdgcn_s_setprio(1);
;   const char* kn = Ks + r32 * 256; const int xn = r32 & 15;
; #pragma unroll
;   for (int d0 = 0; d0 < 8; ++d0) { const int off = ((d0 * 2 + hi) ^ xn) << 4;
;     bf16x8 b0 = *reinterpret_cast<const bf16x8*>(kn + off);
;     bf16x8 b1 = *reinterpret_cast<const bf16x8*>(kn + 32 * 256 + off);
;     p0 = __builtin_amdgcn_mfma_f32_32x32x16_bf16(b0, qr[d0], p0, 0, 0, 0);
;     p1 = __builtin_amdgcn_mfma_f32_32x32x16_bf16(b1, qr[d0], p1, 0, 0, 0); }
;   const char* kr = Ks + KROPE_OFF + r32 * 128; const int xr = (r32 >> 1) & 7;
; #pragma unroll
;   for (int d0 = 8; d0 < 12; ++d0) { const int off = (((d0 - 8) * 2 + hi) ^ xr) << 4;
;     bf16x8 b0 = *reinterpret_cast<const bf16x8*>(kr + off);
;     bf16x8 b1 = *reinterpret_cast<const bf16x8*>(kr + 32 * 128 + off);
;     p0 = __builtin_amdgcn_mfma_f32_32x32x16_bf16(b0, qr[d0], p0, 0, 0, 0);
;     p1 = __builtin_amdgcn_mfma_f32_32x32x16_bf16(b1, qr[d0], p1, 0, 0, 0); }
; __device__ __forceinline__ void attn_body(const u16* __restrict__ Qb, const u16* __restrict__ Kn, const u16* __restrict__ Kr,
;                                           u16* __restrict__ Ob, char* lds, int tid, const float* __restrict__ gq_, const float* __restrict__ tab_, int qpos0, float negM) {
;     ...
;       for (int e = 0; e < 8; ++e) { y1[e] = x1[e] * c_[e] - x2[e] * s_[e]; y2[e] = x2[e] * c_[e] + x1[e] * s_[e]; }
;       const u32x4 o1 = {cvtpk(y1[0], y1[1]), cvtpk(y1[2], y1[3]), cvtpk(y1[4], y1[5]), cvtpk(y1[6], y1[7])};
;       const u32x4 o2 = {cvtpk(y2[0], y2[1]), cvtpk(y2[2], y2[3]), cvtpk(y2[4], y2[5]), cvtpk(y2[6], y2[7])};
;       qr[8 + dd] = *reinterpret_cast<const bf16x8*>(&o1); qr[10 + dd] = *reinterpret_cast<const bf16x8*>(&o2); }
;   }
;   const int vrb = (int)(uintptr_t)lds + v_rd_base(lane);
;   f32x16 pA0, pA1, pB0, pB1; bf16x8 pa0, pa1, pa2, pa3; constexpr int NT = SEQ / KVBLK;
;   WAITV(0); TBAR();
;   AISSUE(KVBLK, STG);
;   qkt(pA0, pA1, lds + KOFF, qr, r32, hi, negM); partialSM(pA0);
	v_mov_b32_e32 v88, v77
	v_add_f32_e32 v18, v16, v17
	v_mov_b32_e32 v16, v60
	v_mov_b32_e32 v17, v92
	v_pk_mul_f32 v[16:17], v[22:23], v[16:17]
	v_pk_mul_f32 v[24:25], v[24:25], v[88:89]
	v_sub_f32_e32 v19, v17, v16
	v_mov_b32_e32 v16, v92
	v_mov_b32_e32 v17, v60
	v_pk_mul_f32 v[16:17], v[22:23], v[16:17]
	v_mov_b32_e32 v92, v61
	v_add_f32_e32 v22, v16, v17
	v_pk_mul_f32 v[16:17], v[24:25], v[92:93]
	v_mov_b32_e32 v60, v93
	v_sub_f32_e32 v23, v17, v16
	v_pk_mul_f32 v[16:17], v[24:25], v[60:61]
	v_mov_b32_e32 v82, v71
	v_add_f32_e32 v24, v16, v17
	v_mov_b32_e32 v16, v28
	v_mov_b32_e32 v17, v62
	v_pk_mul_f32 v[16:17], v[26:27], v[16:17]
	v_pk_mul_f32 v[46:47], v[46:47], v[82:83]
	v_sub_f32_e32 v25, v17, v16
	v_mov_b32_e32 v16, v62
	v_mov_b32_e32 v17, v28
	v_pk_mul_f32 v[16:17], v[26:27], v[16:17]
	v_mov_b32_e32 v62, v29
	v_add_f32_e32 v26, v16, v17
	v_pk_mul_f32 v[16:17], v[46:47], v[62:63]
	v_mov_b32_e32 v28, v63
	v_sub_f32_e32 v27, v17, v16
	v_pk_mul_f32 v[16:17], v[46:47], v[28:29]
	v_mov_b32_e32 v84, v73
	v_add_f32_e32 v28, v16, v17
	v_mov_b32_e32 v16, v30
	v_mov_b32_e32 v17, v64
	v_pk_mul_f32 v[16:17], v[44:45], v[16:17]
	v_pk_mul_f32 v[20:21], v[20:21], v[84:85]
	v_sub_f32_e32 v29, v17, v16
	v_mov_b32_e32 v16, v64
	v_mov_b32_e32 v17, v30
	v_pk_mul_f32 v[16:17], v[44:45], v[16:17]
	v_mov_b32_e32 v64, v31
	v_add_f32_e32 v44, v16, v17
	v_pk_mul_f32 v[16:17], v[20:21], v[64:65]
	v_mov_b32_e32 v30, v65
	v_sub_f32_e32 v45, v17, v16
	v_pk_mul_f32 v[16:17], v[20:21], v[30:31]
	s_nop 0
	v_cvt_pk_bf16_f32 v168, v42, v18
	v_lshlrev_b32_e32 v18, 1, v96
	v_add_f32_e32 v16, v16, v17
	v_lshlrev_b32_e32 v17, 4, v96
	s_nop 0
	v_cvt_pk_bf16_f32 v171, v44, v16
	v_lshlrev_b32_e32 v16, 3, v209
	v_and_b32_e32 v17, 0xc0, v17
	v_and_or_b32 v17, v16, 24, v17
	v_and_b32_e32 v18, 32, v18
	v_and_b32_e32 v16, 0x100, v16
	v_or3_b32 v212, v17, v18, v16
	s_nop 0
	v_cvt_pk_bf16_f32 v172, v48, v43
	s_nop 0
	v_cvt_pk_bf16_f32 v173, v19, v23
	s_nop 0
	v_cvt_pk_bf16_f32 v174, v25, v27
	s_nop 0
	v_cvt_pk_bf16_f32 v175, v29, v45
	s_nop 0
	v_cvt_pk_bf16_f32 v169, v22, v24
	s_nop 0
	v_cvt_pk_bf16_f32 v170, v26, v28
	v_add_u32_e32 v16, 0xe000, v211
	s_add_u32 s48, s48, 0x40000
	v_readfirstlane_b32 s51, v16
	v_add_u32_e32 v16, 0x10000, v211
	s_addc_u32 s49, s49, 0
	s_mov_b32 m0, s51
	v_readfirstlane_b32 s51, v16
	v_add_u32_e32 v19, 0x12000, v211
	global_load_lds_dwordx4 v176, s[48:49]
	s_mov_b32 m0, s51
	v_readfirstlane_b32 s51, v19
	v_add_u32_e32 v18, 0xa000, v211
	global_load_lds_dwordx4 v32, s[48:49]
	v_lshl_add_u64 v[16:17], v[40:41], 0, s[14:15]
	s_mov_b32 m0, s51
	v_readfirstlane_b32 s51, v18
	global_load_lds_dwordx4 v[16:17], off
	v_add_u32_e32 v16, 0xc000, v211
	s_mov_b32 m0, s51
	v_readfirstlane_b32 s51, v16
	global_load_lds_dwordx4 v80, s[48:49]
	s_mov_b32 m0, s51
	s_nop 0
	global_load_lds_dwordx4 v81, s[48:49]
	s_setprio 1
	v_bitop3_b32 v16, v207, v96, 15 bitop3:0x78
	v_lshlrev_b32_e32 v213, 8, v206
	v_lshlrev_b32_e32 v214, 4, v16
	v_or_b32_e32 v16, v213, v214
	ds_read_b128 v[40:43], v16 offset:16384
	ds_read_b128 v[44:47], v16 offset:24576
	v_and_b32_e32 v48, 15, v96
	v_lshlrev_b32_e32 v222, 7, v206
	s_waitcnt lgkmcnt(0)
	v_mfma_f32_32x32x16_bf16 v[16:31], v[40:43], v[128:131], v[0:15]
	v_bitop3_b32 v40, v207, v48, 2 bitop3:0x36
	v_lshlrev_b32_e32 v215, 4, v40
	v_mfma_f32_32x32x16_bf16 v[80:95], v[44:47], v[128:131], v[0:15]
	v_or_b32_e32 v44, v213, v215
	ds_read_b128 v[40:43], v44 offset:16384
	ds_read_b128 v[44:47], v44 offset:24576
	s_waitcnt lgkmcnt(0)
	v_mfma_f32_32x32x16_bf16 v[16:31], v[40:43], v[132:135], v[16:31]
	v_bitop3_b32 v40, v207, v48, 4 bitop3:0x36
	v_lshlrev_b32_e32 v216, 4, v40
	v_mfma_f32_32x32x16_bf16 v[80:95], v[44:47], v[132:135], v[80:95]
	v_or_b32_e32 v44, v213, v216
	ds_read_b128 v[40:43], v44 offset:16384
	ds_read_b128 v[44:47], v44 offset:24576
	s_waitcnt lgkmcnt(0)
	v_mfma_f32_32x32x16_bf16 v[16:31], v[40:43], v[136:139], v[16:31]
	v_bitop3_b32 v40, v207, v48, 6 bitop3:0x36
	v_lshlrev_b32_e32 v217, 4, v40
	v_mfma_f32_32x32x16_bf16 v[80:95], v[44:47], v[136:139], v[80:95]
	v_or_b32_e32 v44, v213, v217
	ds_read_b128 v[40:43], v44 offset:16384
	ds_read_b128 v[44:47], v44 offset:24576
	s_waitcnt lgkmcnt(0)
	v_mfma_f32_32x32x16_bf16 v[16:31], v[40:43], v[140:143], v[16:31]
	v_bitop3_b32 v40, v207, v48, 8 bitop3:0x36
	v_lshlrev_b32_e32 v218, 4, v40
	v_mfma_f32_32x32x16_bf16 v[80:95], v[44:47], v[140:143], v[80:95]
	v_or_b32_e32 v44, v213, v218
	ds_read_b128 v[40:43], v44 offset:16384
	ds_read_b128 v[44:47], v44 offset:24576
	s_waitcnt lgkmcnt(0)
	v_mfma_f32_32x32x16_bf16 v[16:31], v[40:43], v[144:147], v[16:31]
	v_bitop3_b32 v40, v207, v48, 10 bitop3:0x36
	v_lshlrev_b32_e32 v219, 4, v40
	v_mfma_f32_32x32x16_bf16 v[80:95], v[44:47], v[144:147], v[80:95]
	v_or_b32_e32 v44, v213, v219
	ds_read_b128 v[40:43], v44 offset:16384
	ds_read_b128 v[44:47], v44 offset:24576
	s_waitcnt lgkmcnt(0)
	v_mfma_f32_32x32x16_bf16 v[16:31], v[40:43], v[148:151], v[16:31]
	v_bitop3_b32 v40, v207, v48, 12 bitop3:0x36
	v_lshlrev_b32_e32 v220, 4, v40
	v_mfma_f32_32x32x16_bf16 v[80:95], v[44:47], v[148:151], v[80:95]
	v_or_b32_e32 v44, v213, v220
	ds_read_b128 v[40:43], v44 offset:16384
	ds_read_b128 v[44:47], v44 offset:24576
	s_waitcnt lgkmcnt(0)
	v_mfma_f32_32x32x16_bf16 v[16:31], v[40:43], v[152:155], v[16:31]
	v_bitop3_b32 v40, v207, v48, 14 bitop3:0x36
	v_lshlrev_b32_e32 v221, 4, v40
	v_bfe_u32 v48, v96, 1, 3
	v_mfma_f32_32x32x16_bf16 v[80:95], v[44:47], v[152:155], v[80:95]
	v_or_b32_e32 v44, v213, v221
	ds_read_b128 v[40:43], v44 offset:16384
	ds_read_b128 v[44:47], v44 offset:24576
	s_waitcnt lgkmcnt(0)
; __device__ __forceinline__ void qkt(f32x16& p0, f32x16& p1, const char* Ks, const bf16x8* qr, int r32, int hi, float negM) {
; #pragma unroll
;   for (int r = 0; r < 16; ++r) { p0[r] = negM; p1[r] = negM; }
;   __builtin_amdgcn_s_setprio(1);
;   const char* kn = Ks + r32 * 256; const int xn = r32 & 15;
; #pragma unroll
;   for (int d0 = 0; d0 < 8; ++d0) { const int off = ((d0 * 2 + hi) ^ xn) << 4;
;     bf16x8 b0 = *reinterpret_cast<const bf16x8*>(kn + off);
;     bf16x8 b1 = *reinterpret_cast<const bf16x8*>(kn + 32 * 256 + off);
;     p0 = __builtin_amdgcn_mfma_f32_32x32x16_bf16(b0, qr[d0], p0, 0, 0, 0);
;     p1 = __builtin_amdgcn_mfma_f32_32x32x16_bf16(b1, qr[d0], p1, 0, 0, 0); }
;   const char* kr = Ks + KROPE_OFF + r32 * 128; const int xr = (r32 >> 1) & 7;
; #pragma unroll
;   for (int d0 = 8; d0 < 12; ++d0) { const int off = (((d0 - 8) * 2 + hi) ^ xr) << 4;
;     bf16x8 b0 = *reinterpret_cast<const bf16x8*>(kr + off);
;     bf16x8 b1 = *reinterpret_cast<const bf16x8*>(kr + 32 * 128 + off);
;     p0 = __builtin_amdgcn_mfma_f32_32x32x16_bf16(b0, qr[d0], p0, 0, 0, 0);
;     p1 = __builtin_amdgcn_mfma_f32_32x32x16_bf16(b1, qr[d0], p1, 0, 0, 0); }
;   __builtin_amdgcn_s_setprio(0);
; }
; __device__ __forceinline__ void attn_body(const u16* __restrict__ Qb, const u16* __restrict__ Kn, const u16* __restrict__ Kr,
;                                           u16* __restrict__ Ob, char* lds, int tid, const float* __restrict__ gq_, const float* __restrict__ tab_, int qpos0, float negM) {
;     ...
;   const int vrb = (int)(uintptr_t)lds + v_rd_base(lane);
;   f32x16 pA0, pA1, pB0, pB1; bf16x8 pa0, pa1, pa2, pa3; constexpr int NT = SEQ / KVBLK;
;   WAITV(0); TBAR();
;   AISSUE(KVBLK, STG);
;   qkt(pA0, pA1, lds + KOFF, qr, r32, hi, negM); partialSM(pA0);
;   int prv = 0, cur = STG, nxt = 2 * STG;
;   for (int j = 1; j + 1 < NT; j += 2) {
;     WAITV(0); asm volatile("s_waitcnt lgkmcnt(0)" ::: "memory"); TBAR();
;     AISSUE((j + 1) * KVBLK, nxt);
;     qkt(pB0, pB1, lds + cur + KOFF, qr, r32, hi, negM);
;     finishSM(pA0, pA1, l_reg, pa0, pa1, pa2, pa3); SBAR();
;     pv_d0(o, vrb + prv, pa0, pa1, pa2, pa3); partialSM(pB0);
;     { const int t_ = prv; prv = cur; cur = nxt; nxt = t_; }
;     WAITV(0); asm volatile("s_waitcnt lgkmcnt(0)" ::: "memory"); TBAR();
;     if (j + 2 < NT) AISSUE((j + 2) * KVBLK, nxt);
;     qkt(pA0, pA1, lds + cur + KOFF, qr, r32, hi, negM);
	v_mfma_f32_32x32x16_bf16 v[16:31], v[40:43], v[156:159], v[16:31]
	v_lshrrev_b32_e32 v40, 1, v96
	v_bitop3_b32 v40, v207, v40, 7 bitop3:0x78
	v_lshlrev_b32_e32 v223, 4, v40
	v_mfma_f32_32x32x16_bf16 v[80:95], v[44:47], v[156:159], v[80:95]
	v_or_b32_e32 v44, v222, v223
	ds_read_b128 v[40:43], v44 offset:32768
	ds_read_b128 v[44:47], v44 offset:36864
	s_waitcnt lgkmcnt(0)
	v_mfma_f32_32x32x16_bf16 v[16:31], v[40:43], v[164:167], v[16:31]
	v_bitop3_b32 v40, v207, v48, 2 bitop3:0x36
	v_lshlrev_b32_e32 v224, 4, v40
	v_mfma_f32_32x32x16_bf16 v[80:95], v[44:47], v[164:167], v[80:95]
	v_or_b32_e32 v44, v222, v224
	ds_read_b128 v[40:43], v44 offset:32768
	ds_read_b128 v[44:47], v44 offset:36864
	s_waitcnt lgkmcnt(0)
	v_mfma_f32_32x32x16_bf16 v[16:31], v[40:43], v[172:175], v[16:31]
	v_bitop3_b32 v40, v207, v48, 4 bitop3:0x36
	v_lshlrev_b32_e32 v225, 4, v40
	v_mfma_f32_32x32x16_bf16 v[80:95], v[44:47], v[172:175], v[80:95]
	v_or_b32_e32 v44, v222, v225
	ds_read_b128 v[40:43], v44 offset:32768
	ds_read_b128 v[44:47], v44 offset:36864
	s_waitcnt lgkmcnt(0)
	v_mfma_f32_32x32x16_bf16 v[16:31], v[40:43], v[160:163], v[16:31]
	v_bitop3_b32 v40, v207, v48, 6 bitop3:0x36
	v_lshlrev_b32_e32 v226, 4, v40
	v_mfma_f32_32x32x16_bf16 v[80:95], v[44:47], v[160:163], v[80:95]
	v_or_b32_e32 v44, v222, v226
	ds_read_b128 v[40:43], v44 offset:32768
	ds_read_b128 v[44:47], v44 offset:36864
	s_waitcnt lgkmcnt(0)
	v_mfma_f32_32x32x16_bf16 v[16:31], v[40:43], v[168:171], v[16:31]
	v_mfma_f32_32x32x16_bf16 v[80:95], v[44:47], v[168:171], v[80:95]
	s_setprio 0
	s_nop 9
	v_exp_f32_e32 v240, v16
	v_exp_f32_e32 v242, v17
	v_exp_f32_e32 v238, v18
	v_exp_f32_e32 v241, v19
	v_exp_f32_e32 v236, v20
	v_exp_f32_e32 v239, v21
	v_exp_f32_e32 v235, v22
	v_exp_f32_e32 v237, v23
	v_exp_f32_e32 v232, v24
	v_exp_f32_e32 v234, v25
	v_exp_f32_e32 v230, v26
	v_exp_f32_e32 v233, v27
	v_exp_f32_e32 v228, v28
	v_exp_f32_e32 v231, v29
	v_exp_f32_e32 v227, v30
	v_exp_f32_e32 v229, v31
	s_or_b32 s48, s63, s80
	s_mov_b32 s49, s64
	v_lshl_add_u64 v[178:179], s[48:49], 0, v[34:35]
	s_or_b32 s48, s59, s79
	s_mov_b32 s49, s60
	v_lshl_add_u64 v[180:181], s[48:49], 0, v[38:39]
	v_lshl_add_u64 v[182:183], s[48:49], 0, v[36:37]
	v_lshl_add_u64 v[184:185], s[48:49], 0, v[176:177]
	v_lshl_add_u64 v[186:187], s[48:49], 0, v[32:33]
	s_mov_b32 s54, 0x14000
	s_mov_b32 s48, -1
	s_mov_b32 s49, 0xa000
	v_mov_b32_e32 v176, 0
	v_mov_b32_e32 v16, 0
	v_mov_b32_e32 v17, v177
	v_mov_b32_e32 v18, v177
	v_mov_b32_e32 v19, v177
	v_mov_b32_e32 v20, v177
	v_mov_b32_e32 v21, v177
	v_mov_b32_e32 v22, v177
	v_mov_b32_e32 v23, v177
	v_mov_b32_e32 v24, v177
	v_mov_b32_e32 v25, v177
	v_mov_b32_e32 v26, v177
	v_mov_b32_e32 v27, v177
	v_mov_b32_e32 v28, v177
	v_mov_b32_e32 v29, v177
	v_mov_b32_e32 v30, v177
	v_mov_b32_e32 v31, v177
	v_mov_b32_e32 v32, 0
	v_mov_b32_e32 v34, v177
	v_mov_b32_e32 v36, v177
	v_mov_b32_e32 v38, v177
	v_mov_b32_e32 v40, v177
	v_mov_b32_e32 v41, v177
	v_mov_b32_e32 v42, v177
	v_mov_b32_e32 v43, v177
	v_mov_b32_e32 v44, v177
	v_mov_b32_e32 v45, v177
	v_mov_b32_e32 v46, v177
	v_mov_b32_e32 v47, v177
	v_mov_b32_e32 v48, 0
	v_mov_b32_e32 v49, v177
	v_mov_b32_e32 v50, v177
	v_mov_b32_e32 v51, v177
	v_mov_b32_e32 v52, v177
	v_mov_b32_e32 v53, v177
	v_mov_b32_e32 v54, v177
	v_mov_b32_e32 v55, v177
	v_mov_b32_e32 v56, v177
	v_mov_b32_e32 v57, v177
	v_mov_b32_e32 v58, v177
	v_mov_b32_e32 v59, v177
	v_mov_b32_e32 v60, v177
	v_mov_b32_e32 v61, v177
	v_mov_b32_e32 v62, v177
	v_mov_b32_e32 v63, v177
	v_mov_b32_e32 v64, 0
	v_mov_b32_e32 v65, v177
	v_mov_b32_e32 v66, v177
	v_mov_b32_e32 v67, v177
	v_mov_b32_e32 v68, v177
	v_mov_b32_e32 v69, v177
	v_mov_b32_e32 v70, v177
	v_mov_b32_e32 v71, v177
	v_mov_b32_e32 v72, v177
	v_mov_b32_e32 v73, v177
	v_mov_b32_e32 v74, v177
	v_mov_b32_e32 v75, v177
	v_mov_b32_e32 v76, v177
	v_mov_b32_e32 v77, v177
	v_mov_b32_e32 v78, v177
	v_mov_b32_e32 v79, v177
.LBB0_719:
	s_waitcnt vmcnt(0)
	s_waitcnt lgkmcnt(0)
	s_mov_b32 s51, s54
	s_barrier
	s_setprio 1
	v_add_u32_e32 v243, s49, v213
	v_add_u32_e32 v100, v243, v214
	ds_read_b128 v[96:99], v100 offset:16384
	ds_read_b128 v[244:247], v100 offset:24576
	v_add_u32_e32 v248, v243, v215
	s_add_u32 s54, s51, s87
	v_lshl_add_u64 v[188:189], s[26:27], 0, v[184:185]
	v_lshl_add_u64 v[190:191], s[26:27], 0, v[186:187]
	v_lshl_add_u64 v[192:193], s[26:27], 0, v[178:179]
	v_lshl_add_u64 v[194:195], s[26:27], 0, v[182:183]
	v_lshl_add_u64 v[196:197], s[26:27], 0, v[180:181]
	v_exp_f32_e32 v80, v80
	v_add_f32_e32 v252, 0, v240
	v_add_f32_e32 v252, v242, v252
	s_waitcnt lgkmcnt(0)
	v_mfma_f32_32x32x16_bf16 v[112:127], v[96:99], v[128:131], v[0:15]
	v_exp_f32_e32 v81, v81
	v_add_f32_e32 v252, v238, v252
	v_add_f32_e32 v252, v241, v252
	v_mfma_f32_32x32x16_bf16 v[96:111], v[244:247], v[128:131], v[0:15]
	ds_read_b128 v[244:247], v248 offset:16384
	ds_read_b128 v[248:251], v248 offset:24576
	s_add_u32 m0, s54, 0x4000
	v_lshl_add_u64 v[254:255], v[188:189], 0, s[16:17]
	global_load_lds_dwordx4 v[254:255], off
	v_exp_f32_e32 v82, v82
	v_add_f32_e32 v252, v236, v252
	v_add_f32_e32 v252, v239, v252
	s_waitcnt lgkmcnt(0)
	v_mfma_f32_32x32x16_bf16 v[112:127], v[244:247], v[132:135], v[112:127]
	v_exp_f32_e32 v83, v83
	v_add_f32_e32 v252, v235, v252
	v_add_f32_e32 v252, v237, v252
	v_mfma_f32_32x32x16_bf16 v[96:111], v[248:251], v[132:135], v[96:111]
	v_add_u32_e32 v248, v243, v216
	ds_read_b128 v[244:247], v248 offset:16384
	ds_read_b128 v[248:251], v248 offset:24576
	s_add_u32 m0, s54, 0x6000
	v_lshl_add_u64 v[254:255], v[190:191], 0, s[16:17]
	global_load_lds_dwordx4 v[254:255], off
	v_exp_f32_e32 v84, v84
	v_add_f32_e32 v252, v232, v252
	v_add_f32_e32 v252, v234, v252
	s_waitcnt lgkmcnt(0)
; __device__ __forceinline__ void finishSM(f32x16& p0, f32x16& p1, float& l_reg, bf16x8& pa0, bf16x8& pa1, bf16x8& pa2, bf16x8& pa3) {
; #pragma unroll
;   for (int r = 0; r < 16; ++r) p1[r] = __builtin_amdgcn_exp2f(p1[r]);
;   float ps = 0;
; #pragma unroll
;   for (int r = 0; r < 16; ++r) ps += p0[r];
; #pragma unroll
;   for (int r = 0; r < 16; ++r) ps += p1[r];
;   { auto rr = __builtin_amdgcn_permlane32_swap(__float_as_uint(ps), __float_as_uint(ps), false, false);
;     ps = __uint_as_float(rr[0]) + __uint_as_float(rr[1]); }
;   l_reg += ps;
; __device__ __forceinline__ void qkt(f32x16& p0, f32x16& p1, const char* Ks, const bf16x8* qr, int r32, int hi, float negM) {
; #pragma unroll
;   for (int r = 0; r < 16; ++r) { p0[r] = negM; p1[r] = negM; }
;   __builtin_amdgcn_s_setprio(1);
;   const char* kn = Ks + r32 * 256; const int xn = r32 & 15;
; #pragma unroll
;   for (int d0 = 0; d0 < 8; ++d0) { const int off = ((d0 * 2 + hi) ^ xn) << 4;
;     bf16x8 b0 = *reinterpret_cast<const bf16x8*>(kn + off);
;     bf16x8 b1 = *reinterpret_cast<const bf16x8*>(kn + 32 * 256 + off);
;     p0 = __builtin_amdgcn_mfma_f32_32x32x16_bf16(b0, qr[d0], p0, 0, 0, 0);
;     p1 = __builtin_amdgcn_mfma_f32_32x32x16_bf16(b1, qr[d0], p1, 0, 0, 0); }
;   const char* kr = Ks + KROPE_OFF + r32 * 128; const int xr = (r32 >> 1) & 7;
; #pragma unroll
;   for (int d0 = 8; d0 < 12; ++d0) { const int off = (((d0 - 8) * 2 + hi) ^ xr) << 4;
;     bf16x8 b0 = *reinterpret_cast<const bf16x8*>(kr + off);
;     bf16x8 b1 = *reinterpret_cast<const bf16x8*>(kr + 32 * 128 + off);
;     p0 = __builtin_amdgcn_mfma_f32_32x32x16_bf16(b0, qr[d0], p0, 0, 0, 0);
;     p1 = __builtin_amdgcn_mfma_f32_32x32x16_bf16(b1, qr[d0], p1, 0, 0, 0); }
;   __builtin_amdgcn_s_setprio(0);
; }
; __device__ __forceinline__ void attn_body(const u16* __restrict__ Qb, const u16* __restrict__ Kn, const u16* __restrict__ Kr,
;                                           u16* __restrict__ Ob, char* lds, int tid, const float* __restrict__ gq_, const float* __restrict__ tab_, int qpos0, float negM) {
;     ...
;   for (int j = 1; j + 1 < NT; j += 2) {
;     WAITV(0); asm volatile("s_waitcnt lgkmcnt(0)" ::: "memory"); TBAR();
;     AISSUE((j + 1) * KVBLK, nxt);
;     qkt(pB0, pB1, lds + cur + KOFF, qr, r32, hi, negM);
;     finishSM(pA0, pA1, l_reg, pa0, pa1, pa2, pa3); SBAR();
;     pv_d0(o, vrb + prv, pa0, pa1, pa2, pa3); partialSM(pB0);
	v_mfma_f32_32x32x16_bf16 v[112:127], v[244:247], v[136:139], v[112:127]
	v_exp_f32_e32 v85, v85
	v_add_f32_e32 v252, v230, v252
	v_add_f32_e32 v252, v233, v252
	v_mfma_f32_32x32x16_bf16 v[96:111], v[248:251], v[136:139], v[96:111]
	v_add_u32_e32 v248, v243, v217
	ds_read_b128 v[244:247], v248 offset:16384
	ds_read_b128 v[248:251], v248 offset:24576
	s_add_u32 m0, s54, 0x8000
	v_lshl_add_u64 v[254:255], v[192:193], 0, s[18:19]
	global_load_lds_dwordx4 v[254:255], off
	v_exp_f32_e32 v86, v86
	v_add_f32_e32 v252, v228, v252
	v_add_f32_e32 v252, v231, v252
	s_waitcnt lgkmcnt(0)
	v_mfma_f32_32x32x16_bf16 v[112:127], v[244:247], v[140:143], v[112:127]
	v_exp_f32_e32 v87, v87
	v_add_f32_e32 v252, v227, v252
	v_add_f32_e32 v252, v229, v252
	v_mfma_f32_32x32x16_bf16 v[96:111], v[248:251], v[140:143], v[96:111]
	v_add_u32_e32 v248, v243, v218
	ds_read_b128 v[244:247], v248 offset:16384
	ds_read_b128 v[248:251], v248 offset:24576
	s_mov_b32 m0, s54
	v_lshl_add_u64 v[254:255], v[194:195], 0, s[20:21]
	global_load_lds_dwordx4 v[254:255], off
	v_exp_f32_e32 v88, v88
	v_add_f32_e32 v252, v80, v252
	v_exp_f32_e32 v89, v89
	s_waitcnt lgkmcnt(0)
	v_mfma_f32_32x32x16_bf16 v[112:127], v[244:247], v[144:147], v[112:127]
	v_add_f32_e32 v252, v81, v252
	v_exp_f32_e32 v90, v90
	v_add_f32_e32 v252, v82, v252
	v_mfma_f32_32x32x16_bf16 v[96:111], v[248:251], v[144:147], v[96:111]
	v_add_u32_e32 v248, v243, v219
	ds_read_b128 v[244:247], v248 offset:16384
	ds_read_b128 v[248:251], v248 offset:24576
	s_add_u32 m0, s54, 0x2000
	v_lshl_add_u64 v[254:255], v[196:197], 0, s[20:21]
	global_load_lds_dwordx4 v[254:255], off
	v_exp_f32_e32 v91, v91
	v_add_f32_e32 v252, v83, v252
	v_exp_f32_e32 v92, v92
	s_waitcnt lgkmcnt(0)
	v_mfma_f32_32x32x16_bf16 v[112:127], v[244:247], v[148:151], v[112:127]
	v_add_f32_e32 v252, v84, v252
	v_exp_f32_e32 v93, v93
	v_add_f32_e32 v252, v85, v252
	v_mfma_f32_32x32x16_bf16 v[96:111], v[248:251], v[148:151], v[96:111]
	v_add_u32_e32 v248, v243, v220
	ds_read_b128 v[244:247], v248 offset:16384
	ds_read_b128 v[248:251], v248 offset:24576
	v_add_u32_e32 v243, v243, v221
	v_exp_f32_e32 v94, v94
	v_add_f32_e32 v252, v86, v252
	v_exp_f32_e32 v95, v95
	s_waitcnt lgkmcnt(0)
	v_mfma_f32_32x32x16_bf16 v[112:127], v[244:247], v[152:155], v[112:127]
	v_add_f32_e32 v252, v87, v252
	v_add_f32_e32 v252, v88, v252
	v_add_f32_e32 v252, v89, v252
	v_mfma_f32_32x32x16_bf16 v[96:111], v[248:251], v[152:155], v[96:111]
	ds_read_b128 v[244:247], v243 offset:16384
	ds_read_b128 v[248:251], v243 offset:24576
	v_add_u32_e32 v243, s49, v222
	v_add_f32_e32 v252, v90, v252
	v_add_f32_e32 v252, v91, v252
	v_add_f32_e32 v252, v92, v252
	s_waitcnt lgkmcnt(0)
	v_mfma_f32_32x32x16_bf16 v[112:127], v[244:247], v[156:159], v[112:127]
	v_add_f32_e32 v252, v93, v252
	v_add_f32_e32 v252, v94, v252
	v_add_f32_e32 v252, v95, v252
	v_mfma_f32_32x32x16_bf16 v[96:111], v[248:251], v[156:159], v[96:111]
	v_add_u32_e32 v248, v243, v223
	ds_read_b128 v[244:247], v248 offset:32768
	ds_read_b128 v[248:251], v248 offset:36864
	v_mov_b32_e32 v253, v252
	v_cvt_pk_bf16_f32 v95, v94, v95
	v_cvt_pk_bf16_f32 v94, v92, v93
	s_waitcnt lgkmcnt(0)
	v_mfma_f32_32x32x16_bf16 v[112:127], v[244:247], v[164:167], v[112:127]
	v_permlane32_swap_b32_e32 v252, v253
	v_cvt_pk_bf16_f32 v93, v90, v91
	v_cvt_pk_bf16_f32 v92, v88, v89
	v_mfma_f32_32x32x16_bf16 v[96:111], v[248:251], v[164:167], v[96:111]
	v_add_u32_e32 v248, v243, v224
	ds_read_b128 v[244:247], v248 offset:32768
	ds_read_b128 v[248:251], v248 offset:36864
	v_add_f32_e32 v252, v252, v253
	v_cvt_pk_bf16_f32 v91, v86, v87
	v_add_f32_e32 v176, v176, v252
	s_waitcnt lgkmcnt(0)
	v_mfma_f32_32x32x16_bf16 v[112:127], v[244:247], v[172:175], v[112:127]
	v_cvt_pk_bf16_f32 v90, v84, v85
	v_cvt_pk_bf16_f32 v89, v82, v83
	v_cvt_pk_bf16_f32 v88, v80, v81
	v_mfma_f32_32x32x16_bf16 v[96:111], v[248:251], v[172:175], v[96:111]
	v_add_u32_e32 v248, v243, v225
	ds_read_b128 v[244:247], v248 offset:32768
	ds_read_b128 v[248:251], v248 offset:36864
	v_add_u32_e32 v243, v243, v226
	v_cvt_pk_bf16_f32 v80, v240, v242
	v_cvt_pk_bf16_f32 v81, v238, v241
	v_cvt_pk_bf16_f32 v82, v236, v239
	s_waitcnt lgkmcnt(0)
	v_mfma_f32_32x32x16_bf16 v[112:127], v[244:247], v[160:163], v[112:127]
	v_cvt_pk_bf16_f32 v83, v235, v237
	v_cvt_pk_bf16_f32 v84, v232, v234
	v_cvt_pk_bf16_f32 v85, v230, v233
	v_mfma_f32_32x32x16_bf16 v[96:111], v[248:251], v[160:163], v[96:111]
	ds_read_b128 v[244:247], v243 offset:32768
	ds_read_b128 v[248:251], v243 offset:36864
	v_cvt_pk_bf16_f32 v86, v228, v231
	v_cvt_pk_bf16_f32 v87, v227, v229
	v_permlane32_swap_b32_e32 v88, v90
	s_waitcnt lgkmcnt(0)
	v_mfma_f32_32x32x16_bf16 v[112:127], v[244:247], v[168:171], v[112:127]
	v_permlane32_swap_b32_e32 v89, v91
	v_permlane32_swap_b32_e32 v92, v94
	v_permlane32_swap_b32_e32 v93, v95
	v_mfma_f32_32x32x16_bf16 v[96:111], v[248:251], v[168:171], v[96:111]
	s_setprio 0
	v_permlane32_swap_b32_e32 v80, v82
	v_permlane32_swap_b32_e32 v81, v83
	v_permlane32_swap_b32_e32 v84, v86
	v_permlane32_swap_b32_e32 v85, v87
	v_add_u32_e32 v198, s50, v212
	ds_read_b64_tr_b16 v[228:229], v198 offset:0
	ds_read_b64_tr_b16 v[230:231], v198 offset:0x800
	ds_read_b64_tr_b16 v[232:233], v198 offset:0x1000
	ds_read_b64_tr_b16 v[234:235], v198 offset:0x1800
	ds_read_b64_tr_b16 v[236:237], v198 offset:0x2000
	ds_read_b64_tr_b16 v[238:239], v198 offset:0x2800
	ds_read_b64_tr_b16 v[240:241], v198 offset:0x3000
	ds_read_b64_tr_b16 v[242:243], v198 offset:0x3800
	s_waitcnt lgkmcnt(0)
; #define SBAR() __builtin_amdgcn_sched_barrier(0)
; #define AISSUE(k0, soff) do { const char* kb_ = (const char*)Kn + (size_t)(k0) * 4096; const char* rb_ = (const char*)Kr + (size_t)(k0) * 1024; \
;     char* st_ = lds + (soff) + tid * 16; \
;     GLDS(kb_ + vkn0, st_ + KOFF); GLDS(kb_ + vkn1, st_ + KOFF + 8192); GLDS(rb_ + vkr, st_ + KOFF + KROPE_OFF); \
;     GLDS(kb_ + vv0, st_); GLDS(kb_ + vv1, st_ + 8192); } while (0)
; #define WAITV(n) asm volatile("s_waitcnt vmcnt(" #n ")" ::: "memory")
; template <int D0> __device__ __forceinline__ void pv_one(f32x16& od, int vb, bf16x8 pa0, bf16x8 pa1, bf16x8 pa2, bf16x8 pa3) {
;   const s16x4 l0 = tr_read<v_rd_off(D0, 0, 0)>(vb), h0 = tr_read<v_rd_off(D0, 0, 1)>(vb), l1 = tr_read<v_rd_off(D0, 1, 0)>(vb), h1 = tr_read<v_rd_off(D0, 1, 1)>(vb);
;   const s16x4 l2 = tr_read<v_rd_off(D0, 2, 0)>(vb), h2 = tr_read<v_rd_off(D0, 2, 1)>(vb), l3 = tr_read<v_rd_off(D0, 3, 0)>(vb), h3 = tr_read<v_rd_off(D0, 3, 1)>(vb);
;   asm volatile("s_waitcnt lgkmcnt(0)" ::: "memory"); SBAR();
;     ...
;   od = __builtin_amdgcn_mfma_f32_32x32x16_bf16(pa0, PK(l0, h0), od, 0, 0, 0);
;   od = __builtin_amdgcn_mfma_f32_32x32x16_bf16(pa1, PK(l1, h1), od, 0, 0, 0);
;   od = __builtin_amdgcn_mfma_f32_32x32x16_bf16(pa2, PK(l2, h2), od, 0, 0, 0);
;   od = __builtin_amdgcn_mfma_f32_32x32x16_bf16(pa3, PK(l3, h3), od, 0, 0, 0);
;     ...
; }
; __device__ __forceinline__ void pv_d0(f32x16* o, int vb, bf16x8 pa0, bf16x8 pa1, bf16x8 pa2, bf16x8 pa3) {
;   pv_one<0>(o[0], vb, pa0, pa1, pa2, pa3); pv_one<1>(o[1], vb, pa0, pa1, pa2, pa3); pv_one<2>(o[2], vb, pa0, pa1, pa2, pa3); pv_one<3>(o[3], vb, pa0, pa1, pa2, pa3);
; __device__ __forceinline__ void attn_body(const u16* __restrict__ Qb, const u16* __restrict__ Kn, const u16* __restrict__ Kr,
;                                           u16* __restrict__ Ob, char* lds, int tid, const float* __restrict__ gq_, const float* __restrict__ tab_, int qpos0, float negM) {
;     ...
;     pv_d0(o, vrb + prv, pa0, pa1, pa2, pa3); partialSM(pB0);
;     { const int t_ = prv; prv = cur; cur = nxt; nxt = t_; }
;     WAITV(0); asm volatile("s_waitcnt lgkmcnt(0)" ::: "memory"); TBAR();
;     if (j + 2 < NT) AISSUE((j + 2) * KVBLK, nxt);
;     qkt(pA0, pA1, lds + cur + KOFF, qr, r32, hi, negM);
;     finishSM(pB0, pB1, l_reg, pa0, pa1, pa2, pa3); SBAR();
;     pv_d0(o, vrb + prv, pa0, pa1, pa2, pa3); partialSM(pA0);
	s_nop 0
	v_mfma_f32_32x32x16_bf16 v[64:79], v[80:83], v[228:231], v[64:79]
	ds_read_b64_tr_b16 v[228:229], v198 offset:0x200
	ds_read_b64_tr_b16 v[230:231], v198 offset:0xa00
	v_mfma_f32_32x32x16_bf16 v[64:79], v[84:87], v[232:235], v[64:79]
	ds_read_b64_tr_b16 v[232:233], v198 offset:0x1200
	ds_read_b64_tr_b16 v[234:235], v198 offset:0x1a00
	v_mfma_f32_32x32x16_bf16 v[64:79], v[88:91], v[236:239], v[64:79]
	ds_read_b64_tr_b16 v[236:237], v198 offset:0x2200
	ds_read_b64_tr_b16 v[238:239], v198 offset:0x2a00
	ds_read_b64_tr_b16 v[244:245], v198 offset:0x3200
	ds_read_b64_tr_b16 v[246:247], v198 offset:0x3a00
	s_waitcnt lgkmcnt(0)
	v_mfma_f32_32x32x16_bf16 v[64:79], v[92:95], v[240:243], v[64:79]
	v_mfma_f32_32x32x16_bf16 v[48:63], v[80:83], v[228:231], v[48:63]
	ds_read_b64_tr_b16 v[228:229], v198 offset:0x400
	ds_read_b64_tr_b16 v[230:231], v198 offset:0xc00
	v_mfma_f32_32x32x16_bf16 v[48:63], v[84:87], v[232:235], v[48:63]
	ds_read_b64_tr_b16 v[232:233], v198 offset:0x1400
	ds_read_b64_tr_b16 v[234:235], v198 offset:0x1c00
	v_mfma_f32_32x32x16_bf16 v[48:63], v[88:91], v[236:239], v[48:63]
	ds_read_b64_tr_b16 v[236:237], v198 offset:0x2400
	ds_read_b64_tr_b16 v[238:239], v198 offset:0x2c00
	ds_read_b64_tr_b16 v[240:241], v198 offset:0x3400
	ds_read_b64_tr_b16 v[242:243], v198 offset:0x3c00
	s_waitcnt lgkmcnt(0)
	v_mfma_f32_32x32x16_bf16 v[48:63], v[92:95], v[244:247], v[48:63]
	v_mfma_f32_32x32x16_bf16 v[32:47], v[80:83], v[228:231], v[32:47]
	ds_read_b64_tr_b16 v[228:229], v198 offset:0x600
	ds_read_b64_tr_b16 v[230:231], v198 offset:0xe00
	v_mfma_f32_32x32x16_bf16 v[32:47], v[84:87], v[232:235], v[32:47]
	ds_read_b64_tr_b16 v[232:233], v198 offset:0x1600
	ds_read_b64_tr_b16 v[234:235], v198 offset:0x1e00
	v_mfma_f32_32x32x16_bf16 v[32:47], v[88:91], v[236:239], v[32:47]
	ds_read_b64_tr_b16 v[236:237], v198 offset:0x2600
	ds_read_b64_tr_b16 v[238:239], v198 offset:0x2e00
	ds_read_b64_tr_b16 v[244:245], v198 offset:0x3600
	ds_read_b64_tr_b16 v[246:247], v198 offset:0x3e00
	s_waitcnt lgkmcnt(0)
	v_mfma_f32_32x32x16_bf16 v[32:47], v[92:95], v[240:243], v[32:47]
	v_mfma_f32_32x32x16_bf16 v[16:31], v[80:83], v[228:231], v[16:31]
	v_exp_f32_e32 v227, v114
	v_exp_f32_e32 v228, v115
	v_exp_f32_e32 v229, v116
	v_exp_f32_e32 v230, v117
	v_exp_f32_e32 v231, v118
	v_exp_f32_e32 v240, v127
	s_waitcnt vmcnt(0)
	v_mfma_f32_32x32x16_bf16 v[16:31], v[84:87], v[232:235], v[16:31]
	v_exp_f32_e32 v232, v119
	v_exp_f32_e32 v233, v120
	v_exp_f32_e32 v234, v121
	v_exp_f32_e32 v235, v122
	s_waitcnt lgkmcnt(0)
	v_exp_f32_e32 v198, v112
	v_exp_f32_e32 v199, v113
	v_mfma_f32_32x32x16_bf16 v[16:31], v[88:91], v[236:239], v[16:31]
	v_exp_f32_e32 v236, v123
	v_exp_f32_e32 v237, v124
	v_exp_f32_e32 v238, v125
	v_exp_f32_e32 v239, v126
	s_barrier
	v_mfma_f32_32x32x16_bf16 v[16:31], v[92:95], v[244:247], v[16:31]
	s_setprio 1
	v_add_u32_e32 v243, s51, v213
	v_add_u32_e32 v84, v243, v214
	ds_read_b128 v[80:83], v84 offset:16384
	ds_read_b128 v[244:247], v84 offset:24576
	v_add_u32_e32 v248, v243, v215
	s_add_u32 s54, s50, s87
	v_exp_f32_e32 v96, v96
	v_add_f32_e32 v252, 0, v198
	v_add_f32_e32 v252, v199, v252
	s_waitcnt lgkmcnt(0)
	v_mfma_f32_32x32x16_bf16 v[112:127], v[80:83], v[128:131], v[0:15]
	v_exp_f32_e32 v97, v97
	v_add_f32_e32 v252, v227, v252
	v_add_f32_e32 v252, v228, v252
	v_mfma_f32_32x32x16_bf16 v[80:95], v[244:247], v[128:131], v[0:15]
	ds_read_b128 v[244:247], v248 offset:16384
	ds_read_b128 v[248:251], v248 offset:24576
	s_add_u32 m0, s54, 0x4000
	v_lshl_add_u64 v[254:255], v[188:189], 0, s[22:23]
	global_load_lds_dwordx4 v[254:255], off
	v_exp_f32_e32 v98, v98
	v_add_f32_e32 v252, v229, v252
	v_add_f32_e32 v252, v230, v252
	s_waitcnt lgkmcnt(0)
	v_mfma_f32_32x32x16_bf16 v[80:95], v[248:251], v[132:135], v[80:95]
	v_exp_f32_e32 v99, v99
	v_add_f32_e32 v252, v231, v252
	v_add_f32_e32 v252, v232, v252
	v_add_u32_e32 v248, v243, v216
	v_mfma_f32_32x32x16_bf16 v[112:127], v[244:247], v[132:135], v[112:127]
	ds_read_b128 v[244:247], v248 offset:16384
	ds_read_b128 v[248:251], v248 offset:24576
	s_add_u32 m0, s54, 0x6000
	v_lshl_add_u64 v[254:255], v[190:191], 0, s[22:23]
	global_load_lds_dwordx4 v[254:255], off
	v_exp_f32_e32 v100, v100
	v_add_f32_e32 v252, v233, v252
	v_add_f32_e32 v252, v234, v252
	s_waitcnt lgkmcnt(0)
	v_mfma_f32_32x32x16_bf16 v[80:95], v[248:251], v[136:139], v[80:95]
	v_exp_f32_e32 v101, v101
	v_add_f32_e32 v252, v235, v252
	v_add_f32_e32 v252, v236, v252
	v_add_u32_e32 v248, v243, v217
	v_mfma_f32_32x32x16_bf16 v[112:127], v[244:247], v[136:139], v[112:127]
	ds_read_b128 v[244:247], v248 offset:16384
	ds_read_b128 v[248:251], v248 offset:24576
	s_add_u32 m0, s54, 0x8000
	v_lshl_add_u64 v[254:255], v[192:193], 0, s[40:41]
	global_load_lds_dwordx4 v[254:255], off
	v_exp_f32_e32 v102, v102
	v_add_f32_e32 v252, v237, v252
	v_add_f32_e32 v252, v238, v252
	s_waitcnt lgkmcnt(0)
	v_mfma_f32_32x32x16_bf16 v[80:95], v[248:251], v[140:143], v[80:95]
	v_exp_f32_e32 v103, v103
	v_add_f32_e32 v252, v239, v252
	v_add_f32_e32 v252, v240, v252
	v_add_u32_e32 v248, v243, v218
	v_mfma_f32_32x32x16_bf16 v[112:127], v[244:247], v[140:143], v[112:127]
	ds_read_b128 v[244:247], v248 offset:16384
	ds_read_b128 v[248:251], v248 offset:24576
	s_mov_b32 m0, s54
	v_lshl_add_u64 v[254:255], v[194:195], 0, s[42:43]
	global_load_lds_dwordx4 v[254:255], off
	v_exp_f32_e32 v104, v104
	v_add_f32_e32 v252, v96, v252
	v_exp_f32_e32 v105, v105
	s_waitcnt lgkmcnt(0)
; #define SBAR() __builtin_amdgcn_sched_barrier(0)
; __device__ __forceinline__ void finishSM(f32x16& p0, f32x16& p1, float& l_reg, bf16x8& pa0, bf16x8& pa1, bf16x8& pa2, bf16x8& pa3) {
; #pragma unroll
;   for (int r = 0; r < 16; ++r) p1[r] = __builtin_amdgcn_exp2f(p1[r]);
;   float ps = 0;
; #pragma unroll
;   for (int r = 0; r < 16; ++r) ps += p0[r];
; #pragma unroll
;   for (int r = 0; r < 16; ++r) ps += p1[r];
;   { auto rr = __builtin_amdgcn_permlane32_swap(__float_as_uint(ps), __float_as_uint(ps), false, false);
;     ps = __uint_as_float(rr[0]) + __uint_as_float(rr[1]); }
;   l_reg += ps;
;     ...
;   PK4(p0, 0, pa0); PK4(p0, 8, pa1); PK4(p1, 0, pa2); PK4(p1, 8, pa3);
; __device__ __forceinline__ void attn_body(const u16* __restrict__ Qb, const u16* __restrict__ Kn, const u16* __restrict__ Kr,
;                                           u16* __restrict__ Ob, char* lds, int tid, const float* __restrict__ gq_, const float* __restrict__ tab_, int qpos0, float negM) {
;     ...
;     qkt(pA0, pA1, lds + cur + KOFF, qr, r32, hi, negM);
;     finishSM(pB0, pB1, l_reg, pa0, pa1, pa2, pa3); SBAR();
;     pv_d0(o, vrb + prv, pa0, pa1, pa2, pa3); partialSM(pA0);
	v_mfma_f32_32x32x16_bf16 v[80:95], v[248:251], v[144:147], v[80:95]
	v_add_f32_e32 v252, v97, v252
	v_exp_f32_e32 v106, v106
	v_add_f32_e32 v252, v98, v252
	v_add_u32_e32 v248, v243, v219
	v_mfma_f32_32x32x16_bf16 v[112:127], v[244:247], v[144:147], v[112:127]
	ds_read_b128 v[244:247], v248 offset:16384
	ds_read_b128 v[248:251], v248 offset:24576
	s_add_u32 m0, s54, 0x2000
	v_lshl_add_u64 v[254:255], v[196:197], 0, s[42:43]
	global_load_lds_dwordx4 v[254:255], off
	v_exp_f32_e32 v107, v107
	v_add_f32_e32 v252, v99, v252
	v_exp_f32_e32 v108, v108
	s_waitcnt lgkmcnt(0)
	v_mfma_f32_32x32x16_bf16 v[80:95], v[248:251], v[148:151], v[80:95]
	v_add_f32_e32 v252, v100, v252
	v_exp_f32_e32 v109, v109
	v_add_f32_e32 v252, v101, v252
	v_add_u32_e32 v248, v243, v220
	v_mfma_f32_32x32x16_bf16 v[112:127], v[244:247], v[148:151], v[112:127]
	ds_read_b128 v[244:247], v248 offset:16384
	ds_read_b128 v[248:251], v248 offset:24576
	v_exp_f32_e32 v110, v110
	v_add_f32_e32 v252, v102, v252
	v_exp_f32_e32 v111, v111
	s_waitcnt lgkmcnt(0)
	v_mfma_f32_32x32x16_bf16 v[80:95], v[248:251], v[152:155], v[80:95]
	v_add_f32_e32 v252, v103, v252
	v_add_f32_e32 v252, v104, v252
	v_add_f32_e32 v252, v105, v252
	v_add_u32_e32 v248, v243, v221
	v_add_u32_e32 v243, s51, v222
	v_mfma_f32_32x32x16_bf16 v[112:127], v[244:247], v[152:155], v[112:127]
	ds_read_b128 v[244:247], v248 offset:16384
	ds_read_b128 v[248:251], v248 offset:24576
	v_add_f32_e32 v252, v106, v252
	v_add_f32_e32 v252, v107, v252
	v_add_f32_e32 v252, v108, v252
	s_waitcnt lgkmcnt(0)
	v_mfma_f32_32x32x16_bf16 v[80:95], v[248:251], v[156:159], v[80:95]
	v_add_f32_e32 v252, v109, v252
	v_add_f32_e32 v252, v110, v252
	v_add_f32_e32 v252, v111, v252
	v_add_u32_e32 v248, v243, v223
	v_mfma_f32_32x32x16_bf16 v[112:127], v[244:247], v[156:159], v[112:127]
	ds_read_b128 v[244:247], v248 offset:32768
	ds_read_b128 v[248:251], v248 offset:36864
	v_mov_b32_e32 v253, v252
	v_cvt_pk_bf16_f32 v111, v110, v111
	v_cvt_pk_bf16_f32 v110, v108, v109
	s_waitcnt lgkmcnt(0)
	v_mfma_f32_32x32x16_bf16 v[80:95], v[248:251], v[164:167], v[80:95]
	v_permlane32_swap_b32_e32 v252, v253
	v_cvt_pk_bf16_f32 v109, v106, v107
	v_cvt_pk_bf16_f32 v108, v104, v105
	v_add_u32_e32 v248, v243, v224
	v_mfma_f32_32x32x16_bf16 v[112:127], v[244:247], v[164:167], v[112:127]
	ds_read_b128 v[244:247], v248 offset:32768
	ds_read_b128 v[248:251], v248 offset:36864
	v_add_f32_e32 v252, v252, v253
	v_cvt_pk_bf16_f32 v107, v102, v103
	v_add_f32_e32 v176, v176, v252
	s_waitcnt lgkmcnt(0)
	v_mfma_f32_32x32x16_bf16 v[80:95], v[248:251], v[172:175], v[80:95]
	v_cvt_pk_bf16_f32 v106, v100, v101
	v_cvt_pk_bf16_f32 v105, v98, v99
	v_cvt_pk_bf16_f32 v104, v96, v97
	v_add_u32_e32 v248, v243, v225
	v_mfma_f32_32x32x16_bf16 v[112:127], v[244:247], v[172:175], v[112:127]
	ds_read_b128 v[244:247], v248 offset:32768
	ds_read_b128 v[248:251], v248 offset:36864
	v_cvt_pk_bf16_f32 v96, v198, v199
	v_cvt_pk_bf16_f32 v97, v227, v228
	v_cvt_pk_bf16_f32 v98, v229, v230
	s_waitcnt lgkmcnt(0)
	v_mfma_f32_32x32x16_bf16 v[80:95], v[248:251], v[160:163], v[80:95]
	v_cvt_pk_bf16_f32 v99, v231, v232
	v_cvt_pk_bf16_f32 v100, v233, v234
	v_cvt_pk_bf16_f32 v101, v235, v236
	v_add_u32_e32 v248, v243, v226
	v_mfma_f32_32x32x16_bf16 v[112:127], v[244:247], v[160:163], v[112:127]
	ds_read_b128 v[244:247], v248 offset:32768
	ds_read_b128 v[248:251], v248 offset:36864
	v_cvt_pk_bf16_f32 v102, v237, v238
	v_cvt_pk_bf16_f32 v103, v239, v240
	v_permlane32_swap_b32_e32 v104, v106
	s_waitcnt lgkmcnt(0)
	v_mfma_f32_32x32x16_bf16 v[80:95], v[248:251], v[168:171], v[80:95]
	v_permlane32_swap_b32_e32 v105, v107
	v_permlane32_swap_b32_e32 v108, v110
	v_permlane32_swap_b32_e32 v109, v111
	v_mfma_f32_32x32x16_bf16 v[112:127], v[244:247], v[168:171], v[112:127]
	s_setprio 0
	v_permlane32_swap_b32_e32 v96, v98
	v_permlane32_swap_b32_e32 v97, v99
	v_permlane32_swap_b32_e32 v100, v102
	v_permlane32_swap_b32_e32 v101, v103
	v_add_u32_e32 v196, s49, v212
	ds_read_b64_tr_b16 v[188:189], v196 offset:0
	ds_read_b64_tr_b16 v[190:191], v196 offset:0x800
	ds_read_b64_tr_b16 v[192:193], v196 offset:0x1000
	ds_read_b64_tr_b16 v[194:195], v196 offset:0x1800
	ds_read_b64_tr_b16 v[228:229], v196 offset:0x2000
	ds_read_b64_tr_b16 v[230:231], v196 offset:0x2800
	ds_read_b64_tr_b16 v[232:233], v196 offset:0x3000
	ds_read_b64_tr_b16 v[234:235], v196 offset:0x3800
	s_waitcnt lgkmcnt(0)
	s_nop 0
	v_mfma_f32_32x32x16_bf16 v[64:79], v[96:99], v[188:191], v[64:79]
	ds_read_b64_tr_b16 v[188:189], v196 offset:0x200
	ds_read_b64_tr_b16 v[190:191], v196 offset:0xa00
	v_mfma_f32_32x32x16_bf16 v[64:79], v[100:103], v[192:195], v[64:79]
	ds_read_b64_tr_b16 v[192:193], v196 offset:0x1200
	ds_read_b64_tr_b16 v[194:195], v196 offset:0x1a00
	v_mfma_f32_32x32x16_bf16 v[64:79], v[104:107], v[228:231], v[64:79]
	ds_read_b64_tr_b16 v[228:229], v196 offset:0x2200
	ds_read_b64_tr_b16 v[230:231], v196 offset:0x2a00
	ds_read_b64_tr_b16 v[236:237], v196 offset:0x3200
	ds_read_b64_tr_b16 v[238:239], v196 offset:0x3a00
	s_waitcnt lgkmcnt(0)
	v_mfma_f32_32x32x16_bf16 v[64:79], v[108:111], v[232:235], v[64:79]
	v_mfma_f32_32x32x16_bf16 v[48:63], v[96:99], v[188:191], v[48:63]
	ds_read_b64_tr_b16 v[188:189], v196 offset:0x400
	ds_read_b64_tr_b16 v[190:191], v196 offset:0xc00
	v_mfma_f32_32x32x16_bf16 v[48:63], v[100:103], v[192:195], v[48:63]
	ds_read_b64_tr_b16 v[192:193], v196 offset:0x1400
	ds_read_b64_tr_b16 v[194:195], v196 offset:0x1c00
	v_mfma_f32_32x32x16_bf16 v[48:63], v[104:107], v[228:231], v[48:63]
	ds_read_b64_tr_b16 v[228:229], v196 offset:0x2400
	ds_read_b64_tr_b16 v[230:231], v196 offset:0x2c00
	ds_read_b64_tr_b16 v[232:233], v196 offset:0x3400
	ds_read_b64_tr_b16 v[234:235], v196 offset:0x3c00
	s_waitcnt lgkmcnt(0)
; #define WAITV(n) asm volatile("s_waitcnt vmcnt(" #n ")" ::: "memory")
; #define TBAR() do { __builtin_amdgcn_s_barrier(); SBAR(); } while (0)
; __device__ __forceinline__ void qkt(f32x16& p0, f32x16& p1, const char* Ks, const bf16x8* qr, int r32, int hi, float negM) {
; #pragma unroll
;   for (int r = 0; r < 16; ++r) { p0[r] = negM; p1[r] = negM; }
;   __builtin_amdgcn_s_setprio(1);
;   const char* kn = Ks + r32 * 256; const int xn = r32 & 15;
; #pragma unroll
;   for (int d0 = 0; d0 < 8; ++d0) { const int off = ((d0 * 2 + hi) ^ xn) << 4;
;     bf16x8 b0 = *reinterpret_cast<const bf16x8*>(kn + off);
;     bf16x8 b1 = *reinterpret_cast<const bf16x8*>(kn + 32 * 256 + off);
;     p0 = __builtin_amdgcn_mfma_f32_32x32x16_bf16(b0, qr[d0], p0, 0, 0, 0);
;     p1 = __builtin_amdgcn_mfma_f32_32x32x16_bf16(b1, qr[d0], p1, 0, 0, 0); }
;   const char* kr = Ks + KROPE_OFF + r32 * 128; const int xr = (r32 >> 1) & 7;
; #pragma unroll
;   for (int d0 = 8; d0 < 12; ++d0) { const int off = (((d0 - 8) * 2 + hi) ^ xr) << 4;
;     bf16x8 b0 = *reinterpret_cast<const bf16x8*>(kr + off);
;     bf16x8 b1 = *reinterpret_cast<const bf16x8*>(kr + 32 * 128 + off);
;     p0 = __builtin_amdgcn_mfma_f32_32x32x16_bf16(b0, qr[d0], p0, 0, 0, 0);
;     p1 = __builtin_amdgcn_mfma_f32_32x32x16_bf16(b1, qr[d0], p1, 0, 0, 0); }
;   __builtin_amdgcn_s_setprio(0);
; }
; __device__ __forceinline__ void attn_body(const u16* __restrict__ Qb, const u16* __restrict__ Kn, const u16* __restrict__ Kr,
;                                           u16* __restrict__ Ob, char* lds, int tid, const float* __restrict__ gq_, const float* __restrict__ tab_, int qpos0, float negM) {
;     ...
;     pv_d0(o, vrb + prv, pa0, pa1, pa2, pa3); partialSM(pA0);
;     { const int t_ = prv; prv = cur; cur = nxt; nxt = t_; }
;   }
;   WAITV(0); asm volatile("s_waitcnt lgkmcnt(0)" ::: "memory"); TBAR();
;   qkt(pB0, pB1, lds + cur + KOFF, qr, r32, hi, negM);
	v_mfma_f32_32x32x16_bf16 v[48:63], v[108:111], v[236:239], v[48:63]
	v_mfma_f32_32x32x16_bf16 v[32:47], v[96:99], v[188:191], v[32:47]
	ds_read_b64_tr_b16 v[188:189], v196 offset:0x600
	ds_read_b64_tr_b16 v[190:191], v196 offset:0xe00
	v_mfma_f32_32x32x16_bf16 v[32:47], v[100:103], v[192:195], v[32:47]
	ds_read_b64_tr_b16 v[192:193], v196 offset:0x1600
	ds_read_b64_tr_b16 v[194:195], v196 offset:0x1e00
	ds_read_b64_tr_b16 v[244:245], v196 offset:0x2600
	ds_read_b64_tr_b16 v[246:247], v196 offset:0x2e00
	ds_read_b64_tr_b16 v[248:249], v196 offset:0x3600
	ds_read_b64_tr_b16 v[250:251], v196 offset:0x3e00
	s_waitcnt lgkmcnt(0)
	v_mfma_f32_32x32x16_bf16 v[32:47], v[104:107], v[228:231], v[32:47]
	v_mfma_f32_32x32x16_bf16 v[32:47], v[108:111], v[232:235], v[32:47]
	v_mfma_f32_32x32x16_bf16 v[16:31], v[96:99], v[188:191], v[16:31]
	v_exp_f32_e32 v240, v112
	v_exp_f32_e32 v242, v113
	v_exp_f32_e32 v238, v114
	v_exp_f32_e32 v241, v115
	v_exp_f32_e32 v236, v116
	v_exp_f32_e32 v239, v117
	v_exp_f32_e32 v235, v118
	v_mfma_f32_32x32x16_bf16 v[16:31], v[100:103], v[192:195], v[16:31]
	v_exp_f32_e32 v237, v119
	v_exp_f32_e32 v232, v120
	v_exp_f32_e32 v234, v121
	v_exp_f32_e32 v230, v122
	v_exp_f32_e32 v233, v123
	v_exp_f32_e32 v228, v124
	v_exp_f32_e32 v231, v125
	v_mfma_f32_32x32x16_bf16 v[16:31], v[104:107], v[244:247], v[16:31]
	v_exp_f32_e32 v227, v126
	v_exp_f32_e32 v229, v127
	s_add_i32 s48, s48, 2
	v_lshl_add_u64 v[178:179], v[178:179], 0, s[44:45]
	v_lshl_add_u64 v[180:181], v[180:181], 0, s[46:47]
	v_lshl_add_u64 v[182:183], v[182:183], 0, s[46:47]
	v_lshl_add_u64 v[184:185], v[184:185], 0, s[46:47]
	v_mfma_f32_32x32x16_bf16 v[16:31], v[108:111], v[248:251], v[16:31]
	v_lshl_add_u64 v[186:187], v[186:187], 0, s[46:47]
	s_mov_b32 s54, s49
	s_mov_b32 s49, s50
	s_cmp_gt_u32 s48, 28
	s_mov_b32 s50, s51
	s_cbranch_scc0 .LBB0_719
	s_waitcnt vmcnt(0)
	s_waitcnt lgkmcnt(0)
	v_and_b32_e32 v96, 0x3fffffc0, v210
	v_mov_b32_e32 v97, 0x1e000
	v_lshl_add_u32 v178, v96, 2, v97
	s_barrier
	s_setprio 1
	v_or_b32_e32 v179, 0xe000, v213
	v_add_u32_e32 v96, v213, v214
	v_add_u32_e32 v100, v179, v214
	ds_read_b128 v[96:99], v96 offset:57344
	ds_read_b128 v[180:183], v100 offset:8192
	s_waitcnt lgkmcnt(0)
	v_mfma_f32_32x32x16_bf16 v[112:127], v[96:99], v[128:131], v[0:15]
	v_mfma_f32_32x32x16_bf16 v[96:111], v[180:183], v[128:131], v[0:15]
	v_add_u32_e32 v128, v213, v215
	v_add_u32_e32 v180, v179, v215
	ds_read_b128 v[128:131], v128 offset:57344
	ds_read_b128 v[180:183], v180 offset:8192
	s_waitcnt lgkmcnt(0)
	v_mfma_f32_32x32x16_bf16 v[112:127], v[128:131], v[132:135], v[112:127]
	v_add_u32_e32 v128, v213, v216
	ds_read_b128 v[128:131], v128 offset:57344
	v_mfma_f32_32x32x16_bf16 v[96:111], v[180:183], v[132:135], v[96:111]
	v_add_u32_e32 v132, v179, v216
	ds_read_b128 v[132:135], v132 offset:8192
	s_waitcnt lgkmcnt(0)
	v_mfma_f32_32x32x16_bf16 v[112:127], v[128:131], v[136:139], v[112:127]
	v_add_u32_e32 v128, v213, v217
	ds_read_b128 v[128:131], v128 offset:57344
	v_mfma_f32_32x32x16_bf16 v[96:111], v[132:135], v[136:139], v[96:111]
	v_add_u32_e32 v132, v179, v217
	ds_read_b128 v[132:135], v132 offset:8192
	v_or_b32_e32 v136, 0x12000, v222
	s_waitcnt lgkmcnt(0)
	v_mfma_f32_32x32x16_bf16 v[112:127], v[128:131], v[140:143], v[112:127]
	v_add_u32_e32 v128, v213, v218
	ds_read_b128 v[128:131], v128 offset:57344
	v_mfma_f32_32x32x16_bf16 v[96:111], v[132:135], v[140:143], v[96:111]
	v_add_u32_e32 v132, v179, v218
	ds_read_b128 v[132:135], v132 offset:8192
	s_waitcnt lgkmcnt(0)
	v_mfma_f32_32x32x16_bf16 v[112:127], v[128:131], v[144:147], v[112:127]
	v_add_u32_e32 v128, v213, v219
	ds_read_b128 v[128:131], v128 offset:57344
	v_mfma_f32_32x32x16_bf16 v[96:111], v[132:135], v[144:147], v[96:111]
	v_add_u32_e32 v132, v179, v219
	ds_read_b128 v[132:135], v132 offset:8192
	s_waitcnt lgkmcnt(0)
	v_mfma_f32_32x32x16_bf16 v[112:127], v[128:131], v[148:151], v[112:127]
	v_add_u32_e32 v128, v213, v220
	ds_read_b128 v[128:131], v128 offset:57344
	v_mfma_f32_32x32x16_bf16 v[96:111], v[132:135], v[148:151], v[96:111]
	v_add_u32_e32 v132, v179, v220
	ds_read_b128 v[132:135], v132 offset:8192
	s_waitcnt lgkmcnt(0)
	v_mfma_f32_32x32x16_bf16 v[112:127], v[128:131], v[152:155], v[112:127]
	v_add_u32_e32 v128, v213, v221
	ds_read_b128 v[128:131], v128 offset:57344
	v_mfma_f32_32x32x16_bf16 v[96:111], v[132:135], v[152:155], v[96:111]
	v_add_u32_e32 v132, v179, v221
	ds_read_b128 v[132:135], v132 offset:8192
	s_waitcnt lgkmcnt(0)
	v_mfma_f32_32x32x16_bf16 v[112:127], v[128:131], v[156:159], v[112:127]
	v_mfma_f32_32x32x16_bf16 v[96:111], v[132:135], v[156:159], v[96:111]
	v_add_u32_e32 v132, v136, v223
	ds_read_b128 v[128:131], v132
	ds_read_b128 v[132:135], v132 offset:4096
	s_waitcnt lgkmcnt(0)
	v_mfma_f32_32x32x16_bf16 v[112:127], v[128:131], v[164:167], v[112:127]
	v_mfma_f32_32x32x16_bf16 v[96:111], v[132:135], v[164:167], v[96:111]
	v_add_u32_e32 v132, v136, v224
	ds_read_b128 v[128:131], v132
	ds_read_b128 v[132:135], v132 offset:4096
	s_waitcnt lgkmcnt(0)
	v_mfma_f32_32x32x16_bf16 v[112:127], v[128:131], v[172:175], v[112:127]
	v_mfma_f32_32x32x16_bf16 v[96:111], v[132:135], v[172:175], v[96:111]
	v_add_u32_e32 v132, v136, v225
	ds_read_b128 v[128:131], v132
	ds_read_b128 v[132:135], v132 offset:4096
	s_waitcnt lgkmcnt(0)
	v_mfma_f32_32x32x16_bf16 v[112:127], v[128:131], v[160:163], v[112:127]
	v_mfma_f32_32x32x16_bf16 v[96:111], v[132:135], v[160:163], v[96:111]
	v_add_u32_e32 v132, v136, v226
	ds_read_b128 v[128:131], v132
	ds_read_b128 v[132:135], v132 offset:4096
	s_waitcnt lgkmcnt(0)
; #define SBAR() __builtin_amdgcn_sched_barrier(0)
; __device__ __forceinline__ void finishSM(f32x16& p0, f32x16& p1, float& l_reg, bf16x8& pa0, bf16x8& pa1, bf16x8& pa2, bf16x8& pa3) {
; #pragma unroll
;   for (int r = 0; r < 16; ++r) p1[r] = __builtin_amdgcn_exp2f(p1[r]);
;   float ps = 0;
; #pragma unroll
;   for (int r = 0; r < 16; ++r) ps += p0[r];
; #pragma unroll
;   for (int r = 0; r < 16; ++r) ps += p1[r];
;   { auto rr = __builtin_amdgcn_permlane32_swap(__float_as_uint(ps), __float_as_uint(ps), false, false);
;     ps = __uint_as_float(rr[0]) + __uint_as_float(rr[1]); }
;   l_reg += ps;
;     ...
;   PK4(p0, 0, pa0); PK4(p0, 8, pa1); PK4(p1, 0, pa2); PK4(p1, 8, pa3);
; __device__ __forceinline__ void attn_body(const u16* __restrict__ Qb, const u16* __restrict__ Kn, const u16* __restrict__ Kr,
;                                           u16* __restrict__ Ob, char* lds, int tid, const float* __restrict__ gq_, const float* __restrict__ tab_, int qpos0, float negM) {
;     ...
;   finishSM(pA0, pA1, l_reg, pa0, pa1, pa2, pa3); SBAR();
;   pv_d0(o, vrb + prv, pa0, pa1, pa2, pa3); partialSM(pB0);
	v_mfma_f32_32x32x16_bf16 v[112:127], v[128:131], v[168:171], v[112:127]
	v_mfma_f32_32x32x16_bf16 v[96:111], v[132:135], v[168:171], v[96:111]
	s_setprio 0
	v_exp_f32_e32 v128, v80
	v_add_f32_e32 v80, 0, v240
	v_add_f32_e32 v80, v242, v80
	v_add_f32_e32 v80, v238, v80
	v_add_f32_e32 v80, v241, v80
	v_add_f32_e32 v80, v236, v80
	v_add_f32_e32 v80, v239, v80
	v_add_f32_e32 v80, v235, v80
	v_add_f32_e32 v80, v237, v80
	v_add_f32_e32 v80, v232, v80
	v_add_f32_e32 v80, v234, v80
	v_add_f32_e32 v80, v230, v80
	v_add_f32_e32 v80, v233, v80
	v_add_f32_e32 v80, v228, v80
	v_exp_f32_e32 v81, v81
	v_add_f32_e32 v80, v231, v80
	v_exp_f32_e32 v129, v82
	v_add_f32_e32 v80, v227, v80
	v_exp_f32_e32 v83, v83
	v_add_f32_e32 v80, v229, v80
	v_exp_f32_e32 v130, v84
	v_add_f32_e32 v80, v128, v80
	v_exp_f32_e32 v131, v85
	v_add_f32_e32 v80, v81, v80
	v_exp_f32_e32 v132, v86
	v_add_f32_e32 v80, v129, v80
	v_exp_f32_e32 v133, v87
	v_add_f32_e32 v80, v83, v80
	v_exp_f32_e32 v134, v88
	v_add_f32_e32 v80, v130, v80
	v_exp_f32_e32 v135, v89
	v_add_f32_e32 v80, v131, v80
	v_exp_f32_e32 v136, v90
	v_add_f32_e32 v80, v132, v80
	v_exp_f32_e32 v137, v91
	v_add_f32_e32 v80, v133, v80
	v_exp_f32_e32 v138, v92
	v_add_f32_e32 v80, v134, v80
	v_exp_f32_e32 v139, v93
	v_add_f32_e32 v80, v135, v80
	v_exp_f32_e32 v140, v94
	v_add_f32_e32 v80, v136, v80
	v_exp_f32_e32 v141, v95
	v_add_f32_e32 v80, v137, v80
	v_add_f32_e32 v80, v138, v80
	v_add_f32_e32 v80, v139, v80
	v_add_f32_e32 v80, v140, v80
	v_add_f32_e32 v80, v141, v80
	v_mov_b32_e32 v82, v80
	s_nop 1
	v_permlane32_swap_b32_e32 v80, v82
	s_nop 0
	v_cvt_pk_bf16_f32 v84, v240, v242
	s_nop 0
	v_cvt_pk_bf16_f32 v85, v238, v241
	s_nop 0
	v_cvt_pk_bf16_f32 v86, v236, v239
	s_nop 0
	v_cvt_pk_bf16_f32 v87, v235, v237
	s_nop 0
	v_cvt_pk_bf16_f32 v88, v232, v234
	s_nop 0
	v_cvt_pk_bf16_f32 v89, v230, v233
	s_nop 0
	v_cvt_pk_bf16_f32 v90, v228, v231
	s_nop 0
	v_cvt_pk_bf16_f32 v91, v227, v229
	s_nop 0
	v_cvt_pk_bf16_f32 v92, v128, v81
	s_nop 0
	v_cvt_pk_bf16_f32 v93, v129, v83
	s_nop 0
	v_cvt_pk_bf16_f32 v94, v130, v131
	s_nop 0
	v_cvt_pk_bf16_f32 v95, v132, v133
	s_nop 0
	v_cvt_pk_bf16_f32 v128, v134, v135
	s_nop 0
	v_cvt_pk_bf16_f32 v129, v136, v137
	s_nop 0
	v_cvt_pk_bf16_f32 v130, v138, v139
	s_nop 0
	v_cvt_pk_bf16_f32 v131, v140, v141
	s_nop 0
	v_permlane32_swap_b32_e32 v84, v86
	v_permlane32_swap_b32_e32 v85, v87
	v_permlane32_swap_b32_e32 v88, v90
	v_permlane32_swap_b32_e32 v89, v91
	v_permlane32_swap_b32_e32 v92, v94
	v_permlane32_swap_b32_e32 v93, v95
	v_permlane32_swap_b32_e32 v128, v130
	v_permlane32_swap_b32_e32 v129, v131
	ds_read_b64_tr_b16 v[132:133], v212 offset:0
	ds_read_b64_tr_b16 v[134:135], v212 offset:0x800
	ds_read_b64_tr_b16 v[136:137], v212 offset:0x1000
	ds_read_b64_tr_b16 v[138:139], v212 offset:0x1800
	ds_read_b64_tr_b16 v[140:141], v212 offset:0x2000
	ds_read_b64_tr_b16 v[142:143], v212 offset:0x2800
	ds_read_b64_tr_b16 v[144:145], v212 offset:0x3000
	ds_read_b64_tr_b16 v[146:147], v212 offset:0x3800
	s_waitcnt lgkmcnt(0)
	s_nop 0
	v_mfma_f32_32x32x16_bf16 v[64:79], v[84:87], v[132:135], v[64:79]
	ds_read_b64_tr_b16 v[132:133], v212 offset:0x200
	ds_read_b64_tr_b16 v[134:135], v212 offset:0xa00
	v_mfma_f32_32x32x16_bf16 v[64:79], v[88:91], v[136:139], v[64:79]
	ds_read_b64_tr_b16 v[136:137], v212 offset:0x1200
	ds_read_b64_tr_b16 v[138:139], v212 offset:0x1a00
	v_mfma_f32_32x32x16_bf16 v[64:79], v[92:95], v[140:143], v[64:79]
	ds_read_b64_tr_b16 v[140:141], v212 offset:0x2200
	ds_read_b64_tr_b16 v[142:143], v212 offset:0x2a00
	ds_read_b64_tr_b16 v[148:149], v212 offset:0x3200
	ds_read_b64_tr_b16 v[150:151], v212 offset:0x3a00
	s_waitcnt lgkmcnt(0)
	v_mfma_f32_32x32x16_bf16 v[64:79], v[128:131], v[144:147], v[64:79]
	v_mfma_f32_32x32x16_bf16 v[48:63], v[84:87], v[132:135], v[48:63]
	ds_read_b64_tr_b16 v[132:133], v212 offset:0x400
	ds_read_b64_tr_b16 v[134:135], v212 offset:0xc00
	v_mfma_f32_32x32x16_bf16 v[48:63], v[88:91], v[136:139], v[48:63]
	ds_read_b64_tr_b16 v[136:137], v212 offset:0x1400
	ds_read_b64_tr_b16 v[138:139], v212 offset:0x1c00
	v_mfma_f32_32x32x16_bf16 v[48:63], v[92:95], v[140:143], v[48:63]
	ds_read_b64_tr_b16 v[140:141], v212 offset:0x2400
	ds_read_b64_tr_b16 v[142:143], v212 offset:0x2c00
	ds_read_b64_tr_b16 v[144:145], v212 offset:0x3400
	ds_read_b64_tr_b16 v[146:147], v212 offset:0x3c00
	s_waitcnt lgkmcnt(0)
	v_mfma_f32_32x32x16_bf16 v[48:63], v[128:131], v[148:151], v[48:63]
	v_mfma_f32_32x32x16_bf16 v[32:47], v[84:87], v[132:135], v[32:47]
	ds_read_b64_tr_b16 v[132:133], v212 offset:0x600
	ds_read_b64_tr_b16 v[134:135], v212 offset:0xe00
	v_mfma_f32_32x32x16_bf16 v[32:47], v[88:91], v[136:139], v[32:47]
	ds_read_b64_tr_b16 v[136:137], v212 offset:0x1600
	ds_read_b64_tr_b16 v[138:139], v212 offset:0x1e00
	v_mfma_f32_32x32x16_bf16 v[32:47], v[92:95], v[140:143], v[32:47]
	ds_read_b64_tr_b16 v[140:141], v212 offset:0x2600
	ds_read_b64_tr_b16 v[142:143], v212 offset:0x2e00
	ds_read_b64_tr_b16 v[148:149], v212 offset:0x3600
	ds_read_b64_tr_b16 v[150:151], v212 offset:0x3e00
	s_waitcnt lgkmcnt(0)
; #define SBAR() __builtin_amdgcn_sched_barrier(0)
; __device__ __forceinline__ void finishSM(f32x16& p0, f32x16& p1, float& l_reg, bf16x8& pa0, bf16x8& pa1, bf16x8& pa2, bf16x8& pa3) {
; #pragma unroll
;   for (int r = 0; r < 16; ++r) p1[r] = __builtin_amdgcn_exp2f(p1[r]);
;   float ps = 0;
; #pragma unroll
;   for (int r = 0; r < 16; ++r) ps += p0[r];
; #pragma unroll
;   for (int r = 0; r < 16; ++r) ps += p1[r];
;   { auto rr = __builtin_amdgcn_permlane32_swap(__float_as_uint(ps), __float_as_uint(ps), false, false);
;     ps = __uint_as_float(rr[0]) + __uint_as_float(rr[1]); }
;   l_reg += ps;
;     ...
;   PK4(p0, 0, pa0); PK4(p0, 8, pa1); PK4(p1, 0, pa2); PK4(p1, 8, pa3);
; __device__ __forceinline__ void attn_body(const u16* __restrict__ Qb, const u16* __restrict__ Kn, const u16* __restrict__ Kr,
;                                           u16* __restrict__ Ob, char* lds, int tid, const float* __restrict__ gq_, const float* __restrict__ tab_, int qpos0, float negM) {
;     ...
;   pv_d0(o, vrb + prv, pa0, pa1, pa2, pa3); partialSM(pB0);
;   finishSM(pB0, pB1, l_reg, pa0, pa1, pa2, pa3); SBAR();
;   pv_d0(o, vrb + cur, pa0, pa1, pa2, pa3);
;   if (hi == 0) li_l[r32] = l_reg; asm volatile("s_waitcnt lgkmcnt(0)" ::: "memory");
	v_mfma_f32_32x32x16_bf16 v[32:47], v[128:131], v[144:147], v[32:47]
	v_exp_f32_e32 v112, v112
	v_exp_f32_e32 v113, v113
	v_exp_f32_e32 v114, v114
	v_exp_f32_e32 v115, v115
	v_exp_f32_e32 v116, v116
	v_mfma_f32_32x32x16_bf16 v[16:31], v[84:87], v[132:135], v[16:31]
	v_add_f32_e32 v81, 0, v112
	v_exp_f32_e32 v117, v117
	v_add_f32_e32 v81, v113, v81
	v_exp_f32_e32 v87, v118
	v_add_f32_e32 v81, v114, v81
	v_exp_f32_e32 v118, v119
	v_add_f32_e32 v81, v115, v81
	v_exp_f32_e32 v119, v120
	v_add_f32_e32 v81, v116, v81
	v_exp_f32_e32 v120, v121
	v_add_f32_e32 v81, v117, v81
	v_exp_f32_e32 v121, v122
	v_add_f32_e32 v81, v87, v81
	v_exp_f32_e32 v122, v123
	v_add_f32_e32 v81, v118, v81
	v_exp_f32_e32 v123, v124
	v_mfma_f32_32x32x16_bf16 v[16:31], v[88:91], v[136:139], v[16:31]
	v_add_f32_e32 v81, v119, v81
	v_exp_f32_e32 v90, v125
	v_add_f32_e32 v81, v120, v81
	v_exp_f32_e32 v91, v126
	v_add_f32_e32 v81, v121, v81
	v_exp_f32_e32 v124, v127
	v_add_f32_e32 v81, v122, v81
	v_exp_f32_e32 v96, v96
	v_add_f32_e32 v81, v123, v81
	v_exp_f32_e32 v97, v97
	v_add_f32_e32 v81, v90, v81
	v_exp_f32_e32 v98, v98
	v_add_f32_e32 v81, v91, v81
	v_exp_f32_e32 v99, v99
	v_add_f32_e32 v81, v124, v81
	v_mfma_f32_32x32x16_bf16 v[16:31], v[92:95], v[140:143], v[16:31]
	v_exp_f32_e32 v94, v100
	v_add_f32_e32 v81, v96, v81
	v_exp_f32_e32 v95, v101
	v_add_f32_e32 v81, v97, v81
	v_exp_f32_e32 v100, v102
	v_add_f32_e32 v81, v98, v81
	v_exp_f32_e32 v101, v103
	v_add_f32_e32 v81, v99, v81
	v_exp_f32_e32 v102, v104
	v_add_f32_e32 v81, v94, v81
	v_exp_f32_e32 v103, v105
	v_add_f32_e32 v81, v95, v81
	v_exp_f32_e32 v104, v106
	v_add_f32_e32 v81, v100, v81
	v_exp_f32_e32 v105, v107
	v_add_f32_e32 v81, v101, v81
	v_exp_f32_e32 v106, v108
	v_add_f32_e32 v81, v102, v81
	v_exp_f32_e32 v107, v109
	v_add_f32_e32 v81, v103, v81
	v_mfma_f32_32x32x16_bf16 v[16:31], v[128:131], v[148:151], v[16:31]
	v_exp_f32_e32 v108, v110
	v_add_f32_e32 v81, v104, v81
	v_exp_f32_e32 v109, v111
	v_add_f32_e32 v81, v105, v81
	v_add_f32_e32 v81, v106, v81
	v_add_f32_e32 v81, v107, v81
	v_add_f32_e32 v81, v108, v81
	v_add_f32_e32 v81, v109, v81
	v_mov_b32_e32 v83, v81
	s_nop 1
	v_permlane32_swap_b32_e32 v81, v83
	s_nop 0
	v_cvt_pk_bf16_f32 v84, v112, v113
	s_nop 0
	v_cvt_pk_bf16_f32 v85, v114, v115
	s_nop 0
	v_cvt_pk_bf16_f32 v86, v116, v117
	s_nop 0
	v_cvt_pk_bf16_f32 v87, v87, v118
	s_nop 0
	v_cvt_pk_bf16_f32 v88, v119, v120
	s_nop 0
	v_cvt_pk_bf16_f32 v89, v121, v122
	s_nop 0
	v_cvt_pk_bf16_f32 v90, v123, v90
	s_nop 0
	v_cvt_pk_bf16_f32 v91, v91, v124
	s_nop 0
	v_cvt_pk_bf16_f32 v92, v96, v97
	s_nop 0
	v_cvt_pk_bf16_f32 v93, v98, v99
	s_nop 0
	v_cvt_pk_bf16_f32 v94, v94, v95
	s_nop 0
	v_cvt_pk_bf16_f32 v95, v100, v101
	s_nop 0
	v_cvt_pk_bf16_f32 v96, v102, v103
	s_nop 0
	v_cvt_pk_bf16_f32 v97, v104, v105
	s_nop 0
	v_cvt_pk_bf16_f32 v98, v106, v107
	s_nop 0
	v_cvt_pk_bf16_f32 v99, v108, v109
	s_nop 0
	v_permlane32_swap_b32_e32 v84, v86
	v_permlane32_swap_b32_e32 v85, v87
	v_permlane32_swap_b32_e32 v88, v90
	v_permlane32_swap_b32_e32 v89, v91
	v_permlane32_swap_b32_e32 v92, v94
	v_permlane32_swap_b32_e32 v93, v95
	v_permlane32_swap_b32_e32 v96, v98
	v_permlane32_swap_b32_e32 v97, v99
	v_or_b32_e32 v120, 0xa000, v212
	ds_read_b64_tr_b16 v[100:101], v120 offset:0
	ds_read_b64_tr_b16 v[102:103], v120 offset:0x800
	ds_read_b64_tr_b16 v[104:105], v120 offset:0x1000
	ds_read_b64_tr_b16 v[106:107], v120 offset:0x1800
	ds_read_b64_tr_b16 v[108:109], v120 offset:0x2000
	ds_read_b64_tr_b16 v[110:111], v120 offset:0x2800
	ds_read_b64_tr_b16 v[112:113], v120 offset:0x3000
	ds_read_b64_tr_b16 v[114:115], v120 offset:0x3800
	s_waitcnt lgkmcnt(0)
	s_nop 0
	v_mfma_f32_32x32x16_bf16 v[64:79], v[84:87], v[100:103], v[64:79]
	ds_read_b64_tr_b16 v[100:101], v120 offset:0x200
	ds_read_b64_tr_b16 v[102:103], v120 offset:0xa00
	v_mfma_f32_32x32x16_bf16 v[64:79], v[88:91], v[104:107], v[64:79]
	ds_read_b64_tr_b16 v[104:105], v120 offset:0x1200
	ds_read_b64_tr_b16 v[106:107], v120 offset:0x1a00
	v_mfma_f32_32x32x16_bf16 v[64:79], v[92:95], v[108:111], v[64:79]
	ds_read_b64_tr_b16 v[108:109], v120 offset:0x2200
	ds_read_b64_tr_b16 v[110:111], v120 offset:0x2a00
	ds_read_b64_tr_b16 v[116:117], v120 offset:0x3200
	ds_read_b64_tr_b16 v[118:119], v120 offset:0x3a00
	s_waitcnt lgkmcnt(0)
	v_mfma_f32_32x32x16_bf16 v[64:79], v[96:99], v[112:115], v[64:79]
	v_mfma_f32_32x32x16_bf16 v[48:63], v[84:87], v[100:103], v[48:63]
	ds_read_b64_tr_b16 v[100:101], v120 offset:0x400
	ds_read_b64_tr_b16 v[102:103], v120 offset:0xc00
	v_mfma_f32_32x32x16_bf16 v[48:63], v[88:91], v[104:107], v[48:63]
	ds_read_b64_tr_b16 v[104:105], v120 offset:0x1400
	ds_read_b64_tr_b16 v[106:107], v120 offset:0x1c00
	v_mfma_f32_32x32x16_bf16 v[48:63], v[92:95], v[108:111], v[48:63]
	ds_read_b64_tr_b16 v[108:109], v120 offset:0x2400
	ds_read_b64_tr_b16 v[110:111], v120 offset:0x2c00
	ds_read_b64_tr_b16 v[112:113], v120 offset:0x3400
	ds_read_b64_tr_b16 v[114:115], v120 offset:0x3c00
	s_waitcnt lgkmcnt(0)
	v_mfma_f32_32x32x16_bf16 v[48:63], v[96:99], v[116:119], v[48:63]
	v_mfma_f32_32x32x16_bf16 v[32:47], v[84:87], v[100:103], v[32:47]
	ds_read_b64_tr_b16 v[100:101], v120 offset:0x600
	ds_read_b64_tr_b16 v[102:103], v120 offset:0xe00
	v_mfma_f32_32x32x16_bf16 v[32:47], v[88:91], v[104:107], v[32:47]
	ds_read_b64_tr_b16 v[104:105], v120 offset:0x1600
	ds_read_b64_tr_b16 v[106:107], v120 offset:0x1e00
	v_mfma_f32_32x32x16_bf16 v[32:47], v[92:95], v[108:111], v[32:47]
	ds_read_b64_tr_b16 v[108:109], v120 offset:0x2600
	ds_read_b64_tr_b16 v[110:111], v120 offset:0x2e00
	ds_read_b64_tr_b16 v[116:117], v120 offset:0x3600
	ds_read_b64_tr_b16 v[118:119], v120 offset:0x3e00
	s_waitcnt lgkmcnt(0)
	v_mfma_f32_32x32x16_bf16 v[32:47], v[96:99], v[112:115], v[32:47]
	v_mfma_f32_32x32x16_bf16 v[16:31], v[84:87], v[100:103], v[16:31]
	v_cmp_gt_u32_e32 vcc, 32, v209
	v_mfma_f32_32x32x16_bf16 v[16:31], v[88:91], v[104:107], v[16:31]
	v_mfma_f32_32x32x16_bf16 v[16:31], v[92:95], v[108:111], v[16:31]
	v_mfma_f32_32x32x16_bf16 v[16:31], v[96:99], v[116:119], v[16:31]
	s_and_saveexec_b64 s[48:49], vcc
	s_cbranch_execz .LBB0_717
	v_pk_add_f32 v[80:81], v[80:81], v[82:83]
	v_lshl_add_u32 v84, v206, 2, v178
	v_add_f32_e32 v80, v176, v80
	v_add_f32_e32 v80, v80, v81
	ds_write_b32 v84, v80
	s_branch .LBB0_717

; #define E_BLK _Pragma("unroll") for(int ai=0;ai<2;++ai) _Pragma("unroll") for(int m=0;m<4;++m) _Pragma("unroll") for(int bj=0;bj<2;++bj) _Pragma("unroll") for(int n=0;n<2;++n)
; __device__ __forceinline__ u32x2 pack4(f32x4 v) { return u32x2{cvtpk(v[0], v[1]), cvtpk(v[2], v[3])}; }
; template <int EPI, int nN, int lda, int ldb, int K, int ldc>
; __device__ __forceinline__ void gemm_phase(const Params& p, const u16* __restrict__ A, const u16* __restrict__ Bt, u16* C, u16* shm, int wave_s) {
;     ...
;     } else if constexpr (EPI == EPI_RELU2) {
;       const float* rs = (const float*)((const char*)shm + SMEM_BYTES + 16);
;       E_BLK { const float r_ = rs[trow + E_R]; f32x4 v = acc[ai][bj][m][n] * r_;
;         v = f32x4{fmaxf(v[0], 0.f), fmaxf(v[1], 0.f), fmaxf(v[2], 0.f), fmaxf(v[3], 0.f)};
;         stg_w<256>(stg, trow + E_R, tcol + E_C, pack4(v * v)); }
;       stage_store<256>(stg, C + (size_t)brow * 4096 + bcol, 4096, tid);
.LBB0_925:
	s_or_b64 exec, exec, s[40:41]
	v_ashrrev_i32_e32 v128, 2, v144
	v_and_or_b32 v131, v128, s64, v146
	v_lshrrev_b32_e32 v128, 2, v143
	v_and_b32_e32 v133, 8, v128
	v_lshl_add_u32 v128, v131, 2, v141
	ds_read_b32 v248, v128
	ds_read_b32 v249, v128 offset:64
	ds_read_b32 v250, v128 offset:128
	ds_read_b32 v251, v128 offset:192
	ds_read_b32 v252, v128 offset:512
	ds_read_b32 v253, v128 offset:576
	ds_read_b32 v254, v128 offset:640
	ds_read_b32 v255, v128 offset:704
	s_waitcnt lgkmcnt(0)
	v_mov_b32_e32 v132, v248
	v_lshrrev_b32_e32 v130, 1, v144
	v_and_or_b32 v134, v130, s65, v133
	v_lshrrev_b32_e32 v130, 1, v143
	v_and_b32_e32 v135, 8, v130
	v_pk_mul_f32 v[124:125], v[124:125], v[132:133] op_sel_hi:[1,0]
	v_pk_mul_f32 v[126:127], v[126:127], v[132:133] op_sel_hi:[1,0]
	v_max_f32_e32 v124, 0, v124
	v_max_f32_e32 v125, 0, v125
	v_pk_mul_f32 v[124:125], v[124:125], v[124:125]
	v_max_f32_e32 v126, 0, v126
	s_nop 0
	v_cvt_pk_bf16_f32 v132, v124, v125
	v_lshrrev_b32_e32 v125, 3, v134
	v_max_f32_e32 v127, 0, v127
	v_xor_b32_e32 v124, v125, v146
	v_lshl_or_b32 v130, v131, 9, v135
	v_pk_mul_f32 v[126:127], v[126:127], v[126:127]
	v_lshlrev_b32_e32 v124, 4, v124
	s_nop 0
	v_cvt_pk_bf16_f32 v133, v126, v127
	v_or_b32_e32 v126, v130, v124
	ds_write_b64 v126, v[132:133]
	v_mov_b32_e32 v126, v248
	s_lshl_b64 s[36:37], s[36:37], 13
	s_add_u32 s40, s6, s36
	s_addc_u32 s41, s7, s37
	s_lshl_b64 s[36:37], s[38:39], 1
	v_pk_mul_f32 v[120:121], v[120:121], v[126:127] op_sel_hi:[1,0]
	v_pk_mul_f32 v[122:123], v[122:123], v[126:127] op_sel_hi:[1,0]
	v_max_f32_e32 v120, 0, v120
	v_max_f32_e32 v121, 0, v121
	v_pk_mul_f32 v[120:121], v[120:121], v[120:121]
	v_max_f32_e32 v122, 0, v122
	s_nop 0
	v_cvt_pk_bf16_f32 v126, v120, v121
	v_bitop3_b32 v120, v125, v146, 2 bitop3:0x36
	v_lshlrev_b32_e32 v120, 4, v120
	v_max_f32_e32 v123, 0, v123
	v_or_b32_e32 v121, v130, v120
	v_pk_mul_f32 v[122:123], v[122:123], v[122:123]
	s_add_u32 s36, s40, s36
	s_nop 0
	v_cvt_pk_bf16_f32 v127, v122, v123
	ds_write_b64 v121, v[126:127]
	s_waitcnt vmcnt(0)
	v_mov_b32_e32 v122, v248
	s_addc_u32 s37, s41, s37
	v_pk_mul_f32 v[116:117], v[116:117], v[122:123] op_sel_hi:[1,0]
	s_nop 0
	v_max_f32_e32 v116, 0, v116
	v_max_f32_e32 v117, 0, v117
	v_pk_mul_f32 v[116:117], v[116:117], v[116:117]
	v_pk_mul_f32 v[118:119], v[118:119], v[122:123] op_sel_hi:[1,0]
	s_nop 0
	v_cvt_pk_bf16_f32 v122, v116, v117
	v_bitop3_b32 v116, v125, v146, 16 bitop3:0x36
	v_lshlrev_b32_e32 v116, 4, v116
	v_max_f32_e32 v118, 0, v118
	v_max_f32_e32 v119, 0, v119
	v_or_b32_e32 v117, v130, v116
	v_pk_mul_f32 v[118:119], v[118:119], v[118:119]
	s_nop 0
	s_nop 0
	v_cvt_pk_bf16_f32 v123, v118, v119
	ds_write_b64 v117, v[122:123]
	v_mov_b32_e32 v118, v248
	v_pk_mul_f32 v[112:113], v[112:113], v[118:119] op_sel_hi:[1,0]
	s_nop 0
	v_max_f32_e32 v112, 0, v112
	v_max_f32_e32 v113, 0, v113
	v_pk_mul_f32 v[112:113], v[112:113], v[112:113]
	v_pk_mul_f32 v[114:115], v[114:115], v[118:119] op_sel_hi:[1,0]
	s_nop 0
	v_cvt_pk_bf16_f32 v118, v112, v113
	v_bitop3_b32 v112, v125, v146, 18 bitop3:0x36
	v_lshlrev_b32_e32 v112, 4, v112
	v_max_f32_e32 v114, 0, v114
	v_max_f32_e32 v115, 0, v115
	v_or_b32_e32 v113, v130, v112
	v_pk_mul_f32 v[114:115], v[114:115], v[114:115]
	s_nop 0
	s_nop 0
	v_cvt_pk_bf16_f32 v119, v114, v115
	ds_write_b64 v113, v[118:119]
	v_or_b32_e32 v113, 16, v131
	v_lshl_add_u32 v117, v113, 2, v141
	v_mov_b32_e32 v114, v249
	v_lshl_or_b32 v113, v113, 9, v135
	v_pk_mul_f32 v[108:109], v[108:109], v[114:115] op_sel_hi:[1,0]
	s_nop 0
	v_max_f32_e32 v108, 0, v108
	v_max_f32_e32 v109, 0, v109
	v_pk_mul_f32 v[108:109], v[108:109], v[108:109]
	v_pk_mul_f32 v[110:111], v[110:111], v[114:115] op_sel_hi:[1,0]
	s_nop 0
	v_cvt_pk_bf16_f32 v114, v108, v109
	v_bitop3_b32 v108, v125, v146, 16 bitop3:0x1e
	v_lshlrev_b32_e32 v108, 4, v108
	v_max_f32_e32 v110, 0, v110
	v_max_f32_e32 v111, 0, v111
	v_or_b32_e32 v109, v113, v108
	v_pk_mul_f32 v[110:111], v[110:111], v[110:111]
	s_nop 0
	s_nop 0
	v_cvt_pk_bf16_f32 v115, v110, v111
	ds_write_b64 v109, v[114:115]
	v_mov_b32_e32 v110, v249
	v_or_b32_e32 v109, 16, v146
	v_pk_mul_f32 v[104:105], v[104:105], v[110:111] op_sel_hi:[1,0]
	s_nop 0
	v_max_f32_e32 v104, 0, v104
	v_max_f32_e32 v105, 0, v105
	v_pk_mul_f32 v[104:105], v[104:105], v[104:105]
	v_pk_mul_f32 v[106:107], v[106:107], v[110:111] op_sel_hi:[1,0]
	s_nop 0
	v_cvt_pk_bf16_f32 v110, v104, v105
	v_bitop3_b32 v104, v125, v109, 2 bitop3:0x36
	v_lshlrev_b32_e32 v104, 4, v104
	v_max_f32_e32 v106, 0, v106
	v_max_f32_e32 v107, 0, v107
	v_or_b32_e32 v105, v113, v104
	v_pk_mul_f32 v[106:107], v[106:107], v[106:107]
	s_nop 0
	s_nop 0
	v_cvt_pk_bf16_f32 v111, v106, v107
	ds_write_b64 v105, v[110:111]
	v_mov_b32_e32 v106, v249
	v_pk_mul_f32 v[100:101], v[100:101], v[106:107] op_sel_hi:[1,0]
	s_nop 0
	v_max_f32_e32 v100, 0, v100
	v_max_f32_e32 v101, 0, v101
	v_pk_mul_f32 v[100:101], v[100:101], v[100:101]
	v_pk_mul_f32 v[102:103], v[102:103], v[106:107] op_sel_hi:[1,0]
	s_nop 0
	v_cvt_pk_bf16_f32 v106, v100, v101
	v_bitop3_b32 v100, v125, v146, 16 bitop3:0x14
	v_lshlrev_b32_e32 v100, 4, v100
	v_max_f32_e32 v102, 0, v102
	v_max_f32_e32 v103, 0, v103
	v_or_b32_e32 v101, v113, v100
	v_pk_mul_f32 v[102:103], v[102:103], v[102:103]
	s_nop 0
	s_nop 0
	v_cvt_pk_bf16_f32 v107, v102, v103
	ds_write_b64 v101, v[106:107]
	v_mov_b32_e32 v102, v249
	v_pk_mul_f32 v[96:97], v[96:97], v[102:103] op_sel_hi:[1,0]
	s_nop 0
	v_max_f32_e32 v96, 0, v96
	v_max_f32_e32 v97, 0, v97
	v_pk_mul_f32 v[96:97], v[96:97], v[96:97]
	v_pk_mul_f32 v[98:99], v[98:99], v[102:103] op_sel_hi:[1,0]
	s_nop 0
	v_cvt_pk_bf16_f32 v102, v96, v97
	v_bitop3_b32 v96, v125, v109, 18 bitop3:0x36
; #define E_BLK _Pragma("unroll") for(int ai=0;ai<2;++ai) _Pragma("unroll") for(int m=0;m<4;++m) _Pragma("unroll") for(int bj=0;bj<2;++bj) _Pragma("unroll") for(int n=0;n<2;++n)
; __device__ __forceinline__ u32x2 pack4(f32x4 v) { return u32x2{cvtpk(v[0], v[1]), cvtpk(v[2], v[3])}; }
; template <int EPI, int nN, int lda, int ldb, int K, int ldc>
; __device__ __forceinline__ void gemm_phase(const Params& p, const u16* __restrict__ A, const u16* __restrict__ Bt, u16* C, u16* shm, int wave_s) {
;     ...
;       E_BLK { const float r_ = rs[trow + E_R]; f32x4 v = acc[ai][bj][m][n] * r_;
;         v = f32x4{fmaxf(v[0], 0.f), fmaxf(v[1], 0.f), fmaxf(v[2], 0.f), fmaxf(v[3], 0.f)};
;         stg_w<256>(stg, trow + E_R, tcol + E_C, pack4(v * v)); }
	v_lshlrev_b32_e32 v96, 4, v96
	v_max_f32_e32 v98, 0, v98
	v_max_f32_e32 v99, 0, v99
	v_or_b32_e32 v97, v113, v96
	v_pk_mul_f32 v[98:99], v[98:99], v[98:99]
	s_nop 0
	s_nop 0
	v_cvt_pk_bf16_f32 v103, v98, v99
	ds_write_b64 v97, v[102:103]
	v_or_b32_e32 v97, 32, v131
	v_lshl_add_u32 v99, v97, 2, v141
	v_mov_b32_e32 v98, v250
	v_lshl_or_b32 v97, v97, 9, v135
	v_pk_mul_f32 v[94:95], v[94:95], v[98:99] op_sel_hi:[1,0]
	v_pk_mul_f32 v[92:93], v[92:93], v[98:99] op_sel_hi:[1,0]
	v_max_f32_e32 v94, 0, v94
	v_max_f32_e32 v92, 0, v92
	v_max_f32_e32 v93, 0, v93
	v_max_f32_e32 v95, 0, v95
	v_pk_mul_f32 v[94:95], v[94:95], v[94:95]
	v_pk_mul_f32 v[92:93], v[92:93], v[92:93]
	s_nop 0
	s_nop 0
	v_cvt_pk_bf16_f32 v92, v92, v93
	s_nop 0
	v_cvt_pk_bf16_f32 v93, v94, v95
	v_or_b32_e32 v94, v97, v124
	ds_write_b64 v94, v[92:93]
	v_mov_b32_e32 v92, v250
	v_pk_mul_f32 v[90:91], v[90:91], v[92:93] op_sel_hi:[1,0]
	v_pk_mul_f32 v[88:89], v[88:89], v[92:93] op_sel_hi:[1,0]
	v_max_f32_e32 v90, 0, v90
	v_max_f32_e32 v88, 0, v88
	v_max_f32_e32 v89, 0, v89
	v_max_f32_e32 v91, 0, v91
	v_pk_mul_f32 v[90:91], v[90:91], v[90:91]
	v_pk_mul_f32 v[88:89], v[88:89], v[88:89]
	s_nop 0
	s_nop 0
	v_cvt_pk_bf16_f32 v88, v88, v89
	s_nop 0
	v_cvt_pk_bf16_f32 v89, v90, v91
	v_or_b32_e32 v90, v97, v120
	ds_write_b64 v90, v[88:89]
	v_mov_b32_e32 v88, v250
	v_pk_mul_f32 v[86:87], v[86:87], v[88:89] op_sel_hi:[1,0]
	v_pk_mul_f32 v[84:85], v[84:85], v[88:89] op_sel_hi:[1,0]
	v_max_f32_e32 v86, 0, v86
	v_max_f32_e32 v84, 0, v84
	v_max_f32_e32 v85, 0, v85
	v_max_f32_e32 v87, 0, v87
	v_pk_mul_f32 v[86:87], v[86:87], v[86:87]
	v_pk_mul_f32 v[84:85], v[84:85], v[84:85]
	s_nop 0
	s_nop 0
	v_cvt_pk_bf16_f32 v84, v84, v85
	s_nop 0
	v_cvt_pk_bf16_f32 v85, v86, v87
	v_or_b32_e32 v86, v97, v116
	ds_write_b64 v86, v[84:85]
	v_mov_b32_e32 v84, v250
	v_pk_mul_f32 v[82:83], v[82:83], v[84:85] op_sel_hi:[1,0]
	v_pk_mul_f32 v[80:81], v[80:81], v[84:85] op_sel_hi:[1,0]
	v_max_f32_e32 v82, 0, v82
	v_max_f32_e32 v80, 0, v80
	v_max_f32_e32 v81, 0, v81
	v_max_f32_e32 v83, 0, v83
	v_pk_mul_f32 v[82:83], v[82:83], v[82:83]
	v_pk_mul_f32 v[80:81], v[80:81], v[80:81]
	s_nop 0
	s_nop 0
	v_cvt_pk_bf16_f32 v80, v80, v81
	s_nop 0
	v_cvt_pk_bf16_f32 v81, v82, v83
	v_or_b32_e32 v82, v97, v112
	ds_write_b64 v82, v[80:81]
	v_or_b32_e32 v81, 48, v131
	v_lshl_add_u32 v82, v81, 2, v141
	v_mov_b32_e32 v80, v251
	v_lshl_or_b32 v81, v81, 9, v135
	v_pk_mul_f32 v[78:79], v[78:79], v[80:81] op_sel_hi:[1,0]
	v_pk_mul_f32 v[76:77], v[76:77], v[80:81] op_sel_hi:[1,0]
	v_max_f32_e32 v78, 0, v78
	v_max_f32_e32 v76, 0, v76
	v_max_f32_e32 v77, 0, v77
	v_max_f32_e32 v79, 0, v79
	v_pk_mul_f32 v[78:79], v[78:79], v[78:79]
	v_pk_mul_f32 v[76:77], v[76:77], v[76:77]
	s_nop 0
	s_nop 0
	v_cvt_pk_bf16_f32 v76, v76, v77
	s_nop 0
	v_cvt_pk_bf16_f32 v77, v78, v79
	v_or_b32_e32 v78, v81, v108
	ds_write_b64 v78, v[76:77]
	v_mov_b32_e32 v76, v251
	v_pk_mul_f32 v[74:75], v[74:75], v[76:77] op_sel_hi:[1,0]
	v_pk_mul_f32 v[72:73], v[72:73], v[76:77] op_sel_hi:[1,0]
	v_max_f32_e32 v74, 0, v74
	v_max_f32_e32 v72, 0, v72
	v_max_f32_e32 v73, 0, v73
	v_max_f32_e32 v75, 0, v75
	v_pk_mul_f32 v[74:75], v[74:75], v[74:75]
	v_pk_mul_f32 v[72:73], v[72:73], v[72:73]
	s_nop 0
	s_nop 0
	v_cvt_pk_bf16_f32 v72, v72, v73
	s_nop 0
	v_cvt_pk_bf16_f32 v73, v74, v75
	v_or_b32_e32 v74, v81, v104
	ds_write_b64 v74, v[72:73]
	v_mov_b32_e32 v72, v251
	v_pk_mul_f32 v[70:71], v[70:71], v[72:73] op_sel_hi:[1,0]
	v_pk_mul_f32 v[68:69], v[68:69], v[72:73] op_sel_hi:[1,0]
	v_max_f32_e32 v70, 0, v70
	v_max_f32_e32 v68, 0, v68
	v_max_f32_e32 v69, 0, v69
	v_max_f32_e32 v71, 0, v71
	v_pk_mul_f32 v[70:71], v[70:71], v[70:71]
	v_pk_mul_f32 v[68:69], v[68:69], v[68:69]
	s_nop 0
	s_nop 0
	v_cvt_pk_bf16_f32 v68, v68, v69
	s_nop 0
	v_cvt_pk_bf16_f32 v69, v70, v71
	v_or_b32_e32 v70, v81, v100
	ds_write_b64 v70, v[68:69]
	v_mov_b32_e32 v68, v251
	v_pk_mul_f32 v[66:67], v[66:67], v[68:69] op_sel_hi:[1,0]
	v_pk_mul_f32 v[64:65], v[64:65], v[68:69] op_sel_hi:[1,0]
	v_max_f32_e32 v66, 0, v66
	v_max_f32_e32 v64, 0, v64
	v_max_f32_e32 v65, 0, v65
	v_max_f32_e32 v67, 0, v67
	v_pk_mul_f32 v[66:67], v[66:67], v[66:67]
	v_pk_mul_f32 v[64:65], v[64:65], v[64:65]
	s_nop 0
	s_nop 0
	v_cvt_pk_bf16_f32 v64, v64, v65
	s_nop 0
	v_cvt_pk_bf16_f32 v65, v66, v67
	v_or_b32_e32 v66, v81, v96
	ds_write_b64 v66, v[64:65]
	v_mov_b32_e32 v64, v252
	v_add_u32_e32 v65, 0x10000, v130
	v_pk_mul_f32 v[62:63], v[62:63], v[64:65] op_sel_hi:[1,0]
	v_pk_mul_f32 v[60:61], v[60:61], v[64:65] op_sel_hi:[1,0]
	v_max_f32_e32 v62, 0, v62
	v_max_f32_e32 v60, 0, v60
	v_max_f32_e32 v61, 0, v61
	v_max_f32_e32 v63, 0, v63
	v_pk_mul_f32 v[62:63], v[62:63], v[62:63]
	v_pk_mul_f32 v[60:61], v[60:61], v[60:61]
	s_nop 0
	s_nop 0
	v_cvt_pk_bf16_f32 v60, v60, v61
	s_nop 0
	v_cvt_pk_bf16_f32 v61, v62, v63
	v_or_b32_e32 v62, v65, v124
	ds_write_b64 v62, v[60:61]
	v_mov_b32_e32 v60, v252
	v_pk_mul_f32 v[58:59], v[58:59], v[60:61] op_sel_hi:[1,0]
	v_pk_mul_f32 v[56:57], v[56:57], v[60:61] op_sel_hi:[1,0]
	v_max_f32_e32 v58, 0, v58
	v_max_f32_e32 v56, 0, v56
	v_max_f32_e32 v57, 0, v57
	v_max_f32_e32 v59, 0, v59
	v_pk_mul_f32 v[58:59], v[58:59], v[58:59]
	v_pk_mul_f32 v[56:57], v[56:57], v[56:57]
	s_nop 0
	s_nop 0
	v_cvt_pk_bf16_f32 v56, v56, v57
	s_nop 0
	v_cvt_pk_bf16_f32 v57, v58, v59
	v_or_b32_e32 v58, v65, v120
	ds_write_b64 v58, v[56:57]
	v_mov_b32_e32 v56, v252
	v_pk_mul_f32 v[54:55], v[54:55], v[56:57] op_sel_hi:[1,0]
	v_pk_mul_f32 v[52:53], v[52:53], v[56:57] op_sel_hi:[1,0]
	v_max_f32_e32 v54, 0, v54
	v_max_f32_e32 v52, 0, v52
	v_max_f32_e32 v53, 0, v53
	v_max_f32_e32 v55, 0, v55
	v_pk_mul_f32 v[54:55], v[54:55], v[54:55]
; #define E_BLK _Pragma("unroll") for(int ai=0;ai<2;++ai) _Pragma("unroll") for(int m=0;m<4;++m) _Pragma("unroll") for(int bj=0;bj<2;++bj) _Pragma("unroll") for(int n=0;n<2;++n)
; __device__ __forceinline__ u32x2 pack4(f32x4 v) { return u32x2{cvtpk(v[0], v[1]), cvtpk(v[2], v[3])}; }
; template <int NC> __device__ __forceinline__ void stage_store(const char* stg, u16* dst, int ld, int tid) {
;   constexpr int CH = NC / 8, RPI = 512 / CH;
;   __syncthreads();
;   const int j = tid & (CH - 1), r0 = tid / CH;
; #pragma unroll
;   for (int i = 0; i < 256 / RPI; ++i) { const int r = i * RPI + r0;
;     __builtin_nontemporal_store(stg_r<NC>(stg, r, j), reinterpret_cast<u32x4*>(dst + (unsigned)(r * ld + j * 8))); }
;   __syncthreads();
; template <int EPI, int nN, int lda, int ldb, int K, int ldc>
; __device__ __forceinline__ void gemm_phase(const Params& p, const u16* __restrict__ A, const u16* __restrict__ Bt, u16* C, u16* shm, int wave_s) {
;     ...
;       E_BLK { const float r_ = rs[trow + E_R]; f32x4 v = acc[ai][bj][m][n] * r_;
;         v = f32x4{fmaxf(v[0], 0.f), fmaxf(v[1], 0.f), fmaxf(v[2], 0.f), fmaxf(v[3], 0.f)};
;         stg_w<256>(stg, trow + E_R, tcol + E_C, pack4(v * v)); }
;       stage_store<256>(stg, C + (size_t)brow * 4096 + bcol, 4096, tid);
	v_pk_mul_f32 v[52:53], v[52:53], v[52:53]
	s_nop 0
	s_nop 0
	v_cvt_pk_bf16_f32 v52, v52, v53
	s_nop 0
	v_cvt_pk_bf16_f32 v53, v54, v55
	v_or_b32_e32 v54, v65, v116
	ds_write_b64 v54, v[52:53]
	v_mov_b32_e32 v52, v252
	v_pk_mul_f32 v[50:51], v[50:51], v[52:53] op_sel_hi:[1,0]
	v_pk_mul_f32 v[48:49], v[48:49], v[52:53] op_sel_hi:[1,0]
	v_max_f32_e32 v50, 0, v50
	v_max_f32_e32 v48, 0, v48
	v_max_f32_e32 v49, 0, v49
	v_max_f32_e32 v51, 0, v51
	v_pk_mul_f32 v[50:51], v[50:51], v[50:51]
	v_pk_mul_f32 v[48:49], v[48:49], v[48:49]
	s_nop 0
	s_nop 0
	v_cvt_pk_bf16_f32 v48, v48, v49
	s_nop 0
	v_cvt_pk_bf16_f32 v49, v50, v51
	v_or_b32_e32 v50, v65, v112
	ds_write_b64 v50, v[48:49]
	v_mov_b32_e32 v48, v253
	v_add_u32_e32 v49, 0x12000, v130
	v_pk_mul_f32 v[46:47], v[46:47], v[48:49] op_sel_hi:[1,0]
	v_pk_mul_f32 v[44:45], v[44:45], v[48:49] op_sel_hi:[1,0]
	v_max_f32_e32 v46, 0, v46
	v_max_f32_e32 v44, 0, v44
	v_max_f32_e32 v45, 0, v45
	v_max_f32_e32 v47, 0, v47
	v_pk_mul_f32 v[46:47], v[46:47], v[46:47]
	v_pk_mul_f32 v[44:45], v[44:45], v[44:45]
	s_nop 0
	s_nop 0
	v_cvt_pk_bf16_f32 v44, v44, v45
	s_nop 0
	v_cvt_pk_bf16_f32 v45, v46, v47
	v_or_b32_e32 v46, v49, v108
	ds_write_b64 v46, v[44:45]
	v_mov_b32_e32 v44, v253
	v_pk_mul_f32 v[42:43], v[42:43], v[44:45] op_sel_hi:[1,0]
	v_pk_mul_f32 v[40:41], v[40:41], v[44:45] op_sel_hi:[1,0]
	v_max_f32_e32 v42, 0, v42
	v_max_f32_e32 v40, 0, v40
	v_max_f32_e32 v41, 0, v41
	v_max_f32_e32 v43, 0, v43
	v_pk_mul_f32 v[42:43], v[42:43], v[42:43]
	v_pk_mul_f32 v[40:41], v[40:41], v[40:41]
	s_nop 0
	s_nop 0
	v_cvt_pk_bf16_f32 v40, v40, v41
	s_nop 0
	v_cvt_pk_bf16_f32 v41, v42, v43
	v_or_b32_e32 v42, v49, v104
	ds_write_b64 v42, v[40:41]
	v_mov_b32_e32 v40, v253
	v_pk_mul_f32 v[38:39], v[38:39], v[40:41] op_sel_hi:[1,0]
	v_pk_mul_f32 v[36:37], v[36:37], v[40:41] op_sel_hi:[1,0]
	v_max_f32_e32 v38, 0, v38
	v_max_f32_e32 v36, 0, v36
	v_max_f32_e32 v37, 0, v37
	v_max_f32_e32 v39, 0, v39
	v_pk_mul_f32 v[38:39], v[38:39], v[38:39]
	v_pk_mul_f32 v[36:37], v[36:37], v[36:37]
	s_nop 0
	s_nop 0
	v_cvt_pk_bf16_f32 v36, v36, v37
	s_nop 0
	v_cvt_pk_bf16_f32 v37, v38, v39
	v_or_b32_e32 v38, v49, v100
	ds_write_b64 v38, v[36:37]
	v_mov_b32_e32 v36, v253
	v_pk_mul_f32 v[34:35], v[34:35], v[36:37] op_sel_hi:[1,0]
	v_pk_mul_f32 v[32:33], v[32:33], v[36:37] op_sel_hi:[1,0]
	v_max_f32_e32 v34, 0, v34
	v_max_f32_e32 v32, 0, v32
	v_max_f32_e32 v33, 0, v33
	v_max_f32_e32 v35, 0, v35
	v_pk_mul_f32 v[34:35], v[34:35], v[34:35]
	v_pk_mul_f32 v[32:33], v[32:33], v[32:33]
	s_nop 0
	s_nop 0
	v_cvt_pk_bf16_f32 v32, v32, v33
	s_nop 0
	v_cvt_pk_bf16_f32 v33, v34, v35
	v_or_b32_e32 v34, v49, v96
	ds_write_b64 v34, v[32:33]
	v_mov_b32_e32 v32, v254
	v_add_u32_e32 v33, 0x14000, v130
	v_pk_mul_f32 v[30:31], v[30:31], v[32:33] op_sel_hi:[1,0]
	v_pk_mul_f32 v[28:29], v[28:29], v[32:33] op_sel_hi:[1,0]
	v_max_f32_e32 v30, 0, v30
	v_max_f32_e32 v28, 0, v28
	v_max_f32_e32 v29, 0, v29
	v_max_f32_e32 v31, 0, v31
	v_pk_mul_f32 v[30:31], v[30:31], v[30:31]
	v_pk_mul_f32 v[28:29], v[28:29], v[28:29]
	s_nop 0
	s_nop 0
	v_cvt_pk_bf16_f32 v28, v28, v29
	s_nop 0
	v_cvt_pk_bf16_f32 v29, v30, v31
	v_or_b32_e32 v30, v33, v124
	ds_write_b64 v30, v[28:29]
	v_mov_b32_e32 v28, v254
	v_pk_mul_f32 v[26:27], v[26:27], v[28:29] op_sel_hi:[1,0]
	v_pk_mul_f32 v[24:25], v[24:25], v[28:29] op_sel_hi:[1,0]
	v_max_f32_e32 v26, 0, v26
	v_max_f32_e32 v24, 0, v24
	v_max_f32_e32 v25, 0, v25
	v_max_f32_e32 v27, 0, v27
	v_pk_mul_f32 v[26:27], v[26:27], v[26:27]
	v_pk_mul_f32 v[24:25], v[24:25], v[24:25]
	s_nop 0
	s_nop 0
	v_cvt_pk_bf16_f32 v24, v24, v25
	s_nop 0
	v_cvt_pk_bf16_f32 v25, v26, v27
	v_or_b32_e32 v26, v33, v120
	ds_write_b64 v26, v[24:25]
	v_mov_b32_e32 v24, v254
	v_pk_mul_f32 v[22:23], v[22:23], v[24:25] op_sel_hi:[1,0]
	v_pk_mul_f32 v[20:21], v[20:21], v[24:25] op_sel_hi:[1,0]
	v_max_f32_e32 v22, 0, v22
	v_max_f32_e32 v20, 0, v20
	v_max_f32_e32 v21, 0, v21
	v_max_f32_e32 v23, 0, v23
	v_pk_mul_f32 v[22:23], v[22:23], v[22:23]
	v_pk_mul_f32 v[20:21], v[20:21], v[20:21]
	s_nop 0
	s_nop 0
	v_cvt_pk_bf16_f32 v20, v20, v21
	s_nop 0
	v_cvt_pk_bf16_f32 v21, v22, v23
	v_or_b32_e32 v22, v33, v116
	ds_write_b64 v22, v[20:21]
	v_mov_b32_e32 v20, v254
	v_pk_mul_f32 v[18:19], v[18:19], v[20:21] op_sel_hi:[1,0]
	v_pk_mul_f32 v[16:17], v[16:17], v[20:21] op_sel_hi:[1,0]
	v_max_f32_e32 v18, 0, v18
	v_max_f32_e32 v16, 0, v16
	v_max_f32_e32 v17, 0, v17
	v_max_f32_e32 v19, 0, v19
	v_pk_mul_f32 v[18:19], v[18:19], v[18:19]
	v_pk_mul_f32 v[16:17], v[16:17], v[16:17]
	s_nop 0
	s_nop 0
	v_cvt_pk_bf16_f32 v16, v16, v17
	s_nop 0
	v_cvt_pk_bf16_f32 v17, v18, v19
	v_or_b32_e32 v18, v33, v112
	ds_write_b64 v18, v[16:17]
	v_mov_b32_e32 v16, v255
	v_add_u32_e32 v17, 0x16000, v130
	v_pk_mul_f32 v[14:15], v[14:15], v[16:17] op_sel_hi:[1,0]
	v_pk_mul_f32 v[12:13], v[12:13], v[16:17] op_sel_hi:[1,0]
	v_max_f32_e32 v14, 0, v14
	v_max_f32_e32 v12, 0, v12
	v_max_f32_e32 v13, 0, v13
	v_max_f32_e32 v15, 0, v15
	v_pk_mul_f32 v[14:15], v[14:15], v[14:15]
	v_pk_mul_f32 v[12:13], v[12:13], v[12:13]
	s_nop 0
	s_nop 0
	v_cvt_pk_bf16_f32 v12, v12, v13
	s_nop 0
	v_cvt_pk_bf16_f32 v13, v14, v15
	v_or_b32_e32 v14, v17, v108
	ds_write_b64 v14, v[12:13]
	v_mov_b32_e32 v12, v255
	v_pk_mul_f32 v[10:11], v[10:11], v[12:13] op_sel_hi:[1,0]
	v_pk_mul_f32 v[8:9], v[8:9], v[12:13] op_sel_hi:[1,0]
	v_max_f32_e32 v10, 0, v10
	v_max_f32_e32 v8, 0, v8
	v_max_f32_e32 v9, 0, v9
	v_max_f32_e32 v11, 0, v11
	v_pk_mul_f32 v[10:11], v[10:11], v[10:11]
	v_pk_mul_f32 v[8:9], v[8:9], v[8:9]
	s_nop 0
	s_nop 0
	v_cvt_pk_bf16_f32 v8, v8, v9
	s_nop 0
	v_cvt_pk_bf16_f32 v9, v10, v11
	v_or_b32_e32 v10, v17, v104
	ds_write_b64 v10, v[8:9]
	v_mov_b32_e32 v8, v255
	v_pk_mul_f32 v[6:7], v[6:7], v[8:9] op_sel_hi:[1,0]
	v_pk_mul_f32 v[4:5], v[4:5], v[8:9] op_sel_hi:[1,0]
	v_max_f32_e32 v6, 0, v6
	v_max_f32_e32 v4, 0, v4
	v_max_f32_e32 v5, 0, v5
	v_max_f32_e32 v7, 0, v7
	v_pk_mul_f32 v[6:7], v[6:7], v[6:7]
	v_pk_mul_f32 v[4:5], v[4:5], v[4:5]
	s_nop 0
	s_nop 0
	v_cvt_pk_bf16_f32 v4, v4, v5
	s_nop 0
	v_cvt_pk_bf16_f32 v5, v6, v7
	v_or_b32_e32 v6, v17, v100
	ds_write_b64 v6, v[4:5]
	v_mov_b32_e32 v4, v255
	v_pk_mul_f32 v[2:3], v[2:3], v[4:5] op_sel_hi:[1,0]
	v_pk_mul_f32 v[0:1], v[0:1], v[4:5] op_sel_hi:[1,0]
	v_max_f32_e32 v2, 0, v2
	v_max_f32_e32 v0, 0, v0
	v_max_f32_e32 v1, 0, v1
	v_max_f32_e32 v3, 0, v3
	v_pk_mul_f32 v[2:3], v[2:3], v[2:3]
	v_pk_mul_f32 v[0:1], v[0:1], v[0:1]
	s_nop 0
	s_nop 0
	v_cvt_pk_bf16_f32 v0, v0, v1
	s_nop 0
	v_cvt_pk_bf16_f32 v1, v2, v3
	v_or_b32_e32 v2, v17, v96
	ds_write_b64 v2, v[0:1]
	v_lshrrev_b32_e32 v0, 27, v145
	v_add_u32_e32 v0, v144, v0
	v_ashrrev_i32_e32 v10, 5, v0
	v_lshlrev_b32_e32 v0, 3, v143
	v_and_b32_e32 v11, 0xf8, v0
	v_xor_b32_e32 v0, v10, v143
	v_add_u32_e32 v13, 16, v10
	v_lshlrev_b32_e32 v0, 4, v0
	v_xor_b32_e32 v4, v13, v143
	v_and_b32_e32 v12, 0x1f0, v0
	v_lshlrev_b32_e32 v4, 4, v4
	v_lshl_or_b32 v0, v10, 9, v12
	v_and_b32_e32 v4, 0x1f0, v4
	s_waitcnt lgkmcnt(0)
	s_barrier
; template <int NC> __device__ __forceinline__ void stage_store(const char* stg, u16* dst, int ld, int tid) {
;   constexpr int CH = NC / 8, RPI = 512 / CH;
;   __syncthreads();
;   const int j = tid & (CH - 1), r0 = tid / CH;
; #pragma unroll
;   for (int i = 0; i < 256 / RPI; ++i) { const int r = i * RPI + r0;
;     __builtin_nontemporal_store(stg_r<NC>(stg, r, j), reinterpret_cast<u32x4*>(dst + (unsigned)(r * ld + j * 8))); }
;   __syncthreads();
; template <int EPI, int nN, int lda, int ldb, int K, int ldc>
; __device__ __forceinline__ void gemm_phase(const Params& p, const u16* __restrict__ A, const u16* __restrict__ Bt, u16* C, u16* shm, int wave_s) {
;     ...
;   for (int tile = blockIdx.x; tile < nwg; tile += NBLK) {
;     const int tid = get_tid(wave_s);
;     const int wid = tid >> 6, lane = tid & 63, wr = wid >> 2, wc = wid & 3, fr = lane & 15, fq = lane >> 4;
;     const int trow = wr * 64 + fr, tcol = wc * 32 + fq * 4;
;     int pm, pn; tile_map(tile, nM, nN, pm, pn);
;     pm = __builtin_amdgcn_readfirstlane(pm); pn = __builtin_amdgcn_readfirstlane(pn);
;     const int brow = pm * BM, bcol = pn * BM;
;     f32x4 acc[2][2][4][2] = {};
;     if constexpr (EPI == EPI_RELU2) {
;       float* rs = (float*)((char*)shm + SMEM_BYTES + 16);
;       if (tid < 256) { const float4 q4 = *reinterpret_cast<const float4*>((const float*)(p.ws + OFF_PSQ) + (size_t)(brow + tid) * 4);
;         rs[tid] = rsqrtf((q4.x + q4.y + q4.z + q4.w) * (1.f / 1024.f) + EPS); }
	ds_read_b128 v[0:3], v0
	v_lshl_or_b32 v4, v13, 9, v4
	ds_read_b128 v[4:7], v4
	v_lshl_or_b32 v128, v10, 12, v11
	v_lshl_add_u64 v[8:9], v[128:129], 1, s[36:37]
	v_lshl_or_b32 v128, v13, 12, v11
	s_waitcnt lgkmcnt(1)
	global_store_dwordx4 v[8:9], v[0:3], off nt
	v_add_u32_e32 v13, 48, v10
	s_nop 0
	v_lshl_add_u64 v[0:1], v[128:129], 1, s[36:37]
	s_waitcnt lgkmcnt(0)
	global_store_dwordx4 v[0:1], v[4:7], off nt
	s_nop 1
	v_add_u32_e32 v4, 32, v10
	v_lshl_or_b32 v0, v4, 9, v12
	v_lshl_or_b32 v128, v4, 12, v11
	v_xor_b32_e32 v4, v13, v143
	v_lshlrev_b32_e32 v4, 4, v4
	v_and_b32_e32 v4, 0x1f0, v4
	ds_read_b128 v[0:3], v0
	v_lshl_or_b32 v4, v13, 9, v4
	ds_read_b128 v[4:7], v4
	v_lshl_add_u64 v[8:9], v[128:129], 1, s[36:37]
	v_lshl_or_b32 v128, v13, 12, v11
	s_waitcnt lgkmcnt(1)
	global_store_dwordx4 v[8:9], v[0:3], off nt
	v_add_u32_e32 v13, 0x50, v10
	s_nop 0
	v_lshl_add_u64 v[0:1], v[128:129], 1, s[36:37]
	s_waitcnt lgkmcnt(0)
	global_store_dwordx4 v[0:1], v[4:7], off nt
	s_nop 1
	v_add_u32_e32 v4, 64, v10
	v_lshl_or_b32 v0, v4, 9, v12
	v_lshl_or_b32 v128, v4, 12, v11
	v_xor_b32_e32 v4, v13, v143
	v_lshlrev_b32_e32 v4, 4, v4
	v_and_b32_e32 v4, 0x1f0, v4
	ds_read_b128 v[0:3], v0
	v_lshl_or_b32 v4, v13, 9, v4
	ds_read_b128 v[4:7], v4
	v_lshl_add_u64 v[8:9], v[128:129], 1, s[36:37]
	v_lshl_or_b32 v128, v13, 12, v11
	s_waitcnt lgkmcnt(1)
	global_store_dwordx4 v[8:9], v[0:3], off nt
	v_add_u32_e32 v13, 0x70, v10
	s_nop 0
	v_lshl_add_u64 v[0:1], v[128:129], 1, s[36:37]
	s_waitcnt lgkmcnt(0)
	global_store_dwordx4 v[0:1], v[4:7], off nt
	s_nop 1
	v_add_u32_e32 v4, 0x60, v10
	v_lshl_or_b32 v0, v4, 9, v12
	v_lshl_or_b32 v128, v4, 12, v11
	v_xor_b32_e32 v4, v13, v143
	v_lshlrev_b32_e32 v4, 4, v4
	v_and_b32_e32 v4, 0x1f0, v4
	ds_read_b128 v[0:3], v0
	v_lshl_or_b32 v4, v13, 9, v4
	ds_read_b128 v[4:7], v4
	v_lshl_add_u64 v[8:9], v[128:129], 1, s[36:37]
	v_lshl_or_b32 v128, v13, 12, v11
	s_waitcnt lgkmcnt(1)
	global_store_dwordx4 v[8:9], v[0:3], off nt
	v_add_u32_e32 v13, 0x90, v10
	s_nop 0
	v_lshl_add_u64 v[0:1], v[128:129], 1, s[36:37]
	s_waitcnt lgkmcnt(0)
	global_store_dwordx4 v[0:1], v[4:7], off nt
	s_nop 1
	v_add_u32_e32 v4, 0x80, v10
	v_lshl_or_b32 v0, v4, 9, v12
	v_lshl_or_b32 v128, v4, 12, v11
	v_xor_b32_e32 v4, v13, v143
	v_lshlrev_b32_e32 v4, 4, v4
	v_and_b32_e32 v4, 0x1f0, v4
	ds_read_b128 v[0:3], v0
	v_lshl_or_b32 v4, v13, 9, v4
	ds_read_b128 v[4:7], v4
	v_lshl_add_u64 v[8:9], v[128:129], 1, s[36:37]
	v_lshl_or_b32 v128, v13, 12, v11
	s_waitcnt lgkmcnt(1)
	global_store_dwordx4 v[8:9], v[0:3], off nt
	v_add_u32_e32 v13, 0xb0, v10
	s_nop 0
	v_lshl_add_u64 v[0:1], v[128:129], 1, s[36:37]
	s_waitcnt lgkmcnt(0)
	global_store_dwordx4 v[0:1], v[4:7], off nt
	s_nop 1
	v_add_u32_e32 v4, 0xa0, v10
	v_lshl_or_b32 v0, v4, 9, v12
	v_lshl_or_b32 v128, v4, 12, v11
	v_xor_b32_e32 v4, v13, v143
	v_lshlrev_b32_e32 v4, 4, v4
	v_and_b32_e32 v4, 0x1f0, v4
	ds_read_b128 v[0:3], v0
	v_lshl_or_b32 v4, v13, 9, v4
	ds_read_b128 v[4:7], v4
	v_lshl_add_u64 v[8:9], v[128:129], 1, s[36:37]
	v_lshl_or_b32 v128, v13, 12, v11
	s_waitcnt lgkmcnt(1)
	global_store_dwordx4 v[8:9], v[0:3], off nt
	v_add_u32_e32 v13, 0xd0, v10
	s_nop 0
	v_lshl_add_u64 v[0:1], v[128:129], 1, s[36:37]
	s_waitcnt lgkmcnt(0)
	global_store_dwordx4 v[0:1], v[4:7], off nt
	s_nop 1
	v_add_u32_e32 v4, 0xc0, v10
	v_lshl_or_b32 v0, v4, 9, v12
	v_lshl_or_b32 v128, v4, 12, v11
	v_xor_b32_e32 v4, v13, v143
	v_lshlrev_b32_e32 v4, 4, v4
	v_and_b32_e32 v4, 0x1f0, v4
	ds_read_b128 v[0:3], v0
	v_lshl_or_b32 v4, v13, 9, v4
	ds_read_b128 v[4:7], v4
	v_lshl_add_u64 v[8:9], v[128:129], 1, s[36:37]
	v_lshl_or_b32 v128, v13, 12, v11
	s_waitcnt lgkmcnt(1)
	global_store_dwordx4 v[8:9], v[0:3], off nt
	s_nop 1
	v_lshl_add_u64 v[0:1], v[128:129], 1, s[36:37]
	s_waitcnt lgkmcnt(0)
	global_store_dwordx4 v[0:1], v[4:7], off nt
	s_nop 1
	v_add_u32_e32 v4, 0xe0, v10
	v_add_u32_e32 v10, 0xf0, v10
	v_lshl_or_b32 v0, v4, 9, v12
	v_lshl_or_b32 v128, v4, 12, v11
	v_xor_b32_e32 v4, v10, v143
	v_lshlrev_b32_e32 v4, 4, v4
	ds_read_b128 v[0:3], v0
	v_and_b32_e32 v4, 0x1f0, v4
	v_lshl_or_b32 v4, v10, 9, v4
	ds_read_b128 v[4:7], v4
	v_lshl_add_u64 v[8:9], v[128:129], 1, s[36:37]
	v_lshl_or_b32 v128, v10, 12, v11
	s_waitcnt lgkmcnt(1)
	global_store_dwordx4 v[8:9], v[0:3], off nt
	s_nop 1
	v_lshl_add_u64 v[0:1], v[128:129], 1, s[36:37]
	s_add_i32 s36, s66, 0x100
	s_cmpk_lt_i32 s66, 0x1300
	s_mov_b32 s66, s36
	s_waitcnt lgkmcnt(0)
	global_store_dwordx4 v[0:1], v[4:7], off nt
	s_barrier
	s_cbranch_scc0 .LBB0_934
.LBB0_926:
	s_ashr_i32 s36, s66, 31
	s_lshr_b32 s36, s36, 29
	s_add_i32 s36, s66, s36
	s_ashr_i32 s37, s36, 3
	s_and_b32 s36, s36, -8
	s_sub_i32 s36, s66, s36
	s_lshr_b32 s38, s36, 31
	s_or_b32 s38, s38, 0x280
	s_mul_i32 s36, s38, s36
	s_add_i32 s36, s36, s37
	s_ashr_i32 s37, s36, 31
	s_lshr_b32 s37, s37, 25
	s_add_i32 s37, s36, s37
	s_ashr_i32 s38, s37, 7
	s_lshl_b32 s38, s38, 3
	s_sub_i32 s39, 0x140, s38
	s_min_u32 s39, s39, 8
	s_and_b32 s37, s37, 0xffffff80
	s_sub_i32 s40, s36, s37
	v_cvt_f32_ubyte0_e32 v1, s39
	v_cvt_f32_i32_e32 v0, s40
	v_rcp_iflag_f32_e32 v2, v1
	s_ashr_i32 s36, s40, 30
	s_or_b32 s41, s36, 1
	v_mbcnt_lo_u32_b32 v143, -1, 0
	v_mbcnt_hi_u32_b32 v143, -1, v143
	v_mul_f32_e32 v2, v0, v2
	v_trunc_f32_e32 v2, v2
	v_fma_f32 v0, -v2, v1, v0
	v_cvt_i32_f32_e32 v2, v2
	v_cmp_ge_f32_e64 s[36:37], |v0|, v1
	s_and_b64 s[36:37], s[36:37], exec
	s_cselect_b32 s36, s41, 0
	v_readfirstlane_b32 s37, v2
	s_add_i32 s36, s37, s36
	s_sext_i32_i8 s37, s36
	s_mul_i32 s36, s36, s39
	s_sub_i32 s36, s40, s36
	s_sext_i32_i8 s36, s36
	v_or_b32_e32 v144, s3, v143
	s_add_i32 s38, s38, s36
	s_lshl_b32 s36, s38, 8
	v_cmp_gt_i32_e32 vcc, s58, v144
	s_and_saveexec_b64 s[38:39], vcc
	s_cbranch_execz .LBB0_928
	v_add_u32_e32 v0, s36, v144
	v_ashrrev_i32_e32 v1, 31, v0
	v_lshl_add_u64 v[0:1], v[0:1], 4, s[4:5]
	global_load_dwordx4 v[246:249], v[0:1], off

; #define G_STAGE(P,BASE,LD,br,kt,VOFF) do{ const char* _sb=(const char*)(BASE)+((size_t)(br)*(size_t)(LD)+(size_t)(kt)*BK)*2; \
;     _Pragma("unroll") for(int _i=0;_i<2;++_i){ \
;       __builtin_amdgcn_global_load_lds((const unsigned*)(_sb+VOFF[_i]), \
;         (unsigned*)((char*)(P)+tid*16+_i*8192),16,0,0);} }while(0)
; #define G_LDA(dst,b,h) _Pragma("unroll") for(int m=0;m<4;++m) _Pragma("unroll") for(int k=0;k<2;++k) \
;     dst[m][k]=*reinterpret_cast<const bf16x8*>((char*)G_SA(b,h)+lds_byte(wr*64+m*16+fr,k*32+fq*8))
; #define G_LDB(dst,b,h) _Pragma("unroll") for(int n=0;n<2;++n) _Pragma("unroll") for(int k=0;k<2;++k) \
;     dst[n][k]=*reinterpret_cast<const bf16x8*>((char*)G_SB(b,h)+lds_byte(wc*32+n*16+fr,k*32+fq*8))
; #define G_MMA(ai,bj,At,Bx) do{__builtin_amdgcn_s_setprio(1); \
;     _Pragma("unroll") for(int m=0;m<4;++m) _Pragma("unroll") for(int n=0;n<2;++n) _Pragma("unroll") for(int k=0;k<2;++k) \
;       acc[ai][bj][m][n]=__builtin_amdgcn_mfma_f32_16x16x32_bf16(Bx[n][k],At[m][k],acc[ai][bj][m][n],0,0,0); \
;     __builtin_amdgcn_s_setprio(0);}while(0)
; #define WAIT_V(n) asm volatile("s_waitcnt vmcnt(" #n ")":::"memory")
; #define BAR __builtin_amdgcn_s_barrier()
; __device__ __forceinline__ void gemm_core(f32x4 (&acc)[2][2][4][2], const u16* __restrict__ A, int lda,
;                                           const u16* __restrict__ Bt, int ldb, int K, int brow, int bcol, u16* shm, int tid) {
;     ...
;   for(int t=0;t<nt-2;t+=2){
;     G_LDB(B0,0,0); SCHED; G_LDA(At,0,0); G_STAGE(G_SA(1,1),A,lda,brow+HALF,t+1,vA);
;     WAIT_L(8); BAR; WAIT_L(0); G_MMA(0,0,At,B0); BAR; SCHED;
;     G_LDB(B1,0,1); G_STAGE(G_SB(0,0),Bt,ldb,bcol,t+2,vB);
;     BAR; WAIT_L(0); G_MMA(0,1,At,B1); BAR;
;     G_LDA(At,0,1); G_STAGE(G_SA(0,0),A,lda,brow,t+2,vA);
;     BAR; WAIT_L(0); G_MMA(1,0,At,B0); BAR; SCHED;
;     G_STAGE(G_SB(0,1),Bt,ldb,bcol+HALF,t+2,vB);
;     WAIT_V(6); BAR; G_MMA(1,1,At,B1); BAR;
;     G_LDB(B0,1,0); SCHED; G_LDA(At,1,0); G_STAGE(G_SA(0,1),A,lda,brow+HALF,t+2,vA);
;     WAIT_L(8); BAR; WAIT_L(0); G_MMA(0,0,At,B0); BAR; SCHED;
;     G_LDB(B1,1,1); G_STAGE(G_SB(1,0),Bt,ldb,bcol,t+3,vB);
;     BAR; WAIT_L(0); G_MMA(0,1,At,B1); BAR;
;     G_LDA(At,1,1); G_STAGE(G_SA(1,0),A,lda,brow,t+3,vA);
;     BAR; WAIT_L(0); G_MMA(1,0,At,B0); BAR; SCHED;
;     G_STAGE(G_SB(1,1),Bt,ldb,bcol+HALF,t+3,vB);
;     WAIT_V(6); BAR; G_MMA(1,1,At,B1); BAR;
.LBB0_931:
	ds_read_b128 v[172:175], v170
	ds_read_b128 v[176:179], v170 offset:1024
	ds_read_b128 v[180:183], v170 offset:2048
	ds_read_b128 v[184:187], v170 offset:3072
	v_lshl_add_u64 v[236:237], s[42:43], 0, v[136:137]
	v_readfirstlane_b32 s45, v169
	v_lshl_add_u64 v[220:221], v[236:237], 0, s[10:11]
	s_mov_b32 m0, s45
	v_lshl_add_u64 v[238:239], s[42:43], 0, v[138:139]
	v_readfirstlane_b32 s45, v168
	ds_read_b128 v[188:191], v152
	ds_read_b128 v[192:195], v152 offset:1024
	ds_read_b128 v[196:199], v151
	ds_read_b128 v[200:203], v151 offset:1024
	ds_read_b128 v[204:207], v150
	ds_read_b128 v[208:211], v150 offset:1024
	ds_read_b128 v[212:215], v149
	ds_read_b128 v[216:219], v149 offset:1024
	global_load_lds_dwordx4 v[220:221], off
	v_lshl_add_u64 v[220:221], v[238:239], 0, s[10:11]
	s_mov_b32 m0, s45
	s_nop 0
	global_load_lds_dwordx4 v[220:221], off
	s_waitcnt lgkmcnt(8)
	s_barrier
	s_waitcnt lgkmcnt(0)
	s_setprio 1
	s_waitcnt lgkmcnt(0)
	v_mfma_f32_16x16x32_bf16 v[124:127], v[172:175], v[188:191], v[124:127]
	v_mfma_f32_16x16x32_bf16 v[120:123], v[180:183], v[188:191], v[120:123]
	v_mfma_f32_16x16x32_bf16 v[116:119], v[172:175], v[196:199], v[116:119]
	v_mfma_f32_16x16x32_bf16 v[112:115], v[180:183], v[196:199], v[112:115]
	v_mfma_f32_16x16x32_bf16 v[108:111], v[172:175], v[204:207], v[108:111]
	v_mfma_f32_16x16x32_bf16 v[104:107], v[180:183], v[204:207], v[104:107]
	v_mfma_f32_16x16x32_bf16 v[100:103], v[172:175], v[212:215], v[100:103]
	v_mfma_f32_16x16x32_bf16 v[96:99], v[180:183], v[212:215], v[96:99]
	v_mfma_f32_16x16x32_bf16 v[124:127], v[176:179], v[192:195], v[124:127]
	v_mfma_f32_16x16x32_bf16 v[120:123], v[184:187], v[192:195], v[120:123]
	v_mfma_f32_16x16x32_bf16 v[116:119], v[176:179], v[200:203], v[116:119]
	v_mfma_f32_16x16x32_bf16 v[112:115], v[184:187], v[200:203], v[112:115]
	v_mfma_f32_16x16x32_bf16 v[108:111], v[176:179], v[208:211], v[108:111]
	v_mfma_f32_16x16x32_bf16 v[104:107], v[184:187], v[208:211], v[104:107]
	v_mfma_f32_16x16x32_bf16 v[100:103], v[176:179], v[216:219], v[100:103]
	v_mfma_f32_16x16x32_bf16 v[96:99], v[184:187], v[216:219], v[96:99]
	s_setprio 0
	s_barrier
	v_lshl_add_u64 v[240:241], s[42:43], 0, v[132:133]
	v_readfirstlane_b32 s45, v153
	v_lshl_add_u64 v[242:243], v[240:241], 0, s[12:13]
	s_mov_b32 m0, s45
	ds_read_b128 v[220:223], v167
	ds_read_b128 v[224:227], v167 offset:1024
	ds_read_b128 v[228:231], v167 offset:2048
	ds_read_b128 v[232:235], v167 offset:3072
	global_load_lds_dwordx4 v[242:243], off
	v_lshl_add_u64 v[242:243], s[42:43], 0, v[134:135]
	v_readfirstlane_b32 s45, v154
	v_lshl_add_u64 v[244:245], v[242:243], 0, s[12:13]
	s_mov_b32 m0, s45
	s_nop 0
	global_load_lds_dwordx4 v[244:245], off
	s_barrier
	s_waitcnt lgkmcnt(0)
	s_setprio 1
	s_waitcnt lgkmcnt(0)
	v_mfma_f32_16x16x32_bf16 v[92:95], v[220:223], v[188:191], v[92:95]
	v_mfma_f32_16x16x32_bf16 v[88:91], v[228:231], v[188:191], v[88:91]
	v_mfma_f32_16x16x32_bf16 v[84:87], v[220:223], v[196:199], v[84:87]
	v_mfma_f32_16x16x32_bf16 v[80:83], v[228:231], v[196:199], v[80:83]
	v_mfma_f32_16x16x32_bf16 v[76:79], v[220:223], v[204:207], v[76:79]
	v_mfma_f32_16x16x32_bf16 v[72:75], v[228:231], v[204:207], v[72:75]
	v_mfma_f32_16x16x32_bf16 v[68:71], v[220:223], v[212:215], v[68:71]
	v_mfma_f32_16x16x32_bf16 v[64:67], v[228:231], v[212:215], v[64:67]
	v_mfma_f32_16x16x32_bf16 v[92:95], v[224:227], v[192:195], v[92:95]
	v_mfma_f32_16x16x32_bf16 v[88:91], v[232:235], v[192:195], v[88:91]
	v_mfma_f32_16x16x32_bf16 v[84:87], v[224:227], v[200:203], v[84:87]
	v_mfma_f32_16x16x32_bf16 v[80:83], v[232:235], v[200:203], v[80:83]
	v_mfma_f32_16x16x32_bf16 v[76:79], v[224:227], v[208:211], v[76:79]
	v_mfma_f32_16x16x32_bf16 v[72:75], v[232:235], v[208:211], v[72:75]
	v_mfma_f32_16x16x32_bf16 v[68:71], v[224:227], v[216:219], v[68:71]
	v_mfma_f32_16x16x32_bf16 v[64:67], v[232:235], v[216:219], v[64:67]
	s_setprio 0
	v_readfirstlane_b32 s45, v147
	v_lshl_add_u64 v[244:245], v[236:237], 0, s[14:15]
	s_mov_b32 m0, s45
	v_readfirstlane_b32 s45, v148
	s_barrier
	ds_read_b128 v[188:191], v152 offset:16384
	ds_read_b128 v[192:195], v152 offset:17408
	ds_read_b128 v[196:199], v151 offset:16384
	ds_read_b128 v[200:203], v151 offset:17408
	ds_read_b128 v[204:207], v150 offset:16384
	ds_read_b128 v[208:211], v150 offset:17408
	ds_read_b128 v[212:215], v149 offset:16384
	ds_read_b128 v[216:219], v149 offset:17408
	global_load_lds_dwordx4 v[244:245], off
	v_lshl_add_u64 v[244:245], v[238:239], 0, s[14:15]
	s_mov_b32 m0, s45
	s_nop 0
	global_load_lds_dwordx4 v[244:245], off
	s_barrier
	s_waitcnt lgkmcnt(0)
	s_setprio 1
	s_waitcnt lgkmcnt(0)
	v_mfma_f32_16x16x32_bf16 v[60:63], v[172:175], v[188:191], v[60:63]
	v_mfma_f32_16x16x32_bf16 v[56:59], v[180:183], v[188:191], v[56:59]
	v_mfma_f32_16x16x32_bf16 v[52:55], v[172:175], v[196:199], v[52:55]
	v_mfma_f32_16x16x32_bf16 v[48:51], v[180:183], v[196:199], v[48:51]
	v_mfma_f32_16x16x32_bf16 v[44:47], v[172:175], v[204:207], v[44:47]
	v_mfma_f32_16x16x32_bf16 v[40:43], v[180:183], v[204:207], v[40:43]
	v_mfma_f32_16x16x32_bf16 v[36:39], v[172:175], v[212:215], v[36:39]
	v_mfma_f32_16x16x32_bf16 v[32:35], v[180:183], v[212:215], v[32:35]
	v_mfma_f32_16x16x32_bf16 v[60:63], v[176:179], v[192:195], v[60:63]
	v_mfma_f32_16x16x32_bf16 v[56:59], v[184:187], v[192:195], v[56:59]
	v_mfma_f32_16x16x32_bf16 v[52:55], v[176:179], v[200:203], v[52:55]
	v_mfma_f32_16x16x32_bf16 v[48:51], v[184:187], v[200:203], v[48:51]
	v_mfma_f32_16x16x32_bf16 v[44:47], v[176:179], v[208:211], v[44:47]
	v_mfma_f32_16x16x32_bf16 v[40:43], v[184:187], v[208:211], v[40:43]
	v_mfma_f32_16x16x32_bf16 v[36:39], v[176:179], v[216:219], v[36:39]
	v_mfma_f32_16x16x32_bf16 v[32:35], v[184:187], v[216:219], v[32:35]
	s_setprio 0
	s_barrier
; #define G_STAGE(P,BASE,LD,br,kt,VOFF) do{ const char* _sb=(const char*)(BASE)+((size_t)(br)*(size_t)(LD)+(size_t)(kt)*BK)*2; \
;     _Pragma("unroll") for(int _i=0;_i<2;++_i){ \
;       __builtin_amdgcn_global_load_lds((const unsigned*)(_sb+VOFF[_i]), \
;         (unsigned*)((char*)(P)+tid*16+_i*8192),16,0,0);} }while(0)
; #define G_LDA(dst,b,h) _Pragma("unroll") for(int m=0;m<4;++m) _Pragma("unroll") for(int k=0;k<2;++k) \
;     dst[m][k]=*reinterpret_cast<const bf16x8*>((char*)G_SA(b,h)+lds_byte(wr*64+m*16+fr,k*32+fq*8))
; #define G_LDB(dst,b,h) _Pragma("unroll") for(int n=0;n<2;++n) _Pragma("unroll") for(int k=0;k<2;++k) \
;     dst[n][k]=*reinterpret_cast<const bf16x8*>((char*)G_SB(b,h)+lds_byte(wc*32+n*16+fr,k*32+fq*8))
; #define G_MMA(ai,bj,At,Bx) do{__builtin_amdgcn_s_setprio(1); \
;     _Pragma("unroll") for(int m=0;m<4;++m) _Pragma("unroll") for(int n=0;n<2;++n) _Pragma("unroll") for(int k=0;k<2;++k) \
;       acc[ai][bj][m][n]=__builtin_amdgcn_mfma_f32_16x16x32_bf16(Bx[n][k],At[m][k],acc[ai][bj][m][n],0,0,0); \
;     __builtin_amdgcn_s_setprio(0);}while(0)
; #define WAIT_V(n) asm volatile("s_waitcnt vmcnt(" #n ")":::"memory")
; #define BAR __builtin_amdgcn_s_barrier()
; __device__ __forceinline__ void gemm_core(f32x4 (&acc)[2][2][4][2], const u16* __restrict__ A, int lda,
;                                           const u16* __restrict__ Bt, int ldb, int K, int brow, int bcol, u16* shm, int tid) {
;     ...
;   for(int t=0;t<nt-2;t+=2){
;     G_LDB(B0,0,0); SCHED; G_LDA(At,0,0); G_STAGE(G_SA(1,1),A,lda,brow+HALF,t+1,vA);
;     WAIT_L(8); BAR; WAIT_L(0); G_MMA(0,0,At,B0); BAR; SCHED;
;     G_LDB(B1,0,1); G_STAGE(G_SB(0,0),Bt,ldb,bcol,t+2,vB);
;     BAR; WAIT_L(0); G_MMA(0,1,At,B1); BAR;
;     G_LDA(At,0,1); G_STAGE(G_SA(0,0),A,lda,brow,t+2,vA);
;     BAR; WAIT_L(0); G_MMA(1,0,At,B0); BAR; SCHED;
;     G_STAGE(G_SB(0,1),Bt,ldb,bcol+HALF,t+2,vB);
;     WAIT_V(6); BAR; G_MMA(1,1,At,B1); BAR;
;     G_LDB(B0,1,0); SCHED; G_LDA(At,1,0); G_STAGE(G_SA(0,1),A,lda,brow+HALF,t+2,vA);
;     WAIT_L(8); BAR; WAIT_L(0); G_MMA(0,0,At,B0); BAR; SCHED;
;     G_LDB(B1,1,1); G_STAGE(G_SB(1,0),Bt,ldb,bcol,t+3,vB);
;     BAR; WAIT_L(0); G_MMA(0,1,At,B1); BAR;
;     G_LDA(At,1,1); G_STAGE(G_SA(1,0),A,lda,brow,t+3,vA);
;     BAR; WAIT_L(0); G_MMA(1,0,At,B0); BAR; SCHED;
;     G_STAGE(G_SB(1,1),Bt,ldb,bcol+HALF,t+3,vB);
;     WAIT_V(6); BAR; G_MMA(1,1,At,B1); BAR;
	v_readfirstlane_b32 s45, v156
	v_lshl_add_u64 v[172:173], v[240:241], 0, s[16:17]
	s_mov_b32 m0, s45
	v_readfirstlane_b32 s45, v157
	global_load_lds_dwordx4 v[172:173], off
	v_lshl_add_u64 v[172:173], v[242:243], 0, s[16:17]
	s_mov_b32 m0, s45
	s_nop 0
	global_load_lds_dwordx4 v[172:173], off
	s_waitcnt vmcnt(6)
	s_barrier
	s_setprio 1
	v_mfma_f32_16x16x32_bf16 v[28:31], v[220:223], v[188:191], v[28:31]
	v_mfma_f32_16x16x32_bf16 v[24:27], v[228:231], v[188:191], v[24:27]
	v_mfma_f32_16x16x32_bf16 v[20:23], v[220:223], v[196:199], v[20:23]
	v_mfma_f32_16x16x32_bf16 v[16:19], v[228:231], v[196:199], v[16:19]
	v_mfma_f32_16x16x32_bf16 v[12:15], v[220:223], v[204:207], v[12:15]
	v_mfma_f32_16x16x32_bf16 v[8:11], v[228:231], v[204:207], v[8:11]
	v_mfma_f32_16x16x32_bf16 v[4:7], v[220:223], v[212:215], v[4:7]
	v_mfma_f32_16x16x32_bf16 v[0:3], v[228:231], v[212:215], v[0:3]
	v_mfma_f32_16x16x32_bf16 v[28:31], v[224:227], v[192:195], v[28:31]
	v_mfma_f32_16x16x32_bf16 v[24:27], v[232:235], v[192:195], v[24:27]
	v_mfma_f32_16x16x32_bf16 v[20:23], v[224:227], v[200:203], v[20:23]
	v_mfma_f32_16x16x32_bf16 v[16:19], v[232:235], v[200:203], v[16:19]
	v_mfma_f32_16x16x32_bf16 v[12:15], v[224:227], v[208:211], v[12:15]
	v_mfma_f32_16x16x32_bf16 v[8:11], v[232:235], v[208:211], v[8:11]
	v_mfma_f32_16x16x32_bf16 v[4:7], v[224:227], v[216:219], v[4:7]
	v_mfma_f32_16x16x32_bf16 v[0:3], v[232:235], v[216:219], v[0:3]
	s_setprio 0
	s_barrier
	ds_read_b128 v[172:175], v158
	ds_read_b128 v[176:179], v158 offset:1024
	ds_read_b128 v[180:183], v158 offset:2048
	ds_read_b128 v[184:187], v158 offset:3072
	v_readfirstlane_b32 s45, v159
	v_lshl_add_u64 v[220:221], v[236:237], 0, s[18:19]
	s_mov_b32 m0, s45
	v_readfirstlane_b32 s45, v160
	ds_read_b128 v[188:191], v152 offset:32768
	ds_read_b128 v[192:195], v152 offset:33792
	ds_read_b128 v[196:199], v151 offset:32768
	ds_read_b128 v[200:203], v151 offset:33792
	ds_read_b128 v[204:207], v150 offset:32768
	ds_read_b128 v[208:211], v150 offset:33792
	ds_read_b128 v[212:215], v149 offset:32768
	ds_read_b128 v[216:219], v149 offset:33792
	global_load_lds_dwordx4 v[220:221], off
	v_lshl_add_u64 v[220:221], v[238:239], 0, s[18:19]
	s_mov_b32 m0, s45
	s_nop 0
	global_load_lds_dwordx4 v[220:221], off
	s_waitcnt lgkmcnt(8)
	s_barrier
	s_waitcnt lgkmcnt(0)
	s_setprio 1
	s_waitcnt lgkmcnt(0)
	v_mfma_f32_16x16x32_bf16 v[124:127], v[172:175], v[188:191], v[124:127]
	v_mfma_f32_16x16x32_bf16 v[120:123], v[180:183], v[188:191], v[120:123]
	v_mfma_f32_16x16x32_bf16 v[116:119], v[172:175], v[196:199], v[116:119]
	v_mfma_f32_16x16x32_bf16 v[112:115], v[180:183], v[196:199], v[112:115]
	v_mfma_f32_16x16x32_bf16 v[108:111], v[172:175], v[204:207], v[108:111]
	v_mfma_f32_16x16x32_bf16 v[104:107], v[180:183], v[204:207], v[104:107]
	v_mfma_f32_16x16x32_bf16 v[100:103], v[172:175], v[212:215], v[100:103]
	v_mfma_f32_16x16x32_bf16 v[96:99], v[180:183], v[212:215], v[96:99]
	v_mfma_f32_16x16x32_bf16 v[124:127], v[176:179], v[192:195], v[124:127]
	v_mfma_f32_16x16x32_bf16 v[120:123], v[184:187], v[192:195], v[120:123]
	v_mfma_f32_16x16x32_bf16 v[116:119], v[176:179], v[200:203], v[116:119]
	v_mfma_f32_16x16x32_bf16 v[112:115], v[184:187], v[200:203], v[112:115]
	v_mfma_f32_16x16x32_bf16 v[108:111], v[176:179], v[208:211], v[108:111]
	v_mfma_f32_16x16x32_bf16 v[104:107], v[184:187], v[208:211], v[104:107]
	v_mfma_f32_16x16x32_bf16 v[100:103], v[176:179], v[216:219], v[100:103]
	v_mfma_f32_16x16x32_bf16 v[96:99], v[184:187], v[216:219], v[96:99]
	s_setprio 0
	s_barrier
	v_readfirstlane_b32 s45, v161
	v_lshl_add_u64 v[244:245], v[240:241], 0, s[20:21]
	s_mov_b32 m0, s45
	v_readfirstlane_b32 s45, v162
	ds_read_b128 v[220:223], v155
	ds_read_b128 v[224:227], v155 offset:1024
	ds_read_b128 v[228:231], v155 offset:2048
	ds_read_b128 v[232:235], v155 offset:3072
	global_load_lds_dwordx4 v[244:245], off
	v_lshl_add_u64 v[244:245], v[242:243], 0, s[20:21]
	s_mov_b32 m0, s45
	s_nop 0
	global_load_lds_dwordx4 v[244:245], off
	s_barrier
	s_waitcnt lgkmcnt(0)
	s_setprio 1
	s_waitcnt lgkmcnt(0)
	v_mfma_f32_16x16x32_bf16 v[92:95], v[220:223], v[188:191], v[92:95]
	v_mfma_f32_16x16x32_bf16 v[88:91], v[228:231], v[188:191], v[88:91]
	v_mfma_f32_16x16x32_bf16 v[84:87], v[220:223], v[196:199], v[84:87]
	v_mfma_f32_16x16x32_bf16 v[80:83], v[228:231], v[196:199], v[80:83]
	v_mfma_f32_16x16x32_bf16 v[76:79], v[220:223], v[204:207], v[76:79]
	v_mfma_f32_16x16x32_bf16 v[72:75], v[228:231], v[204:207], v[72:75]
	v_mfma_f32_16x16x32_bf16 v[68:71], v[220:223], v[212:215], v[68:71]
	v_mfma_f32_16x16x32_bf16 v[64:67], v[228:231], v[212:215], v[64:67]
	v_mfma_f32_16x16x32_bf16 v[92:95], v[224:227], v[192:195], v[92:95]
	v_mfma_f32_16x16x32_bf16 v[88:91], v[232:235], v[192:195], v[88:91]
	v_mfma_f32_16x16x32_bf16 v[84:87], v[224:227], v[200:203], v[84:87]
	v_mfma_f32_16x16x32_bf16 v[80:83], v[232:235], v[200:203], v[80:83]
	v_mfma_f32_16x16x32_bf16 v[76:79], v[224:227], v[208:211], v[76:79]
	v_mfma_f32_16x16x32_bf16 v[72:75], v[232:235], v[208:211], v[72:75]
	v_mfma_f32_16x16x32_bf16 v[68:71], v[224:227], v[216:219], v[68:71]
	v_mfma_f32_16x16x32_bf16 v[64:67], v[232:235], v[216:219], v[64:67]
	s_setprio 0
	v_readfirstlane_b32 s45, v163
	v_lshl_add_u64 v[236:237], v[236:237], 0, s[22:23]
	s_mov_b32 m0, s45
	v_readfirstlane_b32 s45, v164
	s_barrier
	ds_read_b128 v[188:191], v152 offset:49152
	ds_read_b128 v[192:195], v152 offset:50176
	ds_read_b128 v[196:199], v151 offset:49152
	ds_read_b128 v[200:203], v151 offset:50176
	ds_read_b128 v[204:207], v150 offset:49152
	ds_read_b128 v[208:211], v150 offset:50176
	ds_read_b128 v[212:215], v149 offset:49152
	ds_read_b128 v[216:219], v149 offset:50176
	global_load_lds_dwordx4 v[236:237], off
	v_lshl_add_u64 v[236:237], v[238:239], 0, s[22:23]
	s_mov_b32 m0, s45
	s_nop 0
	global_load_lds_dwordx4 v[236:237], off
	s_barrier
; #define G_STAGE(P,BASE,LD,br,kt,VOFF) do{ const char* _sb=(const char*)(BASE)+((size_t)(br)*(size_t)(LD)+(size_t)(kt)*BK)*2; \
;     _Pragma("unroll") for(int _i=0;_i<2;++_i){ \
;       __builtin_amdgcn_global_load_lds((const unsigned*)(_sb+VOFF[_i]), \
;         (unsigned*)((char*)(P)+tid*16+_i*8192),16,0,0);} }while(0)
; #define G_LDA(dst,b,h) _Pragma("unroll") for(int m=0;m<4;++m) _Pragma("unroll") for(int k=0;k<2;++k) \
;     dst[m][k]=*reinterpret_cast<const bf16x8*>((char*)G_SA(b,h)+lds_byte(wr*64+m*16+fr,k*32+fq*8))
; #define G_LDB(dst,b,h) _Pragma("unroll") for(int n=0;n<2;++n) _Pragma("unroll") for(int k=0;k<2;++k) \
;     dst[n][k]=*reinterpret_cast<const bf16x8*>((char*)G_SB(b,h)+lds_byte(wc*32+n*16+fr,k*32+fq*8))
; #define G_MMA(ai,bj,At,Bx) do{__builtin_amdgcn_s_setprio(1); \
;     _Pragma("unroll") for(int m=0;m<4;++m) _Pragma("unroll") for(int n=0;n<2;++n) _Pragma("unroll") for(int k=0;k<2;++k) \
;       acc[ai][bj][m][n]=__builtin_amdgcn_mfma_f32_16x16x32_bf16(Bx[n][k],At[m][k],acc[ai][bj][m][n],0,0,0); \
;     __builtin_amdgcn_s_setprio(0);}while(0)
; #define WAIT_V(n) asm volatile("s_waitcnt vmcnt(" #n ")":::"memory")
; #define WAIT_L(n) asm volatile("s_waitcnt lgkmcnt(" #n ")":::"memory")
; #define BAR __builtin_amdgcn_s_barrier()
; __device__ __forceinline__ void gemm_core(f32x4 (&acc)[2][2][4][2], const u16* __restrict__ A, int lda,
;                                           const u16* __restrict__ Bt, int ldb, int K, int brow, int bcol, u16* shm, int tid) {
;     ...
;     WAIT_V(6); BAR; G_MMA(1,1,At,B1); BAR;
;     G_LDB(B0,1,0); SCHED; G_LDA(At,1,0); G_STAGE(G_SA(0,1),A,lda,brow+HALF,t+2,vA);
;     WAIT_L(8); BAR; WAIT_L(0); G_MMA(0,0,At,B0); BAR; SCHED;
;     G_LDB(B1,1,1); G_STAGE(G_SB(1,0),Bt,ldb,bcol,t+3,vB);
;     BAR; WAIT_L(0); G_MMA(0,1,At,B1); BAR;
;     G_LDA(At,1,1); G_STAGE(G_SA(1,0),A,lda,brow,t+3,vA);
;     BAR; WAIT_L(0); G_MMA(1,0,At,B0); BAR; SCHED;
;     G_STAGE(G_SB(1,1),Bt,ldb,bcol+HALF,t+3,vB);
;     WAIT_V(6); BAR; G_MMA(1,1,At,B1); BAR;
;   }
;   { G_LDB(B0,0,0); G_LDA(At,0,0); G_STAGE(G_SA(1,1),A,lda,brow+HALF,nt-1,vA);
;     BAR; WAIT_L(0); G_MMA(0,0,At,B0); BAR;
;     G_LDB(B1,0,1); BAR; WAIT_L(0); G_MMA(0,1,At,B1); BAR;
;     G_LDA(At,0,1); WAIT_V(4); BAR; WAIT_L(0); G_MMA(1,0,At,B0); G_MMA(1,1,At,B1); BAR; }
;   { G_LDB(B0,1,0); G_LDA(At,1,0); WAIT_V(2); BAR; WAIT_L(0); G_MMA(0,0,At,B0); BAR;
	s_waitcnt lgkmcnt(0)
	s_setprio 1
	s_waitcnt lgkmcnt(0)
	v_mfma_f32_16x16x32_bf16 v[60:63], v[172:175], v[188:191], v[60:63]
	v_mfma_f32_16x16x32_bf16 v[56:59], v[180:183], v[188:191], v[56:59]
	v_mfma_f32_16x16x32_bf16 v[52:55], v[172:175], v[196:199], v[52:55]
	v_mfma_f32_16x16x32_bf16 v[48:51], v[180:183], v[196:199], v[48:51]
	v_mfma_f32_16x16x32_bf16 v[44:47], v[172:175], v[204:207], v[44:47]
	v_mfma_f32_16x16x32_bf16 v[40:43], v[180:183], v[204:207], v[40:43]
	v_mfma_f32_16x16x32_bf16 v[36:39], v[172:175], v[212:215], v[36:39]
	v_mfma_f32_16x16x32_bf16 v[32:35], v[180:183], v[212:215], v[32:35]
	v_mfma_f32_16x16x32_bf16 v[60:63], v[176:179], v[192:195], v[60:63]
	v_mfma_f32_16x16x32_bf16 v[56:59], v[184:187], v[192:195], v[56:59]
	v_mfma_f32_16x16x32_bf16 v[52:55], v[176:179], v[200:203], v[52:55]
	v_mfma_f32_16x16x32_bf16 v[48:51], v[184:187], v[200:203], v[48:51]
	v_mfma_f32_16x16x32_bf16 v[44:47], v[176:179], v[208:211], v[44:47]
	v_mfma_f32_16x16x32_bf16 v[40:43], v[184:187], v[208:211], v[40:43]
	v_mfma_f32_16x16x32_bf16 v[36:39], v[176:179], v[216:219], v[36:39]
	v_mfma_f32_16x16x32_bf16 v[32:35], v[184:187], v[216:219], v[32:35]
	s_setprio 0
	s_barrier
	v_readfirstlane_b32 s45, v165
	v_lshl_add_u64 v[172:173], v[240:241], 0, s[34:35]
	s_mov_b32 m0, s45
	v_readfirstlane_b32 s45, v166
	global_load_lds_dwordx4 v[172:173], off
	v_lshl_add_u64 v[172:173], v[242:243], 0, s[34:35]
	s_mov_b32 m0, s45
	s_nop 0
	global_load_lds_dwordx4 v[172:173], off
	s_waitcnt vmcnt(6)
	s_barrier
	s_setprio 1
	v_mfma_f32_16x16x32_bf16 v[28:31], v[220:223], v[188:191], v[28:31]
	v_mfma_f32_16x16x32_bf16 v[24:27], v[228:231], v[188:191], v[24:27]
	v_mfma_f32_16x16x32_bf16 v[20:23], v[220:223], v[196:199], v[20:23]
	v_mfma_f32_16x16x32_bf16 v[16:19], v[228:231], v[196:199], v[16:19]
	v_mfma_f32_16x16x32_bf16 v[12:15], v[220:223], v[204:207], v[12:15]
	v_mfma_f32_16x16x32_bf16 v[8:11], v[228:231], v[204:207], v[8:11]
	v_mfma_f32_16x16x32_bf16 v[4:7], v[220:223], v[212:215], v[4:7]
	v_mfma_f32_16x16x32_bf16 v[0:3], v[228:231], v[212:215], v[0:3]
	v_mfma_f32_16x16x32_bf16 v[28:31], v[224:227], v[192:195], v[28:31]
	v_mfma_f32_16x16x32_bf16 v[24:27], v[232:235], v[192:195], v[24:27]
	v_mfma_f32_16x16x32_bf16 v[20:23], v[224:227], v[200:203], v[20:23]
	v_mfma_f32_16x16x32_bf16 v[16:19], v[232:235], v[200:203], v[16:19]
	v_mfma_f32_16x16x32_bf16 v[12:15], v[224:227], v[208:211], v[12:15]
	v_mfma_f32_16x16x32_bf16 v[8:11], v[232:235], v[208:211], v[8:11]
	v_mfma_f32_16x16x32_bf16 v[4:7], v[224:227], v[216:219], v[4:7]
	v_mfma_f32_16x16x32_bf16 v[0:3], v[232:235], v[216:219], v[0:3]
	s_setprio 0
	s_add_i32 s44, s44, 2
	s_add_u32 s42, s42, 0x100
	s_addc_u32 s43, s43, 0
	s_cmp_lt_u32 s44, 12
	s_barrier
	s_cbranch_scc1 .LBB0_931
	s_add_u32 s40, s56, s40
	s_addc_u32 s41, s57, s41
	v_readfirstlane_b32 s42, v169
	v_lshl_add_u64 v[156:157], s[40:41], 0, v[128:129]
	s_mov_b32 m0, s42
	v_lshl_add_u64 v[130:131], s[40:41], 0, v[130:131]
	v_readfirstlane_b32 s40, v168
	ds_read_b128 v[132:135], v170
	ds_read_b128 v[136:139], v170 offset:1024
	ds_read_b128 v[160:163], v170 offset:2048
	ds_read_b128 v[170:173], v170 offset:3072
	ds_read_b128 v[174:177], v152
	ds_read_b128 v[178:181], v152 offset:1024
	ds_read_b128 v[182:185], v151
	ds_read_b128 v[186:189], v151 offset:1024
	ds_read_b128 v[190:193], v150
	ds_read_b128 v[194:197], v150 offset:1024
	ds_read_b128 v[198:201], v149
	ds_read_b128 v[202:205], v149 offset:1024
	global_load_lds_dwordx4 v[156:157], off
	s_mov_b32 m0, s40
	s_nop 0
	global_load_lds_dwordx4 v[130:131], off
	s_barrier
	s_waitcnt lgkmcnt(0)
	s_setprio 1
	s_waitcnt lgkmcnt(0)
	v_mfma_f32_16x16x32_bf16 v[124:127], v[132:135], v[174:177], v[124:127]
	v_mfma_f32_16x16x32_bf16 v[120:123], v[160:163], v[174:177], v[120:123]
	v_mfma_f32_16x16x32_bf16 v[116:119], v[132:135], v[182:185], v[116:119]
	v_mfma_f32_16x16x32_bf16 v[112:115], v[160:163], v[182:185], v[112:115]
	v_mfma_f32_16x16x32_bf16 v[100:103], v[132:135], v[198:201], v[100:103]
	v_mfma_f32_16x16x32_bf16 v[96:99], v[160:163], v[198:201], v[96:99]
	v_mfma_f32_16x16x32_bf16 v[124:127], v[136:139], v[178:181], v[124:127]
	v_mfma_f32_16x16x32_bf16 v[120:123], v[170:173], v[178:181], v[120:123]
	v_mfma_f32_16x16x32_bf16 v[116:119], v[136:139], v[186:189], v[116:119]
	v_mfma_f32_16x16x32_bf16 v[112:115], v[170:173], v[186:189], v[112:115]
	v_mfma_f32_16x16x32_bf16 v[108:111], v[132:135], v[190:193], v[108:111]
	v_mfma_f32_16x16x32_bf16 v[104:107], v[160:163], v[190:193], v[104:107]
	v_mfma_f32_16x16x32_bf16 v[100:103], v[136:139], v[202:205], v[100:103]
	v_mfma_f32_16x16x32_bf16 v[96:99], v[170:173], v[202:205], v[96:99]
	v_mfma_f32_16x16x32_bf16 v[206:209], v[136:139], v[194:197], v[108:111]
	v_mfma_f32_16x16x32_bf16 v[210:213], v[170:173], v[194:197], v[104:107]
	s_setprio 0
	s_barrier
	s_nop 1
	ds_read_b128 v[104:107], v167
	ds_read_b128 v[108:111], v167 offset:1024
	ds_read_b128 v[214:217], v167 offset:2048
	ds_read_b128 v[164:167], v167 offset:3072
	s_barrier
	s_waitcnt lgkmcnt(0)
	s_setprio 1
	s_waitcnt lgkmcnt(0)
	v_mfma_f32_16x16x32_bf16 v[84:87], v[104:107], v[182:185], v[84:87]
	v_mfma_f32_16x16x32_bf16 v[80:83], v[214:217], v[182:185], v[80:83]
	v_mfma_f32_16x16x32_bf16 v[68:71], v[104:107], v[198:201], v[68:71]
	v_mfma_f32_16x16x32_bf16 v[64:67], v[214:217], v[198:201], v[64:67]
	v_mfma_f32_16x16x32_bf16 v[92:95], v[104:107], v[174:177], v[92:95]
	v_mfma_f32_16x16x32_bf16 v[88:91], v[214:217], v[174:177], v[88:91]
	v_mfma_f32_16x16x32_bf16 v[84:87], v[108:111], v[186:189], v[84:87]
	v_mfma_f32_16x16x32_bf16 v[80:83], v[164:167], v[186:189], v[80:83]
	v_mfma_f32_16x16x32_bf16 v[76:79], v[104:107], v[190:193], v[76:79]
	v_mfma_f32_16x16x32_bf16 v[72:75], v[214:217], v[190:193], v[72:75]
	v_mfma_f32_16x16x32_bf16 v[68:71], v[108:111], v[202:205], v[68:71]
	v_mfma_f32_16x16x32_bf16 v[64:67], v[164:167], v[202:205], v[64:67]
	v_mfma_f32_16x16x32_bf16 v[218:221], v[108:111], v[178:181], v[92:95]
	v_mfma_f32_16x16x32_bf16 v[174:177], v[164:167], v[178:181], v[88:91]
	v_mfma_f32_16x16x32_bf16 v[178:181], v[108:111], v[194:197], v[76:79]
	v_mfma_f32_16x16x32_bf16 v[182:185], v[164:167], v[194:197], v[72:75]
	s_setprio 0
	s_barrier
; #define G_STAGE(P,BASE,LD,br,kt,VOFF) do{ const char* _sb=(const char*)(BASE)+((size_t)(br)*(size_t)(LD)+(size_t)(kt)*BK)*2; \
;     _Pragma("unroll") for(int _i=0;_i<2;++_i){ \
;       __builtin_amdgcn_global_load_lds((const unsigned*)(_sb+VOFF[_i]), \
;         (unsigned*)((char*)(P)+tid*16+_i*8192),16,0,0);} }while(0)
; #define G_LDA(dst,b,h) _Pragma("unroll") for(int m=0;m<4;++m) _Pragma("unroll") for(int k=0;k<2;++k) \
;     dst[m][k]=*reinterpret_cast<const bf16x8*>((char*)G_SA(b,h)+lds_byte(wr*64+m*16+fr,k*32+fq*8))
; #define G_LDB(dst,b,h) _Pragma("unroll") for(int n=0;n<2;++n) _Pragma("unroll") for(int k=0;k<2;++k) \
;     dst[n][k]=*reinterpret_cast<const bf16x8*>((char*)G_SB(b,h)+lds_byte(wc*32+n*16+fr,k*32+fq*8))
; #define G_MMA(ai,bj,At,Bx) do{__builtin_amdgcn_s_setprio(1); \
;     _Pragma("unroll") for(int m=0;m<4;++m) _Pragma("unroll") for(int n=0;n<2;++n) _Pragma("unroll") for(int k=0;k<2;++k) \
;       acc[ai][bj][m][n]=__builtin_amdgcn_mfma_f32_16x16x32_bf16(Bx[n][k],At[m][k],acc[ai][bj][m][n],0,0,0); \
;     __builtin_amdgcn_s_setprio(0);}while(0)
; #define WAIT_V(n) asm volatile("s_waitcnt vmcnt(" #n ")":::"memory")
; #define WAIT_L(n) asm volatile("s_waitcnt lgkmcnt(" #n ")":::"memory")
; #define BAR __builtin_amdgcn_s_barrier()
; __device__ __forceinline__ void gemm_core(f32x4 (&acc)[2][2][4][2], const u16* __restrict__ A, int lda,
;                                           const u16* __restrict__ Bt, int ldb, int K, int brow, int bcol, u16* shm, int tid) {
;     ...
;   { G_LDB(B0,0,0); G_LDA(At,0,0); G_STAGE(G_SA(1,1),A,lda,brow+HALF,nt-1,vA);
;     BAR; WAIT_L(0); G_MMA(0,0,At,B0); BAR;
;     G_LDB(B1,0,1); BAR; WAIT_L(0); G_MMA(0,1,At,B1); BAR;
;     G_LDA(At,0,1); WAIT_V(4); BAR; WAIT_L(0); G_MMA(1,0,At,B0); G_MMA(1,1,At,B1); BAR; }
;   { G_LDB(B0,1,0); G_LDA(At,1,0); WAIT_V(2); BAR; WAIT_L(0); G_MMA(0,0,At,B0); BAR;
;     G_LDB(B1,1,1); WAIT_V(0); BAR; WAIT_L(0); G_MMA(0,1,At,B1); BAR;
;     G_LDA(At,1,1); BAR; WAIT_L(0); G_MMA(1,0,At,B0); G_MMA(1,1,At,B1); BAR; }
	s_nop 0
	ds_read_b128 v[72:75], v152 offset:16384
	ds_read_b128 v[76:79], v152 offset:17408
	ds_read_b128 v[88:91], v151 offset:16384
	ds_read_b128 v[92:95], v151 offset:17408
	ds_read_b128 v[186:189], v150 offset:16384
	ds_read_b128 v[190:193], v150 offset:17408
	ds_read_b128 v[194:197], v149 offset:16384
	ds_read_b128 v[198:201], v149 offset:17408
	s_waitcnt vmcnt(4)
	s_barrier
	s_waitcnt lgkmcnt(0)
	s_setprio 1
	s_waitcnt lgkmcnt(0)
	v_mfma_f32_16x16x32_bf16 v[60:63], v[132:135], v[72:75], v[60:63]
	v_mfma_f32_16x16x32_bf16 v[56:59], v[160:163], v[72:75], v[56:59]
	v_mfma_f32_16x16x32_bf16 v[52:55], v[132:135], v[88:91], v[52:55]
	v_mfma_f32_16x16x32_bf16 v[48:51], v[160:163], v[88:91], v[48:51]
	v_mfma_f32_16x16x32_bf16 v[36:39], v[132:135], v[194:197], v[36:39]
	v_mfma_f32_16x16x32_bf16 v[32:35], v[160:163], v[194:197], v[32:35]
	v_mfma_f32_16x16x32_bf16 v[60:63], v[136:139], v[76:79], v[60:63]
	v_mfma_f32_16x16x32_bf16 v[56:59], v[170:173], v[76:79], v[56:59]
	v_mfma_f32_16x16x32_bf16 v[52:55], v[136:139], v[92:95], v[52:55]
	v_mfma_f32_16x16x32_bf16 v[48:51], v[170:173], v[92:95], v[48:51]
	v_mfma_f32_16x16x32_bf16 v[44:47], v[132:135], v[186:189], v[44:47]
	v_mfma_f32_16x16x32_bf16 v[40:43], v[160:163], v[186:189], v[40:43]
	v_mfma_f32_16x16x32_bf16 v[36:39], v[136:139], v[198:201], v[36:39]
	v_mfma_f32_16x16x32_bf16 v[32:35], v[170:173], v[198:201], v[32:35]
	v_mfma_f32_16x16x32_bf16 v[202:205], v[136:139], v[190:193], v[44:47]
	v_mfma_f32_16x16x32_bf16 v[222:225], v[170:173], v[190:193], v[40:43]
	s_setprio 0
	s_setprio 1
	v_mfma_f32_16x16x32_bf16 v[20:23], v[104:107], v[88:91], v[20:23]
	v_mfma_f32_16x16x32_bf16 v[16:19], v[214:217], v[88:91], v[16:19]
	v_mfma_f32_16x16x32_bf16 v[4:7], v[104:107], v[194:197], v[4:7]
	v_mfma_f32_16x16x32_bf16 v[0:3], v[214:217], v[194:197], v[0:3]
	v_mfma_f32_16x16x32_bf16 v[28:31], v[104:107], v[72:75], v[28:31]
	v_mfma_f32_16x16x32_bf16 v[24:27], v[214:217], v[72:75], v[24:27]
	v_mfma_f32_16x16x32_bf16 v[20:23], v[108:111], v[92:95], v[20:23]
	v_mfma_f32_16x16x32_bf16 v[16:19], v[164:167], v[92:95], v[16:19]
	v_mfma_f32_16x16x32_bf16 v[12:15], v[104:107], v[186:189], v[12:15]
	v_mfma_f32_16x16x32_bf16 v[8:11], v[214:217], v[186:189], v[8:11]
	v_mfma_f32_16x16x32_bf16 v[4:7], v[108:111], v[198:201], v[4:7]
	v_mfma_f32_16x16x32_bf16 v[0:3], v[164:167], v[198:201], v[0:3]
	v_mfma_f32_16x16x32_bf16 v[130:133], v[108:111], v[76:79], v[28:31]
	v_mfma_f32_16x16x32_bf16 v[134:137], v[164:167], v[76:79], v[24:27]
	v_mfma_f32_16x16x32_bf16 v[160:163], v[108:111], v[190:193], v[12:15]
	v_mfma_f32_16x16x32_bf16 v[168:171], v[164:167], v[190:193], v[8:11]
	s_setprio 0
	s_barrier
	s_nop 0
	ds_read_b128 v[8:11], v158
	ds_read_b128 v[12:15], v158 offset:1024
	ds_read_b128 v[164:167], v158 offset:2048
	ds_read_b128 v[156:159], v158 offset:3072
	ds_read_b128 v[24:27], v152 offset:32768
	ds_read_b128 v[28:31], v152 offset:33792
	ds_read_b128 v[40:43], v151 offset:32768
	ds_read_b128 v[44:47], v151 offset:33792
	ds_read_b128 v[186:189], v150 offset:32768
	ds_read_b128 v[190:193], v150 offset:33792
	ds_read_b128 v[194:197], v149 offset:32768
	ds_read_b128 v[198:201], v149 offset:33792
	s_waitcnt vmcnt(2)
	s_barrier
	s_waitcnt lgkmcnt(0)
	s_setprio 1
	s_waitcnt lgkmcnt(0)
	v_mfma_f32_16x16x32_bf16 v[72:75], v[8:11], v[24:27], v[124:127]
	v_mfma_f32_16x16x32_bf16 v[124:127], v[12:15], v[28:31], v[72:75]
	v_mfma_f32_16x16x32_bf16 v[72:75], v[164:167], v[24:27], v[120:123]
	v_mfma_f32_16x16x32_bf16 v[120:123], v[156:159], v[28:31], v[72:75]
	v_mfma_f32_16x16x32_bf16 v[72:75], v[8:11], v[40:43], v[116:119]
	v_mfma_f32_16x16x32_bf16 v[108:111], v[12:15], v[44:47], v[72:75]
	v_mfma_f32_16x16x32_bf16 v[72:75], v[164:167], v[40:43], v[112:115]
	v_mfma_f32_16x16x32_bf16 v[104:107], v[156:159], v[44:47], v[72:75]
	v_mfma_f32_16x16x32_bf16 v[72:75], v[8:11], v[186:189], v[206:209]
	v_mfma_f32_16x16x32_bf16 v[92:95], v[12:15], v[190:193], v[72:75]
	v_mfma_f32_16x16x32_bf16 v[72:75], v[164:167], v[186:189], v[210:213]
	v_mfma_f32_16x16x32_bf16 v[88:91], v[156:159], v[190:193], v[72:75]
	v_mfma_f32_16x16x32_bf16 v[72:75], v[8:11], v[194:197], v[100:103]
	v_mfma_f32_16x16x32_bf16 v[76:79], v[12:15], v[198:201], v[72:75]
	v_mfma_f32_16x16x32_bf16 v[72:75], v[164:167], v[194:197], v[96:99]
	v_mfma_f32_16x16x32_bf16 v[72:75], v[156:159], v[198:201], v[72:75]
	s_setprio 0
	s_barrier
	ds_read_b128 v[206:209], v155
	ds_read_b128 v[210:213], v155 offset:1024
	ds_read_b128 v[214:217], v155 offset:2048
	ds_read_b128 v[226:229], v155 offset:3072
	s_waitcnt vmcnt(0)
	s_barrier
; #define G_LDA(dst,b,h) _Pragma("unroll") for(int m=0;m<4;++m) _Pragma("unroll") for(int k=0;k<2;++k) \
;     dst[m][k]=*reinterpret_cast<const bf16x8*>((char*)G_SA(b,h)+lds_byte(wr*64+m*16+fr,k*32+fq*8))
; #define G_LDB(dst,b,h) _Pragma("unroll") for(int n=0;n<2;++n) _Pragma("unroll") for(int k=0;k<2;++k) \
;     dst[n][k]=*reinterpret_cast<const bf16x8*>((char*)G_SB(b,h)+lds_byte(wc*32+n*16+fr,k*32+fq*8))
; #define G_MMA(ai,bj,At,Bx) do{__builtin_amdgcn_s_setprio(1); \
;     _Pragma("unroll") for(int m=0;m<4;++m) _Pragma("unroll") for(int n=0;n<2;++n) _Pragma("unroll") for(int k=0;k<2;++k) \
;       acc[ai][bj][m][n]=__builtin_amdgcn_mfma_f32_16x16x32_bf16(Bx[n][k],At[m][k],acc[ai][bj][m][n],0,0,0); \
;     __builtin_amdgcn_s_setprio(0);}while(0)
; #define WAIT_V(n) asm volatile("s_waitcnt vmcnt(" #n ")":::"memory")
; #define WAIT_L(n) asm volatile("s_waitcnt lgkmcnt(" #n ")":::"memory")
; #define BAR __builtin_amdgcn_s_barrier()
; __device__ __forceinline__ void gemm_core(f32x4 (&acc)[2][2][4][2], const u16* __restrict__ A, int lda,
;                                           const u16* __restrict__ Bt, int ldb, int K, int brow, int bcol, u16* shm, int tid) {
;     ...
;   { G_LDB(B0,1,0); G_LDA(At,1,0); WAIT_V(2); BAR; WAIT_L(0); G_MMA(0,0,At,B0); BAR;
;     G_LDB(B1,1,1); WAIT_V(0); BAR; WAIT_L(0); G_MMA(0,1,At,B1); BAR;
;     G_LDA(At,1,1); BAR; WAIT_L(0); G_MMA(1,0,At,B0); G_MMA(1,1,At,B1); BAR; }
;   if(wr==0)BAR;
; template <int EPI, int nN, int lda, int ldb, int K, int ldc>
; __device__ __forceinline__ void gemm_phase(const Params& p, const u16* __restrict__ A, const u16* __restrict__ Bt, u16* C, u16* shm, int wave_s) {
;     ...
;     if constexpr (EPI == EPI_RELU2) {
;       float* rs = (float*)((char*)shm + SMEM_BYTES + 16);
;       if (tid < 256) { const float4 q4 = *reinterpret_cast<const float4*>((const float*)(p.ws + OFF_PSQ) + (size_t)(brow + tid) * 4);
;         rs[tid] = rsqrtf((q4.x + q4.y + q4.z + q4.w) * (1.f / 1024.f) + EPS); }
;     }
	s_waitcnt lgkmcnt(0)
	s_setprio 1
	s_waitcnt lgkmcnt(0)
	v_mfma_f32_16x16x32_bf16 v[96:99], v[206:209], v[24:27], v[218:221]
	v_mfma_f32_16x16x32_bf16 v[24:27], v[214:217], v[24:27], v[174:177]
	v_mfma_f32_16x16x32_bf16 v[112:115], v[226:229], v[28:31], v[24:27]
	v_mfma_f32_16x16x32_bf16 v[24:27], v[206:209], v[40:43], v[84:87]
	v_mfma_f32_16x16x32_bf16 v[100:103], v[210:213], v[44:47], v[24:27]
	v_mfma_f32_16x16x32_bf16 v[24:27], v[214:217], v[40:43], v[80:83]
	v_mfma_f32_16x16x32_bf16 v[116:119], v[210:213], v[28:31], v[96:99]
	v_mfma_f32_16x16x32_bf16 v[96:99], v[226:229], v[44:47], v[24:27]
	v_mfma_f32_16x16x32_bf16 v[24:27], v[206:209], v[186:189], v[178:181]
	v_mfma_f32_16x16x32_bf16 v[84:87], v[210:213], v[190:193], v[24:27]
	v_mfma_f32_16x16x32_bf16 v[24:27], v[214:217], v[186:189], v[182:185]
	v_mfma_f32_16x16x32_bf16 v[80:83], v[226:229], v[190:193], v[24:27]
	v_mfma_f32_16x16x32_bf16 v[24:27], v[206:209], v[194:197], v[68:71]
	v_mfma_f32_16x16x32_bf16 v[68:71], v[210:213], v[198:201], v[24:27]
	v_mfma_f32_16x16x32_bf16 v[24:27], v[214:217], v[194:197], v[64:67]
	v_mfma_f32_16x16x32_bf16 v[64:67], v[226:229], v[198:201], v[24:27]
	s_setprio 0
	s_barrier
	ds_read_b128 v[172:175], v152 offset:49152
	ds_read_b128 v[152:155], v152 offset:50176
	ds_read_b128 v[176:179], v151 offset:49152
	ds_read_b128 v[180:183], v151 offset:50176
	ds_read_b128 v[184:187], v150 offset:49152
	ds_read_b128 v[188:191], v150 offset:50176
	ds_read_b128 v[192:195], v149 offset:49152
	ds_read_b128 v[148:151], v149 offset:50176
	s_barrier
	s_waitcnt lgkmcnt(0)
	s_setprio 1
	s_waitcnt lgkmcnt(0)
	v_mfma_f32_16x16x32_bf16 v[24:27], v[8:11], v[172:175], v[60:63]
	v_mfma_f32_16x16x32_bf16 v[60:63], v[12:15], v[152:155], v[24:27]
	v_mfma_f32_16x16x32_bf16 v[24:27], v[164:167], v[172:175], v[56:59]
	v_mfma_f32_16x16x32_bf16 v[56:59], v[156:159], v[152:155], v[24:27]
	v_mfma_f32_16x16x32_bf16 v[24:27], v[8:11], v[176:179], v[52:55]
	v_mfma_f32_16x16x32_bf16 v[44:47], v[12:15], v[180:183], v[24:27]
	v_mfma_f32_16x16x32_bf16 v[24:27], v[164:167], v[176:179], v[48:51]
	v_mfma_f32_16x16x32_bf16 v[40:43], v[156:159], v[180:183], v[24:27]
	v_mfma_f32_16x16x32_bf16 v[24:27], v[8:11], v[184:187], v[202:205]
	v_mfma_f32_16x16x32_bf16 v[8:11], v[8:11], v[192:195], v[36:39]
	v_mfma_f32_16x16x32_bf16 v[28:31], v[12:15], v[188:191], v[24:27]
	v_mfma_f32_16x16x32_bf16 v[24:27], v[164:167], v[184:187], v[222:225]
	v_mfma_f32_16x16x32_bf16 v[12:15], v[12:15], v[148:151], v[8:11]
	v_mfma_f32_16x16x32_bf16 v[8:11], v[164:167], v[192:195], v[32:35]
	v_mfma_f32_16x16x32_bf16 v[24:27], v[156:159], v[188:191], v[24:27]
	v_mfma_f32_16x16x32_bf16 v[8:11], v[156:159], v[148:151], v[8:11]
	s_setprio 0
	s_setprio 1
	v_mfma_f32_16x16x32_bf16 v[32:35], v[206:209], v[172:175], v[130:133]
	v_mfma_f32_16x16x32_bf16 v[52:55], v[210:213], v[152:155], v[32:35]
	v_mfma_f32_16x16x32_bf16 v[32:35], v[214:217], v[172:175], v[134:137]
	v_mfma_f32_16x16x32_bf16 v[16:19], v[214:217], v[176:179], v[16:19]
	v_mfma_f32_16x16x32_bf16 v[48:51], v[226:229], v[152:155], v[32:35]
	v_mfma_f32_16x16x32_bf16 v[20:23], v[206:209], v[176:179], v[20:23]
	v_mfma_f32_16x16x32_bf16 v[32:35], v[226:229], v[180:183], v[16:19]
	v_mfma_f32_16x16x32_bf16 v[16:19], v[206:209], v[184:187], v[160:163]
	v_mfma_f32_16x16x32_bf16 v[36:39], v[210:213], v[180:183], v[20:23]
	v_mfma_f32_16x16x32_bf16 v[20:23], v[210:213], v[188:191], v[16:19]
	v_mfma_f32_16x16x32_bf16 v[16:19], v[214:217], v[184:187], v[168:171]
	v_mfma_f32_16x16x32_bf16 v[4:7], v[206:209], v[192:195], v[4:7]
	v_mfma_f32_16x16x32_bf16 v[0:3], v[214:217], v[192:195], v[0:3]
	v_mfma_f32_16x16x32_bf16 v[16:19], v[226:229], v[188:191], v[16:19]
	v_mfma_f32_16x16x32_bf16 v[4:7], v[210:213], v[148:151], v[4:7]
	v_mfma_f32_16x16x32_bf16 v[0:3], v[226:229], v[148:151], v[0:3]
	s_setprio 0
	v_cmp_gt_i32_e32 vcc, s58, v144
	s_and_saveexec_b64 s[88:89], vcc
	v_add_f32_e32 v246, v246, v247
	v_add_f32_e32 v246, v246, v248
	v_add_f32_e32 v246, v246, v249
	v_fmamk_f32 v246, v246, 0x3a800000, v140
	v_mul_f32_e32 v247, 0x4b800000, v246
	v_cmp_gt_f32_e32 vcc, s59, v246
	s_nop 1
	v_cndmask_b32_e32 v246, v246, v247, vcc
	v_rsq_f32_e32 v246, v246
	s_nop 0
	v_mul_f32_e32 v247, 0x45800000, v246
	v_cndmask_b32_e32 v246, v246, v247, vcc
	v_lshl_add_u32 v247, v144, 2, v141
	ds_write_b32 v247, v246
	s_or_b64 exec, exec, s[88:89]
	s_waitcnt lgkmcnt(0)
	v_cmp_gt_u32_e32 vcc, s58, v144
	s_barrier
	s_and_saveexec_b64 s[40:41], vcc
	s_cbranch_execz .LBB0_925
	s_barrier
	s_branch .LBB0_925
